# baseline (speedup 1.0000x reference)
; #define LDSP(TY, p) ((__attribute__((address_space(3))) TY*)(p))
; #define WAIT_L0() asm volatile("s_waitcnt lgkmcnt(0)" ::: "memory")
; __device__ __forceinline__ int otid() { int t = threadIdx.x; asm volatile("" : "+v"(t)); return t; }
; __device__ __forceinline__ void ph_attn(const Params& p, char* shm) {
;   const int tid_ = otid(); const int wid = __builtin_amdgcn_readfirstlane(tid_ >> 6), lane = tid_ & 63, hd = lane & 15, g4 = lane >> 4;
;   char* wb = shm + wid * 18432;
;   const int gw = blockIdx.x * 8 + wid, nw = gridDim.x * 8;
;   const float scale = 0.08838834764831845f;
;   const int rd = (g4 * 4 + (hd >> 2)) * 1040 + (hd & 3) * 8;
;   for (int it = 0; it * nw < T; ++it) {
;     const int r = it * nw + ((it & 1) ? (nw - 1 - gw) : gw);
;     if (r >= T) continue;
;     const int t = r & (L - 1), b = r >> 13;
;     const int cnt = min(t + 1, 256), nchunk = (cnt + 15) >> 4;
;     const u16* ckvb = p.CKV + (size_t)b * L * 512;
;     __attribute__((address_space(3))) int* idxl = LDSP(int, wb + 16640);
;     if (t >= 256) { WAIT_L0(); topk_row(p, r, lane, idxl); }
;     s16x8 qb[16];
;     const u16* qp = p.QLAT + (size_t)r * 8192 + hd * 512 + g4 * 8;
; #pragma unroll
;     for (int ks = 0; ks < 16; ++ks) qb[ks] = *(const s16x8*)(qp + ks * 32);
;     f32x4 O[32];
; #pragma unroll
;     for (int dt = 0; dt < 32; ++dt) O[dt] = f32x4{0.f, 0.f, 0.f, 0.f};
;     float mref = -INFINITY, lsum = 0.f;
;     for (int c = 0; c < nchunk; ++c) {
;       const int slot = c * 16 + hd;
;       int iv = (slot < cnt) ? slot : 0;
;       if (t >= 256) iv = idxl[slot];
;       WAIT_L0();
; #pragma unroll
;       for (int j = 0; j < 16; ++j) {
;         const int kidx = __builtin_amdgcn_readlane(iv, j);
;         __builtin_amdgcn_global_load_lds((const unsigned*)(ckvb + (size_t)kidx * 512 + lane * 8), LDSP(unsigned, wb + j * 1040), 16, 0, 0);
.LBB0_64:
	s_andn2_b64 vcc, exec, s[0:1]
	s_cbranch_vccnz .LBB0_910
	v_mov_b32_e32 v0, v204
	v_readlane_b32 s1, v246, 25
	v_readfirstlane_b32 s0, v0
	s_ashr_i32 s0, s0, 6
	s_add_i32 s4, s0, s1
	s_mul_i32 s8, s0, 0x4800
	s_not_b32 s0, s4
	v_readlane_b32 s2, v246, 53
	s_add_i32 s0, s2, s0
	v_writelane_b32 v245, s0, 54
	v_readlane_b32 s16, v246, 57
	s_add_i32 s1, s8, 0x820
	v_bfe_u32 v1, v0, 4, 2
	v_readlane_b32 s23, v245, 0
	v_writelane_b32 v245, s1, 55
	s_add_i32 s1, s8, 0xc30
	v_lshlrev_b32_e32 v220, 2, v1
	v_bfe_u32 v2, v0, 2, 2
	v_writelane_b32 v245, s1, 56
	s_add_i32 s1, s8, 0x1450
	v_and_b32_e32 v219, 15, v0
	v_or_b32_e32 v2, v220, v2
	v_lshlrev_b32_e32 v3, 3, v0
	v_lshlrev_b32_e32 v32, 3, v1
	v_mov_b32_e32 v1, s8
	s_movk_i32 s0, 0x420
	v_writelane_b32 v245, s1, 57
	s_add_i32 s1, s8, 0x1860
	v_and_b32_e32 v6, 24, v3
	v_mad_u32_u24 v8, v2, s0, v1
	v_lshlrev_b32_e32 v2, 10, v219
	v_mov_b32_e32 v3, v33
	v_readlane_b32 s17, v246, 58
	v_writelane_b32 v245, s1, 58
	s_add_i32 s1, s8, 0x1c70
	v_and_b32_e32 v218, 63, v0
	v_mad_u32_u24 v7, v219, s0, v1
	v_and_b32_e32 v0, 48, v0
	v_readlane_b32 s18, v246, 59
	v_readlane_b32 s19, v246, 60
	v_lshl_add_u64 v[4:5], s[16:17], 0, v[2:3]
	v_mov_b32_e32 v1, v33
	v_writelane_b32 v245, s1, 59
	s_add_i32 s1, s8, 0x2080
	v_lshl_add_u64 v[196:197], v[4:5], 0, v[0:1]
	v_lshlrev_b32_e32 v4, 4, v218
	v_mov_b32_e32 v5, v33
	v_lshl_add_u64 v[2:3], s[18:19], 0, v[2:3]
	s_add_i32 s0, s8, 0x4200
	v_writelane_b32 v245, s1, 60
	s_add_i32 s1, s8, 0x2490
	v_lshl_add_u64 v[198:199], s[30:31], 0, v[4:5]
	v_lshl_add_u64 v[200:201], v[2:3], 0, v[32:33]
	v_lshl_or_b32 v221, v219, 2, s0
	s_mov_b32 s0, 0
	v_writelane_b32 v245, s1, 61
	s_add_i32 s9, s8, 0x28a0
	s_add_i32 s10, s8, 0x2cb0
	s_add_i32 s11, s8, 0x30c0
	s_add_i32 s12, s8, 0x34d0
	s_add_i32 s13, s8, 0x38e0
	s_add_i32 s14, s8, 0x3cf0
	v_add_u32_e32 v222, v7, v0
	v_add_u32_e32 v223, v8, v6
	s_mov_b32 s1, 0
	v_readlane_b32 s3, v246, 54
	v_readlane_b32 s20, v246, 61
	v_readlane_b32 s21, v246, 62
	v_readlane_b32 s22, v246, 63
	v_writelane_b32 v245, s4, 62
	s_branch .LBB0_68

; __device__ __forceinline__ void topk_row(const Params& p, int r, int lane, __attribute__((address_space(3))) int* out) {
;     ...
;     int base_gt = 0, base_eq = cgt;
; #pragma unroll
;     for (int blk = 0; blk < 8; ++blk) {
;       if (blk * 16 < nch) {
; #pragma unroll
;         for (int ii = 0; ii < 16; ++ii) {
;           const int i = blk * 16 + ii;
;           const bool g = key[i] > Tv, e = key[i] == Tv;
;           const unsigned long long mg = __ballot(g), me = __ballot(e);
;           const int pg = base_gt + mbcnt64(mg);
;           if (g) out[pg] = i * 64 + lo;
;           base_gt += __popcll(mg);
;           const int pe = base_eq + mbcnt64(me);
;           if (e && pe < 256) out[pe] = i * 64 + lo;
;           base_eq += __popcll(me);
;         }
.LBB0_103:
	v_cmp_eq_u32_e64 s[84:85], v139, v123
	v_cndmask_b32_e64 v139, 0, 1, s[82:83]
	v_readlane_b32 s86, v245, 41
	v_cmp_ne_u32_e32 vcc, 0, v139
	s_and_saveexec_b64 s[0:1], s[82:83]
	s_nop 0
	v_mbcnt_lo_u32_b32 v139, vcc_lo, 0
	v_mbcnt_hi_u32_b32 v139, vcc_hi, v139
	v_lshl_add_u32 v139, v139, 2, s8
	ds_write_b32 v139, v0 offset:16896
	s_or_b64 exec, exec, s[0:1]
	v_mbcnt_lo_u32_b32 v139, s84, 0
	v_mbcnt_hi_u32_b32 v139, s85, v139
	v_add_u32_e32 v139, s4, v139
	s_movk_i32 s0, 0x100
	v_cmp_gt_i32_e64 s[0:1], s0, v139
	s_and_b64 s[52:53], s[84:85], s[0:1]
	s_and_saveexec_b64 s[0:1], s[52:53]
	v_lshl_add_u32 v139, v139, 2, s8
	ds_write_b32 v139, v0 offset:16896
	s_or_b64 exec, exec, s[0:1]
	s_bcnt1_i32_b64 s52, vcc
	v_cmp_eq_u32_e32 vcc, v138, v123
	v_cndmask_b32_e64 v138, 0, 1, s[80:81]
	v_cmp_ne_u32_e64 s[82:83], 0, v138
	s_and_saveexec_b64 s[0:1], s[80:81]
	s_cbranch_execz .LBB0_109
	s_lshl_b32 s53, s52, 2
	v_mbcnt_lo_u32_b32 v139, s82, 0
	s_add_i32 s53, s8, s53
	v_mbcnt_hi_u32_b32 v139, s83, v139
	v_add_u32_e32 v138, 64, v0
	v_lshl_add_u32 v139, v139, 2, s53
	ds_write_b32 v139, v138 offset:16896
.LBB0_109:
	s_or_b64 exec, exec, s[0:1]
	s_bcnt1_i32_b64 s0, s[84:85]
	v_mbcnt_lo_u32_b32 v138, vcc_lo, 0
	s_add_i32 s4, s4, s0
	v_mbcnt_hi_u32_b32 v138, vcc_hi, v138
	v_add_u32_e32 v138, s4, v138
	s_movk_i32 s0, 0x100
	v_cmp_gt_i32_e64 s[0:1], s0, v138
	s_and_b64 s[54:55], vcc, s[0:1]
	s_and_saveexec_b64 s[0:1], s[54:55]
	v_lshl_add_u32 v138, v138, 2, s8
	v_add_u32_e32 v139, 64, v0
	ds_write_b32 v138, v139 offset:16896
	s_or_b64 exec, exec, s[0:1]
	s_bcnt1_i32_b64 s0, s[82:83]
	v_cmp_eq_u32_e64 s[80:81], v137, v123
	v_cndmask_b32_e64 v137, 0, 1, s[78:79]
	s_add_i32 s52, s0, s52
	v_cmp_ne_u32_e64 s[82:83], 0, v137
	s_and_saveexec_b64 s[0:1], s[78:79]
	s_cbranch_execz .LBB0_113
	s_lshl_b32 s53, s52, 2
	v_mbcnt_lo_u32_b32 v138, s82, 0
	s_add_i32 s53, s8, s53
	v_mbcnt_hi_u32_b32 v138, s83, v138
	v_add_u32_e32 v137, 0x80, v0
	v_lshl_add_u32 v138, v138, 2, s53
	ds_write_b32 v138, v137 offset:16896
.LBB0_113:
	s_or_b64 exec, exec, s[0:1]
	s_bcnt1_i32_b64 s0, vcc
	v_mbcnt_lo_u32_b32 v137, s80, 0
	s_add_i32 s4, s4, s0
	v_mbcnt_hi_u32_b32 v137, s81, v137
	v_add_u32_e32 v137, s4, v137
	s_movk_i32 s0, 0x100
	v_cmp_gt_i32_e32 vcc, s0, v137
	s_and_b64 s[54:55], s[80:81], vcc
	s_and_saveexec_b64 s[0:1], s[54:55]
	v_lshl_add_u32 v137, v137, 2, s8
	v_add_u32_e32 v138, 0x80, v0
	ds_write_b32 v137, v138 offset:16896
	s_or_b64 exec, exec, s[0:1]
	s_bcnt1_i32_b64 s0, s[82:83]
	v_cmp_eq_u32_e32 vcc, v136, v123
	v_cndmask_b32_e64 v136, 0, 1, s[76:77]
	s_add_i32 s52, s52, s0
	v_cmp_ne_u32_e64 s[78:79], 0, v136
	s_and_saveexec_b64 s[0:1], s[76:77]
	s_cbranch_execz .LBB0_117
	s_lshl_b32 s53, s52, 2
	v_mbcnt_lo_u32_b32 v137, s78, 0
	s_add_i32 s53, s8, s53
	v_mbcnt_hi_u32_b32 v137, s79, v137
	v_add_u32_e32 v136, 0xc0, v0
	v_lshl_add_u32 v137, v137, 2, s53
	ds_write_b32 v137, v136 offset:16896
.LBB0_117:
	s_or_b64 exec, exec, s[0:1]
	s_bcnt1_i32_b64 s0, s[80:81]
	v_mbcnt_lo_u32_b32 v136, vcc_lo, 0
	s_add_i32 s4, s4, s0
	v_mbcnt_hi_u32_b32 v136, vcc_hi, v136
	v_add_u32_e32 v136, s4, v136
	s_movk_i32 s0, 0x100
	v_cmp_gt_i32_e64 s[0:1], s0, v136
	s_and_b64 s[54:55], vcc, s[0:1]
	s_and_saveexec_b64 s[0:1], s[54:55]
	v_lshl_add_u32 v136, v136, 2, s8
	v_add_u32_e32 v137, 0xc0, v0
	ds_write_b32 v136, v137 offset:16896
	s_or_b64 exec, exec, s[0:1]
	s_bcnt1_i32_b64 s0, s[78:79]
	v_cmp_eq_u32_e64 s[76:77], v135, v123
	v_cndmask_b32_e64 v135, 0, 1, s[74:75]
	s_add_i32 s52, s52, s0
	v_cmp_ne_u32_e64 s[78:79], 0, v135
	s_and_saveexec_b64 s[0:1], s[74:75]
	s_cbranch_execz .LBB0_121
	s_lshl_b32 s53, s52, 2
	v_mbcnt_lo_u32_b32 v136, s78, 0
	s_add_i32 s53, s8, s53
	v_mbcnt_hi_u32_b32 v136, s79, v136
	v_add_u32_e32 v135, 0x100, v0
	v_lshl_add_u32 v136, v136, 2, s53
	ds_write_b32 v136, v135 offset:16896
.LBB0_121:
	s_or_b64 exec, exec, s[0:1]
	s_bcnt1_i32_b64 s0, vcc
	v_mbcnt_lo_u32_b32 v135, s76, 0
	s_add_i32 s4, s4, s0
	v_mbcnt_hi_u32_b32 v135, s77, v135
	v_add_u32_e32 v135, s4, v135
	s_movk_i32 s0, 0x100
	v_cmp_gt_i32_e32 vcc, s0, v135
	s_and_b64 s[54:55], s[76:77], vcc
	s_and_saveexec_b64 s[0:1], s[54:55]
	v_lshl_add_u32 v135, v135, 2, s8
	v_add_u32_e32 v136, 0x100, v0
	ds_write_b32 v135, v136 offset:16896
	s_or_b64 exec, exec, s[0:1]
	s_bcnt1_i32_b64 s0, s[78:79]
	v_cmp_eq_u32_e32 vcc, v134, v123
	v_cndmask_b32_e64 v134, 0, 1, s[72:73]
	s_add_i32 s52, s52, s0
	v_cmp_ne_u32_e64 s[74:75], 0, v134
	s_and_saveexec_b64 s[0:1], s[72:73]
	s_cbranch_execz .LBB0_125
	s_lshl_b32 s53, s52, 2
	v_mbcnt_lo_u32_b32 v135, s74, 0
	s_add_i32 s53, s8, s53
	v_mbcnt_hi_u32_b32 v135, s75, v135
	v_add_u32_e32 v134, 0x140, v0
	v_lshl_add_u32 v135, v135, 2, s53
	ds_write_b32 v135, v134 offset:16896
.LBB0_125:
	s_or_b64 exec, exec, s[0:1]
	s_bcnt1_i32_b64 s0, s[76:77]
	v_mbcnt_lo_u32_b32 v134, vcc_lo, 0
	s_add_i32 s4, s4, s0
	v_mbcnt_hi_u32_b32 v134, vcc_hi, v134
	v_add_u32_e32 v134, s4, v134
	s_movk_i32 s0, 0x100
	v_cmp_gt_i32_e64 s[0:1], s0, v134
	s_and_b64 s[54:55], vcc, s[0:1]
	s_and_saveexec_b64 s[0:1], s[54:55]
	v_lshl_add_u32 v134, v134, 2, s8
	v_add_u32_e32 v135, 0x140, v0
	ds_write_b32 v134, v135 offset:16896
	s_or_b64 exec, exec, s[0:1]
	s_bcnt1_i32_b64 s0, s[74:75]
	v_cmp_eq_u32_e64 s[72:73], v133, v123
	v_cndmask_b32_e64 v133, 0, 1, s[70:71]
	s_add_i32 s52, s52, s0
	v_cmp_ne_u32_e64 s[74:75], 0, v133
	s_and_saveexec_b64 s[0:1], s[70:71]
	s_cbranch_execz .LBB0_129
	s_lshl_b32 s53, s52, 2
	v_mbcnt_lo_u32_b32 v134, s74, 0
	s_add_i32 s53, s8, s53
	v_mbcnt_hi_u32_b32 v134, s75, v134
	v_add_u32_e32 v133, 0x180, v0
	v_lshl_add_u32 v134, v134, 2, s53
	ds_write_b32 v134, v133 offset:16896
; __device__ __forceinline__ void topk_row(const Params& p, int r, int lane, __attribute__((address_space(3))) int* out) {
;     ...
;     int base_gt = 0, base_eq = cgt;
; #pragma unroll
;     for (int blk = 0; blk < 8; ++blk) {
;       if (blk * 16 < nch) {
; #pragma unroll
;         for (int ii = 0; ii < 16; ++ii) {
;           const int i = blk * 16 + ii;
;           const bool g = key[i] > Tv, e = key[i] == Tv;
;           const unsigned long long mg = __ballot(g), me = __ballot(e);
;           const int pg = base_gt + mbcnt64(mg);
;           if (g) out[pg] = i * 64 + lo;
;           base_gt += __popcll(mg);
;           const int pe = base_eq + mbcnt64(me);
;           if (e && pe < 256) out[pe] = i * 64 + lo;
;           base_eq += __popcll(me);
;         }
.LBB0_129:
	s_or_b64 exec, exec, s[0:1]
	s_bcnt1_i32_b64 s0, vcc
	v_mbcnt_lo_u32_b32 v133, s72, 0
	s_add_i32 s4, s4, s0
	v_mbcnt_hi_u32_b32 v133, s73, v133
	v_add_u32_e32 v133, s4, v133
	s_movk_i32 s0, 0x100
	v_cmp_gt_i32_e32 vcc, s0, v133
	s_and_b64 s[54:55], s[72:73], vcc
	s_and_saveexec_b64 s[0:1], s[54:55]
	v_lshl_add_u32 v133, v133, 2, s8
	v_add_u32_e32 v134, 0x180, v0
	ds_write_b32 v133, v134 offset:16896
	s_or_b64 exec, exec, s[0:1]
	s_bcnt1_i32_b64 s0, s[74:75]
	v_cmp_eq_u32_e32 vcc, v132, v123
	v_cndmask_b32_e64 v132, 0, 1, s[68:69]
	s_add_i32 s52, s52, s0
	v_cmp_ne_u32_e64 s[70:71], 0, v132
	s_and_saveexec_b64 s[0:1], s[68:69]
	s_cbranch_execz .LBB0_133
	s_lshl_b32 s53, s52, 2
	v_mbcnt_lo_u32_b32 v133, s70, 0
	s_add_i32 s53, s8, s53
	v_mbcnt_hi_u32_b32 v133, s71, v133
	v_add_u32_e32 v132, 0x1c0, v0
	v_lshl_add_u32 v133, v133, 2, s53
	ds_write_b32 v133, v132 offset:16896
.LBB0_133:
	s_or_b64 exec, exec, s[0:1]
	s_bcnt1_i32_b64 s0, s[72:73]
	v_mbcnt_lo_u32_b32 v132, vcc_lo, 0
	s_add_i32 s4, s4, s0
	v_mbcnt_hi_u32_b32 v132, vcc_hi, v132
	v_add_u32_e32 v132, s4, v132
	s_movk_i32 s0, 0x100
	v_cmp_gt_i32_e64 s[0:1], s0, v132
	s_and_b64 s[54:55], vcc, s[0:1]
	s_and_saveexec_b64 s[0:1], s[54:55]
	v_lshl_add_u32 v132, v132, 2, s8
	v_add_u32_e32 v133, 0x1c0, v0
	ds_write_b32 v132, v133 offset:16896
	s_or_b64 exec, exec, s[0:1]
	v_readlane_b32 s54, v244, 12
	v_readlane_b32 s55, v244, 13
	s_bcnt1_i32_b64 s0, s[70:71]
	v_cmp_eq_u32_e64 s[68:69], v131, v123
	v_cndmask_b32_e64 v131, 0, 1, s[54:55]
	s_add_i32 s52, s52, s0
	v_cmp_ne_u32_e64 s[70:71], 0, v131
	s_and_saveexec_b64 s[0:1], s[54:55]
	s_cbranch_execz .LBB0_137
	s_lshl_b32 s53, s52, 2
	v_mbcnt_lo_u32_b32 v132, s70, 0
	s_add_i32 s53, s8, s53
	v_mbcnt_hi_u32_b32 v132, s71, v132
	v_add_u32_e32 v131, 0x200, v0
	v_lshl_add_u32 v132, v132, 2, s53
	ds_write_b32 v132, v131 offset:16896
.LBB0_137:
	s_or_b64 exec, exec, s[0:1]
	s_bcnt1_i32_b64 s0, vcc
	v_mbcnt_lo_u32_b32 v131, s68, 0
	s_add_i32 s4, s4, s0
	v_mbcnt_hi_u32_b32 v131, s69, v131
	v_add_u32_e32 v131, s4, v131
	s_movk_i32 s0, 0x100
	v_cmp_gt_i32_e32 vcc, s0, v131
	s_and_b64 s[54:55], s[68:69], vcc
	s_and_saveexec_b64 s[0:1], s[54:55]
	v_lshl_add_u32 v131, v131, 2, s8
	v_add_u32_e32 v132, 0x200, v0
	ds_write_b32 v131, v132 offset:16896
	s_or_b64 exec, exec, s[0:1]
	v_readlane_b32 s54, v244, 14
	v_readlane_b32 s55, v244, 15
	s_bcnt1_i32_b64 s0, s[70:71]
	v_cmp_eq_u32_e32 vcc, v130, v123
	v_cndmask_b32_e64 v130, 0, 1, s[54:55]
	s_add_i32 s52, s52, s0
	v_cmp_ne_u32_e64 s[66:67], 0, v130
	s_and_saveexec_b64 s[0:1], s[54:55]
	s_cbranch_execz .LBB0_141
	s_lshl_b32 s53, s52, 2
	v_mbcnt_lo_u32_b32 v131, s66, 0
	s_add_i32 s53, s8, s53
	v_mbcnt_hi_u32_b32 v131, s67, v131
	v_add_u32_e32 v130, 0x240, v0
	v_lshl_add_u32 v131, v131, 2, s53
	ds_write_b32 v131, v130 offset:16896
.LBB0_141:
	s_or_b64 exec, exec, s[0:1]
	s_bcnt1_i32_b64 s0, s[68:69]
	v_mbcnt_lo_u32_b32 v130, vcc_lo, 0
	s_add_i32 s4, s4, s0
	v_mbcnt_hi_u32_b32 v130, vcc_hi, v130
	v_add_u32_e32 v130, s4, v130
	s_movk_i32 s0, 0x100
	v_cmp_gt_i32_e64 s[0:1], s0, v130
	s_and_b64 s[54:55], vcc, s[0:1]
	s_and_saveexec_b64 s[0:1], s[54:55]
	v_lshl_add_u32 v130, v130, 2, s8
	v_add_u32_e32 v131, 0x240, v0
	ds_write_b32 v130, v131 offset:16896
	s_or_b64 exec, exec, s[0:1]
	v_readlane_b32 s54, v244, 16
	v_readlane_b32 s55, v244, 17
	s_bcnt1_i32_b64 s0, s[66:67]
	v_cmp_eq_u32_e64 s[64:65], v129, v123
	v_cndmask_b32_e64 v129, 0, 1, s[54:55]
	s_add_i32 s52, s52, s0
	v_cmp_ne_u32_e64 s[66:67], 0, v129
	s_and_saveexec_b64 s[0:1], s[54:55]
	s_cbranch_execz .LBB0_145
	s_lshl_b32 s53, s52, 2
	v_mbcnt_lo_u32_b32 v130, s66, 0
	s_add_i32 s53, s8, s53
	v_mbcnt_hi_u32_b32 v130, s67, v130
	v_add_u32_e32 v129, 0x280, v0
	v_lshl_add_u32 v130, v130, 2, s53
	ds_write_b32 v130, v129 offset:16896
.LBB0_145:
	s_or_b64 exec, exec, s[0:1]
	s_bcnt1_i32_b64 s0, vcc
	v_mbcnt_lo_u32_b32 v129, s64, 0
	s_add_i32 s4, s4, s0
	v_mbcnt_hi_u32_b32 v129, s65, v129
	v_add_u32_e32 v129, s4, v129
	s_movk_i32 s0, 0x100
	v_cmp_gt_i32_e32 vcc, s0, v129
	s_and_b64 s[54:55], s[64:65], vcc
	s_and_saveexec_b64 s[0:1], s[54:55]
	v_lshl_add_u32 v129, v129, 2, s8
	v_add_u32_e32 v130, 0x280, v0
	ds_write_b32 v129, v130 offset:16896
	s_or_b64 exec, exec, s[0:1]
	v_readlane_b32 s54, v244, 18
	v_readlane_b32 s55, v244, 19
	s_bcnt1_i32_b64 s0, s[66:67]
	v_cmp_eq_u32_e32 vcc, v128, v123
	v_cndmask_b32_e64 v128, 0, 1, s[54:55]
	s_add_i32 s52, s52, s0
	v_cmp_ne_u32_e64 s[62:63], 0, v128
	s_and_saveexec_b64 s[0:1], s[54:55]
	s_cbranch_execz .LBB0_149
	s_lshl_b32 s53, s52, 2
	v_mbcnt_lo_u32_b32 v129, s62, 0
	s_add_i32 s53, s8, s53
	v_mbcnt_hi_u32_b32 v129, s63, v129
	v_add_u32_e32 v128, 0x2c0, v0
	v_lshl_add_u32 v129, v129, 2, s53
	ds_write_b32 v129, v128 offset:16896
.LBB0_149:
	s_or_b64 exec, exec, s[0:1]
	s_bcnt1_i32_b64 s0, s[64:65]
	v_mbcnt_lo_u32_b32 v128, vcc_lo, 0
	s_add_i32 s4, s4, s0
	v_mbcnt_hi_u32_b32 v128, vcc_hi, v128
	v_add_u32_e32 v128, s4, v128
	s_movk_i32 s0, 0x100
	v_cmp_gt_i32_e64 s[0:1], s0, v128
	s_and_b64 s[54:55], vcc, s[0:1]
	s_and_saveexec_b64 s[0:1], s[54:55]
	v_lshl_add_u32 v128, v128, 2, s8
	v_add_u32_e32 v129, 0x2c0, v0
	ds_write_b32 v128, v129 offset:16896
	s_or_b64 exec, exec, s[0:1]
	v_readlane_b32 s54, v244, 20
	v_readlane_b32 s55, v244, 21
	s_bcnt1_i32_b64 s0, s[62:63]
	v_cmp_eq_u32_e64 s[60:61], v127, v123
	v_cndmask_b32_e64 v127, 0, 1, s[54:55]
	s_add_i32 s52, s52, s0
	v_cmp_ne_u32_e64 s[62:63], 0, v127
	s_and_saveexec_b64 s[0:1], s[54:55]
	s_cbranch_execz .LBB0_153
	s_lshl_b32 s53, s52, 2
	v_mbcnt_lo_u32_b32 v128, s62, 0
	s_add_i32 s53, s8, s53
	v_mbcnt_hi_u32_b32 v128, s63, v128
	v_add_u32_e32 v127, 0x300, v0
	v_lshl_add_u32 v128, v128, 2, s53
	ds_write_b32 v128, v127 offset:16896
; __device__ __forceinline__ void topk_row(const Params& p, int r, int lane, __attribute__((address_space(3))) int* out) {
;     ...
;     int base_gt = 0, base_eq = cgt;
; #pragma unroll
;     for (int blk = 0; blk < 8; ++blk) {
;       if (blk * 16 < nch) {
; #pragma unroll
;         for (int ii = 0; ii < 16; ++ii) {
;           const int i = blk * 16 + ii;
;           const bool g = key[i] > Tv, e = key[i] == Tv;
;           const unsigned long long mg = __ballot(g), me = __ballot(e);
;           const int pg = base_gt + mbcnt64(mg);
;           if (g) out[pg] = i * 64 + lo;
;           base_gt += __popcll(mg);
;           const int pe = base_eq + mbcnt64(me);
;           if (e && pe < 256) out[pe] = i * 64 + lo;
;           base_eq += __popcll(me);
;         }
.LBB0_153:
	s_or_b64 exec, exec, s[0:1]
	s_bcnt1_i32_b64 s0, vcc
	v_mbcnt_lo_u32_b32 v127, s60, 0
	s_add_i32 s4, s4, s0
	v_mbcnt_hi_u32_b32 v127, s61, v127
	v_add_u32_e32 v127, s4, v127
	s_movk_i32 s0, 0x100
	v_cmp_gt_i32_e32 vcc, s0, v127
	s_and_b64 s[54:55], s[60:61], vcc
	s_and_saveexec_b64 s[0:1], s[54:55]
	v_lshl_add_u32 v127, v127, 2, s8
	v_add_u32_e32 v128, 0x300, v0
	ds_write_b32 v127, v128 offset:16896
	s_or_b64 exec, exec, s[0:1]
	v_readlane_b32 s54, v244, 22
	v_readlane_b32 s55, v244, 23
	s_bcnt1_i32_b64 s0, s[62:63]
	v_cmp_eq_u32_e32 vcc, v126, v123
	v_cndmask_b32_e64 v126, 0, 1, s[54:55]
	s_add_i32 s52, s52, s0
	v_cmp_ne_u32_e64 s[58:59], 0, v126
	s_and_saveexec_b64 s[0:1], s[54:55]
	s_cbranch_execz .LBB0_157
	s_lshl_b32 s53, s52, 2
	v_mbcnt_lo_u32_b32 v127, s58, 0
	s_add_i32 s53, s8, s53
	v_mbcnt_hi_u32_b32 v127, s59, v127
	v_add_u32_e32 v126, 0x340, v0
	v_lshl_add_u32 v127, v127, 2, s53
	ds_write_b32 v127, v126 offset:16896
.LBB0_157:
	s_or_b64 exec, exec, s[0:1]
	s_bcnt1_i32_b64 s0, s[60:61]
	v_mbcnt_lo_u32_b32 v126, vcc_lo, 0
	s_add_i32 s4, s4, s0
	v_mbcnt_hi_u32_b32 v126, vcc_hi, v126
	v_add_u32_e32 v126, s4, v126
	s_movk_i32 s0, 0x100
	v_cmp_gt_i32_e64 s[0:1], s0, v126
	s_and_b64 s[54:55], vcc, s[0:1]
	s_and_saveexec_b64 s[0:1], s[54:55]
	v_lshl_add_u32 v126, v126, 2, s8
	v_add_u32_e32 v127, 0x340, v0
	ds_write_b32 v126, v127 offset:16896
	s_or_b64 exec, exec, s[0:1]
	v_readlane_b32 s54, v244, 24
	v_readlane_b32 s55, v244, 25
	s_bcnt1_i32_b64 s0, s[58:59]
	v_cmp_eq_u32_e64 s[56:57], v125, v123
	v_cndmask_b32_e64 v125, 0, 1, s[54:55]
	s_add_i32 s52, s52, s0
	v_cmp_ne_u32_e64 s[58:59], 0, v125
	s_and_saveexec_b64 s[0:1], s[54:55]
	s_cbranch_execz .LBB0_161
	s_lshl_b32 s53, s52, 2
	v_mbcnt_lo_u32_b32 v126, s58, 0
	s_add_i32 s53, s8, s53
	v_mbcnt_hi_u32_b32 v126, s59, v126
	v_add_u32_e32 v125, 0x380, v0
	v_lshl_add_u32 v126, v126, 2, s53
	ds_write_b32 v126, v125 offset:16896
.LBB0_161:
	s_or_b64 exec, exec, s[0:1]
	s_bcnt1_i32_b64 s0, vcc
	v_mbcnt_lo_u32_b32 v125, s56, 0
	s_add_i32 s4, s4, s0
	v_mbcnt_hi_u32_b32 v125, s57, v125
	v_add_u32_e32 v125, s4, v125
	s_movk_i32 s0, 0x100
	v_cmp_gt_i32_e32 vcc, s0, v125
	s_and_b64 s[54:55], s[56:57], vcc
	s_and_saveexec_b64 s[0:1], s[54:55]
	v_lshl_add_u32 v125, v125, 2, s8
	v_add_u32_e32 v126, 0x380, v0
	ds_write_b32 v125, v126 offset:16896
	s_or_b64 exec, exec, s[0:1]
	s_bcnt1_i32_b64 s0, s[58:59]
	v_readlane_b32 s58, v244, 26
	v_readlane_b32 s59, v244, 27
	v_cmp_eq_u32_e32 vcc, v124, v123
	s_add_i32 s52, s52, s0
	v_cndmask_b32_e64 v124, 0, 1, s[58:59]
	v_cmp_ne_u32_e64 s[54:55], 0, v124
	s_and_saveexec_b64 s[0:1], s[58:59]
	s_cbranch_execz .LBB0_165
	s_lshl_b32 s53, s52, 2
	v_mbcnt_lo_u32_b32 v125, s54, 0
	s_add_i32 s53, s8, s53
	v_mbcnt_hi_u32_b32 v125, s55, v125
	v_add_u32_e32 v124, 0x3c0, v0
	v_lshl_add_u32 v125, v125, 2, s53
	ds_write_b32 v125, v124 offset:16896
.LBB0_165:
	s_or_b64 exec, exec, s[0:1]
	s_bcnt1_i32_b64 s0, s[56:57]
	v_mbcnt_lo_u32_b32 v124, vcc_lo, 0
	s_add_i32 s4, s4, s0
	v_mbcnt_hi_u32_b32 v124, vcc_hi, v124
	v_add_u32_e32 v124, s4, v124
	s_movk_i32 s0, 0x100
	v_cmp_gt_i32_e64 s[0:1], s0, v124
	s_and_b64 s[56:57], vcc, s[0:1]
	s_and_saveexec_b64 s[0:1], s[56:57]
	v_lshl_add_u32 v124, v124, 2, s8
	v_add_u32_e32 v125, 0x3c0, v0
	ds_write_b32 v124, v125 offset:16896
	s_or_b64 exec, exec, s[0:1]
	s_bcnt1_i32_b64 s0, s[54:55]
	s_add_i32 s54, s52, s0
	s_bcnt1_i32_b64 s0, vcc
	s_and_b64 vcc, exec, s[16:17]
	s_add_i32 s4, s4, s0
	s_cbranch_vccnz .LBB0_233
	v_cmp_gt_u32_e32 vcc, v114, v123
	v_cmp_eq_u32_e64 s[52:53], v114, v123
	s_and_saveexec_b64 s[0:1], vcc
	s_cbranch_execz .LBB0_170
	s_lshl_b32 s55, s54, 2
	v_mbcnt_lo_u32_b32 v125, vcc_lo, 0
	s_add_i32 s55, s8, s55
	v_mbcnt_hi_u32_b32 v125, vcc_hi, v125
	v_add_u32_e32 v124, 0x400, v0
	v_lshl_add_u32 v125, v125, 2, s55
	ds_write_b32 v125, v124 offset:16896
.LBB0_170:
	s_or_b64 exec, exec, s[0:1]
	v_mbcnt_lo_u32_b32 v124, s52, 0
	v_mbcnt_hi_u32_b32 v124, s53, v124
	v_add_u32_e32 v124, s4, v124
	s_movk_i32 s0, 0x100
	v_cmp_gt_i32_e64 s[0:1], s0, v124
	s_and_b64 s[56:57], s[52:53], s[0:1]
	s_and_saveexec_b64 s[0:1], s[56:57]
	v_lshl_add_u32 v124, v124, 2, s8
	v_add_u32_e32 v125, 0x400, v0
	ds_write_b32 v124, v125 offset:16896
	s_or_b64 exec, exec, s[0:1]
	s_bcnt1_i32_b64 s0, vcc
	s_add_i32 s56, s54, s0
	v_cmp_gt_u32_e64 s[54:55], v113, v123
	v_cmp_eq_u32_e32 vcc, v113, v123
	s_and_saveexec_b64 s[0:1], s[54:55]
	s_cbranch_execz .LBB0_174
	s_lshl_b32 s57, s56, 2
	v_mbcnt_lo_u32_b32 v125, s54, 0
	s_add_i32 s57, s8, s57
	v_mbcnt_hi_u32_b32 v125, s55, v125
	v_add_u32_e32 v124, 0x440, v0
	v_lshl_add_u32 v125, v125, 2, s57
	ds_write_b32 v125, v124 offset:16896
.LBB0_174:
	s_or_b64 exec, exec, s[0:1]
	s_bcnt1_i32_b64 s0, s[52:53]
	v_mbcnt_lo_u32_b32 v124, vcc_lo, 0
	s_add_i32 s4, s4, s0
	v_mbcnt_hi_u32_b32 v124, vcc_hi, v124
	v_add_u32_e32 v124, s4, v124
	s_movk_i32 s0, 0x100
	v_cmp_gt_i32_e64 s[0:1], s0, v124
	s_and_b64 s[52:53], vcc, s[0:1]
	s_and_saveexec_b64 s[0:1], s[52:53]
	v_lshl_add_u32 v124, v124, 2, s8
	v_add_u32_e32 v125, 0x440, v0
	ds_write_b32 v124, v125 offset:16896
	s_or_b64 exec, exec, s[0:1]
	s_bcnt1_i32_b64 s0, s[54:55]
	s_add_i32 s56, s56, s0
	v_cmp_gt_u32_e64 s[54:55], v112, v123
	v_cmp_eq_u32_e64 s[52:53], v112, v123
	s_and_saveexec_b64 s[0:1], s[54:55]
	s_cbranch_execz .LBB0_178
	s_lshl_b32 s57, s56, 2
	v_mbcnt_lo_u32_b32 v125, s54, 0
	s_add_i32 s57, s8, s57
	v_mbcnt_hi_u32_b32 v125, s55, v125
	v_add_u32_e32 v124, 0x480, v0
	v_lshl_add_u32 v125, v125, 2, s57
	ds_write_b32 v125, v124 offset:16896
; __device__ __forceinline__ void topk_row(const Params& p, int r, int lane, __attribute__((address_space(3))) int* out) {
;     ...
;     int base_gt = 0, base_eq = cgt;
; #pragma unroll
;     for (int blk = 0; blk < 8; ++blk) {
;       if (blk * 16 < nch) {
; #pragma unroll
;         for (int ii = 0; ii < 16; ++ii) {
;           const int i = blk * 16 + ii;
;           const bool g = key[i] > Tv, e = key[i] == Tv;
;           const unsigned long long mg = __ballot(g), me = __ballot(e);
;           const int pg = base_gt + mbcnt64(mg);
;           if (g) out[pg] = i * 64 + lo;
;           base_gt += __popcll(mg);
;           const int pe = base_eq + mbcnt64(me);
;           if (e && pe < 256) out[pe] = i * 64 + lo;
;           base_eq += __popcll(me);
;         }
.LBB0_178:
	s_or_b64 exec, exec, s[0:1]
	s_bcnt1_i32_b64 s0, vcc
	v_mbcnt_lo_u32_b32 v124, s52, 0
	s_add_i32 s4, s4, s0
	v_mbcnt_hi_u32_b32 v124, s53, v124
	v_add_u32_e32 v124, s4, v124
	s_movk_i32 s0, 0x100
	v_cmp_gt_i32_e32 vcc, s0, v124
	s_and_b64 s[58:59], s[52:53], vcc
	s_and_saveexec_b64 s[0:1], s[58:59]
	v_lshl_add_u32 v124, v124, 2, s8
	v_add_u32_e32 v125, 0x480, v0
	ds_write_b32 v124, v125 offset:16896
	s_or_b64 exec, exec, s[0:1]
	s_bcnt1_i32_b64 s0, s[54:55]
	s_add_i32 s56, s56, s0
	v_cmp_gt_u32_e64 s[54:55], v111, v123
	v_cmp_eq_u32_e32 vcc, v111, v123
	s_and_saveexec_b64 s[0:1], s[54:55]
	s_cbranch_execz .LBB0_182
	s_lshl_b32 s57, s56, 2
	v_mbcnt_lo_u32_b32 v125, s54, 0
	s_add_i32 s57, s8, s57
	v_mbcnt_hi_u32_b32 v125, s55, v125
	v_add_u32_e32 v124, 0x4c0, v0
	v_lshl_add_u32 v125, v125, 2, s57
	ds_write_b32 v125, v124 offset:16896
.LBB0_182:
	s_or_b64 exec, exec, s[0:1]
	s_bcnt1_i32_b64 s0, s[52:53]
	v_mbcnt_lo_u32_b32 v124, vcc_lo, 0
	s_add_i32 s4, s4, s0
	v_mbcnt_hi_u32_b32 v124, vcc_hi, v124
	v_add_u32_e32 v124, s4, v124
	s_movk_i32 s0, 0x100
	v_cmp_gt_i32_e64 s[0:1], s0, v124
	s_and_b64 s[52:53], vcc, s[0:1]
	s_and_saveexec_b64 s[0:1], s[52:53]
	v_lshl_add_u32 v124, v124, 2, s8
	v_add_u32_e32 v125, 0x4c0, v0
	ds_write_b32 v124, v125 offset:16896
	s_or_b64 exec, exec, s[0:1]
	s_bcnt1_i32_b64 s0, s[54:55]
	s_add_i32 s56, s56, s0
	v_cmp_gt_u32_e64 s[54:55], v110, v123
	v_cmp_eq_u32_e64 s[52:53], v110, v123
	s_and_saveexec_b64 s[0:1], s[54:55]
	s_cbranch_execz .LBB0_186
	s_lshl_b32 s57, s56, 2
	v_mbcnt_lo_u32_b32 v125, s54, 0
	s_add_i32 s57, s8, s57
	v_mbcnt_hi_u32_b32 v125, s55, v125
	v_add_u32_e32 v124, 0x500, v0
	v_lshl_add_u32 v125, v125, 2, s57
	ds_write_b32 v125, v124 offset:16896
.LBB0_186:
	s_or_b64 exec, exec, s[0:1]
	s_bcnt1_i32_b64 s0, vcc
	v_mbcnt_lo_u32_b32 v124, s52, 0
	s_add_i32 s4, s4, s0
	v_mbcnt_hi_u32_b32 v124, s53, v124
	v_add_u32_e32 v124, s4, v124
	s_movk_i32 s0, 0x100
	v_cmp_gt_i32_e32 vcc, s0, v124
	s_and_b64 s[58:59], s[52:53], vcc
	s_and_saveexec_b64 s[0:1], s[58:59]
	v_lshl_add_u32 v124, v124, 2, s8
	v_add_u32_e32 v125, 0x500, v0
	ds_write_b32 v124, v125 offset:16896
	s_or_b64 exec, exec, s[0:1]
	s_bcnt1_i32_b64 s0, s[54:55]
	s_add_i32 s56, s56, s0
	v_cmp_gt_u32_e64 s[54:55], v109, v123
	v_cmp_eq_u32_e32 vcc, v109, v123
	s_and_saveexec_b64 s[0:1], s[54:55]
	s_cbranch_execz .LBB0_190
	s_lshl_b32 s57, s56, 2
	v_mbcnt_lo_u32_b32 v125, s54, 0
	s_add_i32 s57, s8, s57
	v_mbcnt_hi_u32_b32 v125, s55, v125
	v_add_u32_e32 v124, 0x540, v0
	v_lshl_add_u32 v125, v125, 2, s57
	ds_write_b32 v125, v124 offset:16896
.LBB0_190:
	s_or_b64 exec, exec, s[0:1]
	s_bcnt1_i32_b64 s0, s[52:53]
	v_mbcnt_lo_u32_b32 v124, vcc_lo, 0
	s_add_i32 s4, s4, s0
	v_mbcnt_hi_u32_b32 v124, vcc_hi, v124
	v_add_u32_e32 v124, s4, v124
	s_movk_i32 s0, 0x100
	v_cmp_gt_i32_e64 s[0:1], s0, v124
	s_and_b64 s[52:53], vcc, s[0:1]
	s_and_saveexec_b64 s[0:1], s[52:53]
	v_lshl_add_u32 v124, v124, 2, s8
	v_add_u32_e32 v125, 0x540, v0
	ds_write_b32 v124, v125 offset:16896
	s_or_b64 exec, exec, s[0:1]
	s_bcnt1_i32_b64 s0, s[54:55]
	s_add_i32 s56, s56, s0
	v_cmp_gt_u32_e64 s[54:55], v108, v123
	v_cmp_eq_u32_e64 s[52:53], v108, v123
	s_and_saveexec_b64 s[0:1], s[54:55]
	s_cbranch_execz .LBB0_194
	s_lshl_b32 s57, s56, 2
	v_mbcnt_lo_u32_b32 v125, s54, 0
	s_add_i32 s57, s8, s57
	v_mbcnt_hi_u32_b32 v125, s55, v125
	v_add_u32_e32 v124, 0x580, v0
	v_lshl_add_u32 v125, v125, 2, s57
	ds_write_b32 v125, v124 offset:16896
.LBB0_194:
	s_or_b64 exec, exec, s[0:1]
	s_bcnt1_i32_b64 s0, vcc
	v_mbcnt_lo_u32_b32 v124, s52, 0
	s_add_i32 s4, s4, s0
	v_mbcnt_hi_u32_b32 v124, s53, v124
	v_add_u32_e32 v124, s4, v124
	s_movk_i32 s0, 0x100
	v_cmp_gt_i32_e32 vcc, s0, v124
	s_and_b64 s[58:59], s[52:53], vcc
	s_and_saveexec_b64 s[0:1], s[58:59]
	v_lshl_add_u32 v124, v124, 2, s8
	v_add_u32_e32 v125, 0x580, v0
	ds_write_b32 v124, v125 offset:16896
	s_or_b64 exec, exec, s[0:1]
	s_bcnt1_i32_b64 s0, s[54:55]
	s_add_i32 s56, s56, s0
	v_cmp_gt_u32_e64 s[54:55], v107, v123
	v_cmp_eq_u32_e32 vcc, v107, v123
	s_and_saveexec_b64 s[0:1], s[54:55]
	s_cbranch_execz .LBB0_198
	s_lshl_b32 s57, s56, 2
	v_mbcnt_lo_u32_b32 v125, s54, 0
	s_add_i32 s57, s8, s57
	v_mbcnt_hi_u32_b32 v125, s55, v125
	v_add_u32_e32 v124, 0x5c0, v0
	v_lshl_add_u32 v125, v125, 2, s57
	ds_write_b32 v125, v124 offset:16896
.LBB0_198:
	s_or_b64 exec, exec, s[0:1]
	s_bcnt1_i32_b64 s0, s[52:53]
	v_mbcnt_lo_u32_b32 v124, vcc_lo, 0
	s_add_i32 s4, s4, s0
	v_mbcnt_hi_u32_b32 v124, vcc_hi, v124
	v_add_u32_e32 v124, s4, v124
	s_movk_i32 s0, 0x100
	v_cmp_gt_i32_e64 s[0:1], s0, v124
	s_and_b64 s[52:53], vcc, s[0:1]
	s_and_saveexec_b64 s[0:1], s[52:53]
	v_lshl_add_u32 v124, v124, 2, s8
	v_add_u32_e32 v125, 0x5c0, v0
	ds_write_b32 v124, v125 offset:16896
	s_or_b64 exec, exec, s[0:1]
	s_bcnt1_i32_b64 s0, s[54:55]
	s_add_i32 s56, s56, s0
	v_cmp_gt_u32_e64 s[54:55], v106, v123
	v_cmp_eq_u32_e64 s[52:53], v106, v123
	s_and_saveexec_b64 s[0:1], s[54:55]
	s_cbranch_execz .LBB0_202
	s_lshl_b32 s57, s56, 2
	v_mbcnt_lo_u32_b32 v125, s54, 0
	s_add_i32 s57, s8, s57
	v_mbcnt_hi_u32_b32 v125, s55, v125
	v_add_u32_e32 v124, 0x600, v0
	v_lshl_add_u32 v125, v125, 2, s57
	ds_write_b32 v125, v124 offset:16896
.LBB0_202:
	s_or_b64 exec, exec, s[0:1]
	s_bcnt1_i32_b64 s0, vcc
	v_mbcnt_lo_u32_b32 v124, s52, 0
	s_add_i32 s4, s4, s0
	v_mbcnt_hi_u32_b32 v124, s53, v124
	v_add_u32_e32 v124, s4, v124
	s_movk_i32 s0, 0x100
	v_cmp_gt_i32_e32 vcc, s0, v124
	s_and_b64 s[58:59], s[52:53], vcc
	s_and_saveexec_b64 s[0:1], s[58:59]
	v_lshl_add_u32 v124, v124, 2, s8
	v_add_u32_e32 v125, 0x600, v0
	ds_write_b32 v124, v125 offset:16896
	s_or_b64 exec, exec, s[0:1]
	s_bcnt1_i32_b64 s0, s[54:55]
	s_add_i32 s56, s56, s0
	v_cmp_gt_u32_e64 s[54:55], v105, v123
	v_cmp_eq_u32_e32 vcc, v105, v123
	s_and_saveexec_b64 s[0:1], s[54:55]
	s_cbranch_execz .LBB0_206
	s_lshl_b32 s57, s56, 2
	v_mbcnt_lo_u32_b32 v125, s54, 0
	s_add_i32 s57, s8, s57
	v_mbcnt_hi_u32_b32 v125, s55, v125
	v_add_u32_e32 v124, 0x640, v0
	v_lshl_add_u32 v125, v125, 2, s57
	ds_write_b32 v125, v124 offset:16896
; __device__ __forceinline__ void topk_row(const Params& p, int r, int lane, __attribute__((address_space(3))) int* out) {
;     ...
;     int base_gt = 0, base_eq = cgt;
; #pragma unroll
;     for (int blk = 0; blk < 8; ++blk) {
;       if (blk * 16 < nch) {
; #pragma unroll
;         for (int ii = 0; ii < 16; ++ii) {
;           const int i = blk * 16 + ii;
;           const bool g = key[i] > Tv, e = key[i] == Tv;
;           const unsigned long long mg = __ballot(g), me = __ballot(e);
;           const int pg = base_gt + mbcnt64(mg);
;           if (g) out[pg] = i * 64 + lo;
;           base_gt += __popcll(mg);
;           const int pe = base_eq + mbcnt64(me);
;           if (e && pe < 256) out[pe] = i * 64 + lo;
;           base_eq += __popcll(me);
;         }
.LBB0_206:
	s_or_b64 exec, exec, s[0:1]
	s_bcnt1_i32_b64 s0, s[52:53]
	v_mbcnt_lo_u32_b32 v124, vcc_lo, 0
	s_add_i32 s4, s4, s0
	v_mbcnt_hi_u32_b32 v124, vcc_hi, v124
	v_add_u32_e32 v124, s4, v124
	s_movk_i32 s0, 0x100
	v_cmp_gt_i32_e64 s[0:1], s0, v124
	s_and_b64 s[52:53], vcc, s[0:1]
	s_and_saveexec_b64 s[0:1], s[52:53]
	v_lshl_add_u32 v124, v124, 2, s8
	v_add_u32_e32 v125, 0x640, v0
	ds_write_b32 v124, v125 offset:16896
	s_or_b64 exec, exec, s[0:1]
	s_bcnt1_i32_b64 s0, s[54:55]
	s_add_i32 s56, s56, s0
	v_cmp_gt_u32_e64 s[54:55], v104, v123
	v_cmp_eq_u32_e64 s[52:53], v104, v123
	s_and_saveexec_b64 s[0:1], s[54:55]
	s_cbranch_execz .LBB0_210
	s_lshl_b32 s57, s56, 2
	v_mbcnt_lo_u32_b32 v125, s54, 0
	s_add_i32 s57, s8, s57
	v_mbcnt_hi_u32_b32 v125, s55, v125
	v_add_u32_e32 v124, 0x680, v0
	v_lshl_add_u32 v125, v125, 2, s57
	ds_write_b32 v125, v124 offset:16896
.LBB0_210:
	s_or_b64 exec, exec, s[0:1]
	s_bcnt1_i32_b64 s0, vcc
	v_mbcnt_lo_u32_b32 v124, s52, 0
	s_add_i32 s4, s4, s0
	v_mbcnt_hi_u32_b32 v124, s53, v124
	v_add_u32_e32 v124, s4, v124
	s_movk_i32 s0, 0x100
	v_cmp_gt_i32_e32 vcc, s0, v124
	s_and_b64 s[58:59], s[52:53], vcc
	s_and_saveexec_b64 s[0:1], s[58:59]
	v_lshl_add_u32 v124, v124, 2, s8
	v_add_u32_e32 v125, 0x680, v0
	ds_write_b32 v124, v125 offset:16896
	s_or_b64 exec, exec, s[0:1]
	s_bcnt1_i32_b64 s0, s[54:55]
	s_add_i32 s56, s56, s0
	v_cmp_gt_u32_e64 s[54:55], v103, v123
	v_cmp_eq_u32_e32 vcc, v103, v123
	s_and_saveexec_b64 s[0:1], s[54:55]
	s_cbranch_execz .LBB0_214
	s_lshl_b32 s57, s56, 2
	v_mbcnt_lo_u32_b32 v125, s54, 0
	s_add_i32 s57, s8, s57
	v_mbcnt_hi_u32_b32 v125, s55, v125
	v_add_u32_e32 v124, 0x6c0, v0
	v_lshl_add_u32 v125, v125, 2, s57
	ds_write_b32 v125, v124 offset:16896
.LBB0_214:
	s_or_b64 exec, exec, s[0:1]
	s_bcnt1_i32_b64 s0, s[52:53]
	v_mbcnt_lo_u32_b32 v124, vcc_lo, 0
	s_add_i32 s4, s4, s0
	v_mbcnt_hi_u32_b32 v124, vcc_hi, v124
	v_add_u32_e32 v124, s4, v124
	s_movk_i32 s0, 0x100
	v_cmp_gt_i32_e64 s[0:1], s0, v124
	s_and_b64 s[52:53], vcc, s[0:1]
	s_and_saveexec_b64 s[0:1], s[52:53]
	v_lshl_add_u32 v124, v124, 2, s8
	v_add_u32_e32 v125, 0x6c0, v0
	ds_write_b32 v124, v125 offset:16896
	s_or_b64 exec, exec, s[0:1]
	s_bcnt1_i32_b64 s0, s[54:55]
	s_add_i32 s56, s56, s0
	v_cmp_gt_u32_e64 s[54:55], v102, v123
	v_cmp_eq_u32_e64 s[52:53], v102, v123
	s_and_saveexec_b64 s[0:1], s[54:55]
	s_cbranch_execz .LBB0_218
	s_lshl_b32 s57, s56, 2
	v_mbcnt_lo_u32_b32 v125, s54, 0
	s_add_i32 s57, s8, s57
	v_mbcnt_hi_u32_b32 v125, s55, v125
	v_add_u32_e32 v124, 0x700, v0
	v_lshl_add_u32 v125, v125, 2, s57
	ds_write_b32 v125, v124 offset:16896
.LBB0_218:
	s_or_b64 exec, exec, s[0:1]
	s_bcnt1_i32_b64 s0, vcc
	v_mbcnt_lo_u32_b32 v124, s52, 0
	s_add_i32 s4, s4, s0
	v_mbcnt_hi_u32_b32 v124, s53, v124
	v_add_u32_e32 v124, s4, v124
	s_movk_i32 s0, 0x100
	v_cmp_gt_i32_e32 vcc, s0, v124
	s_and_b64 s[58:59], s[52:53], vcc
	s_and_saveexec_b64 s[0:1], s[58:59]
	v_lshl_add_u32 v124, v124, 2, s8
	v_add_u32_e32 v125, 0x700, v0
	ds_write_b32 v124, v125 offset:16896
	s_or_b64 exec, exec, s[0:1]
	s_bcnt1_i32_b64 s0, s[54:55]
	s_add_i32 s56, s56, s0
	v_cmp_gt_u32_e64 s[54:55], v101, v123
	v_cmp_eq_u32_e32 vcc, v101, v123
	s_and_saveexec_b64 s[0:1], s[54:55]
	s_cbranch_execz .LBB0_222
	s_lshl_b32 s57, s56, 2
	v_mbcnt_lo_u32_b32 v125, s54, 0
	s_add_i32 s57, s8, s57
	v_mbcnt_hi_u32_b32 v125, s55, v125
	v_add_u32_e32 v124, 0x740, v0
	v_lshl_add_u32 v125, v125, 2, s57
	ds_write_b32 v125, v124 offset:16896
.LBB0_222:
	s_or_b64 exec, exec, s[0:1]
	s_bcnt1_i32_b64 s0, s[52:53]
	v_mbcnt_lo_u32_b32 v124, vcc_lo, 0
	s_add_i32 s4, s4, s0
	v_mbcnt_hi_u32_b32 v124, vcc_hi, v124
	v_add_u32_e32 v124, s4, v124
	s_movk_i32 s0, 0x100
	v_cmp_gt_i32_e64 s[0:1], s0, v124
	s_and_b64 s[52:53], vcc, s[0:1]
	s_and_saveexec_b64 s[0:1], s[52:53]
	v_lshl_add_u32 v124, v124, 2, s8
	v_add_u32_e32 v125, 0x740, v0
	ds_write_b32 v124, v125 offset:16896
	s_or_b64 exec, exec, s[0:1]
	s_bcnt1_i32_b64 s0, s[54:55]
	s_add_i32 s56, s56, s0
	v_cmp_gt_u32_e64 s[54:55], v100, v123
	v_cmp_eq_u32_e64 s[52:53], v100, v123
	s_and_saveexec_b64 s[0:1], s[54:55]
	s_cbranch_execz .LBB0_226
	s_lshl_b32 s57, s56, 2
	v_mbcnt_lo_u32_b32 v125, s54, 0
	s_add_i32 s57, s8, s57
	v_mbcnt_hi_u32_b32 v125, s55, v125
	v_add_u32_e32 v124, 0x780, v0
	v_lshl_add_u32 v125, v125, 2, s57
	ds_write_b32 v125, v124 offset:16896
.LBB0_226:
	s_or_b64 exec, exec, s[0:1]
	s_bcnt1_i32_b64 s0, vcc
	v_mbcnt_lo_u32_b32 v124, s52, 0
	s_add_i32 s4, s4, s0
	v_mbcnt_hi_u32_b32 v124, s53, v124
	v_add_u32_e32 v124, s4, v124
	s_movk_i32 s0, 0x100
	v_cmp_gt_i32_e32 vcc, s0, v124
	s_and_b64 s[58:59], s[52:53], vcc
	s_and_saveexec_b64 s[0:1], s[58:59]
	v_lshl_add_u32 v124, v124, 2, s8
	v_add_u32_e32 v125, 0x780, v0
	ds_write_b32 v124, v125 offset:16896
	s_or_b64 exec, exec, s[0:1]
	s_bcnt1_i32_b64 s0, s[54:55]
	s_add_i32 s56, s56, s0
	v_cmp_gt_u32_e64 s[54:55], v99, v123
	v_cmp_eq_u32_e32 vcc, v99, v123
	s_and_saveexec_b64 s[0:1], s[54:55]
	s_cbranch_execz .LBB0_230
	s_lshl_b32 s57, s56, 2
	v_mbcnt_lo_u32_b32 v125, s54, 0
	s_add_i32 s57, s8, s57
	v_mbcnt_hi_u32_b32 v125, s55, v125
	v_add_u32_e32 v124, 0x7c0, v0
	v_lshl_add_u32 v125, v125, 2, s57
	ds_write_b32 v125, v124 offset:16896
.LBB0_230:
	s_or_b64 exec, exec, s[0:1]
	s_bcnt1_i32_b64 s0, s[52:53]
	v_mbcnt_lo_u32_b32 v124, vcc_lo, 0
	s_add_i32 s4, s4, s0
	v_mbcnt_hi_u32_b32 v124, vcc_hi, v124
	v_add_u32_e32 v124, s4, v124
	s_movk_i32 s0, 0x100
	v_cmp_gt_i32_e64 s[0:1], s0, v124
	s_and_b64 s[52:53], vcc, s[0:1]
	s_and_saveexec_b64 s[0:1], s[52:53]
	v_lshl_add_u32 v124, v124, 2, s8
	v_add_u32_e32 v125, 0x7c0, v0
	ds_write_b32 v124, v125 offset:16896
	s_or_b64 exec, exec, s[0:1]
	s_bcnt1_i32_b64 s0, s[54:55]
	s_add_i32 s54, s56, s0
	s_bcnt1_i32_b64 s0, vcc
	s_add_i32 s4, s4, s0
; __device__ __forceinline__ void topk_row(const Params& p, int r, int lane, __attribute__((address_space(3))) int* out) {
;     ...
;     int base_gt = 0, base_eq = cgt;
; #pragma unroll
;     for (int blk = 0; blk < 8; ++blk) {
;       if (blk * 16 < nch) {
; #pragma unroll
;         for (int ii = 0; ii < 16; ++ii) {
;           const int i = blk * 16 + ii;
;           const bool g = key[i] > Tv, e = key[i] == Tv;
;           const unsigned long long mg = __ballot(g), me = __ballot(e);
;           const int pg = base_gt + mbcnt64(mg);
;           if (g) out[pg] = i * 64 + lo;
;           base_gt += __popcll(mg);
;           const int pe = base_eq + mbcnt64(me);
;           if (e && pe < 256) out[pe] = i * 64 + lo;
;           base_eq += __popcll(me);
;         }
.LBB0_233:
	s_and_b64 vcc, exec, s[6:7]
	s_cbranch_vccnz .LBB0_299
	v_cmp_gt_u32_e32 vcc, v98, v123
	v_cmp_eq_u32_e64 s[52:53], v98, v123
	s_and_saveexec_b64 s[0:1], vcc
	s_cbranch_execz .LBB0_236
	s_lshl_b32 s55, s54, 2
	v_mbcnt_lo_u32_b32 v125, vcc_lo, 0
	s_add_i32 s55, s8, s55
	v_mbcnt_hi_u32_b32 v125, vcc_hi, v125
	v_add_u32_e32 v124, 0x800, v0
	v_lshl_add_u32 v125, v125, 2, s55
	ds_write_b32 v125, v124 offset:16896
.LBB0_236:
	s_or_b64 exec, exec, s[0:1]
	v_mbcnt_lo_u32_b32 v124, s52, 0
	v_mbcnt_hi_u32_b32 v124, s53, v124
	v_add_u32_e32 v124, s4, v124
	s_movk_i32 s0, 0x100
	v_cmp_gt_i32_e64 s[0:1], s0, v124
	s_and_b64 s[56:57], s[52:53], s[0:1]
	s_and_saveexec_b64 s[0:1], s[56:57]
	v_lshl_add_u32 v124, v124, 2, s8
	v_add_u32_e32 v125, 0x800, v0
	ds_write_b32 v124, v125 offset:16896
	s_or_b64 exec, exec, s[0:1]
	s_bcnt1_i32_b64 s0, vcc
	s_add_i32 s56, s54, s0
	v_cmp_gt_u32_e64 s[54:55], v97, v123
	v_cmp_eq_u32_e32 vcc, v97, v123
	s_and_saveexec_b64 s[0:1], s[54:55]
	s_cbranch_execz .LBB0_240
	s_lshl_b32 s57, s56, 2
	v_mbcnt_lo_u32_b32 v125, s54, 0
	s_add_i32 s57, s8, s57
	v_mbcnt_hi_u32_b32 v125, s55, v125
	v_add_u32_e32 v124, 0x840, v0
	v_lshl_add_u32 v125, v125, 2, s57
	ds_write_b32 v125, v124 offset:16896
.LBB0_240:
	s_or_b64 exec, exec, s[0:1]
	s_bcnt1_i32_b64 s0, s[52:53]
	v_mbcnt_lo_u32_b32 v124, vcc_lo, 0
	s_add_i32 s4, s4, s0
	v_mbcnt_hi_u32_b32 v124, vcc_hi, v124
	v_add_u32_e32 v124, s4, v124
	s_movk_i32 s0, 0x100
	v_cmp_gt_i32_e64 s[0:1], s0, v124
	s_and_b64 s[52:53], vcc, s[0:1]
	s_and_saveexec_b64 s[0:1], s[52:53]
	v_lshl_add_u32 v124, v124, 2, s8
	v_add_u32_e32 v125, 0x840, v0
	ds_write_b32 v124, v125 offset:16896
	s_or_b64 exec, exec, s[0:1]
	s_bcnt1_i32_b64 s0, s[54:55]
	s_add_i32 s56, s56, s0
	v_cmp_gt_u32_e64 s[54:55], v96, v123
	v_cmp_eq_u32_e64 s[52:53], v96, v123
	s_and_saveexec_b64 s[0:1], s[54:55]
	s_cbranch_execz .LBB0_244
	s_lshl_b32 s57, s56, 2
	v_mbcnt_lo_u32_b32 v125, s54, 0
	s_add_i32 s57, s8, s57
	v_mbcnt_hi_u32_b32 v125, s55, v125
	v_add_u32_e32 v124, 0x880, v0
	v_lshl_add_u32 v125, v125, 2, s57
	ds_write_b32 v125, v124 offset:16896
.LBB0_244:
	s_or_b64 exec, exec, s[0:1]
	s_bcnt1_i32_b64 s0, vcc
	v_mbcnt_lo_u32_b32 v124, s52, 0
	s_add_i32 s4, s4, s0
	v_mbcnt_hi_u32_b32 v124, s53, v124
	v_add_u32_e32 v124, s4, v124
	s_movk_i32 s0, 0x100
	v_cmp_gt_i32_e32 vcc, s0, v124
	s_and_b64 s[58:59], s[52:53], vcc
	s_and_saveexec_b64 s[0:1], s[58:59]
	v_lshl_add_u32 v124, v124, 2, s8
	v_add_u32_e32 v125, 0x880, v0
	ds_write_b32 v124, v125 offset:16896
	s_or_b64 exec, exec, s[0:1]
	s_bcnt1_i32_b64 s0, s[54:55]
	s_add_i32 s56, s56, s0
	v_cmp_gt_u32_e64 s[54:55], v95, v123
	v_cmp_eq_u32_e32 vcc, v95, v123
	s_and_saveexec_b64 s[0:1], s[54:55]
	s_cbranch_execz .LBB0_248
	s_lshl_b32 s57, s56, 2
	v_mbcnt_lo_u32_b32 v125, s54, 0
	s_add_i32 s57, s8, s57
	v_mbcnt_hi_u32_b32 v125, s55, v125
	v_add_u32_e32 v124, 0x8c0, v0
	v_lshl_add_u32 v125, v125, 2, s57
	ds_write_b32 v125, v124 offset:16896
.LBB0_248:
	s_or_b64 exec, exec, s[0:1]
	s_bcnt1_i32_b64 s0, s[52:53]
	v_mbcnt_lo_u32_b32 v124, vcc_lo, 0
	s_add_i32 s4, s4, s0
	v_mbcnt_hi_u32_b32 v124, vcc_hi, v124
	v_add_u32_e32 v124, s4, v124
	s_movk_i32 s0, 0x100
	v_cmp_gt_i32_e64 s[0:1], s0, v124
	s_and_b64 s[52:53], vcc, s[0:1]
	s_and_saveexec_b64 s[0:1], s[52:53]
	v_lshl_add_u32 v124, v124, 2, s8
	v_add_u32_e32 v125, 0x8c0, v0
	ds_write_b32 v124, v125 offset:16896
	s_or_b64 exec, exec, s[0:1]
	s_bcnt1_i32_b64 s0, s[54:55]
	s_add_i32 s56, s56, s0
	v_cmp_gt_u32_e64 s[54:55], v94, v123
	v_cmp_eq_u32_e64 s[52:53], v94, v123
	s_and_saveexec_b64 s[0:1], s[54:55]
	s_cbranch_execz .LBB0_252
	s_lshl_b32 s57, s56, 2
	v_mbcnt_lo_u32_b32 v125, s54, 0
	s_add_i32 s57, s8, s57
	v_mbcnt_hi_u32_b32 v125, s55, v125
	v_add_u32_e32 v124, 0x900, v0
	v_lshl_add_u32 v125, v125, 2, s57
	ds_write_b32 v125, v124 offset:16896
.LBB0_252:
	s_or_b64 exec, exec, s[0:1]
	s_bcnt1_i32_b64 s0, vcc
	v_mbcnt_lo_u32_b32 v124, s52, 0
	s_add_i32 s4, s4, s0
	v_mbcnt_hi_u32_b32 v124, s53, v124
	v_add_u32_e32 v124, s4, v124
	s_movk_i32 s0, 0x100
	v_cmp_gt_i32_e32 vcc, s0, v124
	s_and_b64 s[58:59], s[52:53], vcc
	s_and_saveexec_b64 s[0:1], s[58:59]
	v_lshl_add_u32 v124, v124, 2, s8
	v_add_u32_e32 v125, 0x900, v0
	ds_write_b32 v124, v125 offset:16896
	s_or_b64 exec, exec, s[0:1]
	s_bcnt1_i32_b64 s0, s[54:55]
	s_add_i32 s56, s56, s0
	v_cmp_gt_u32_e64 s[54:55], v93, v123
	v_cmp_eq_u32_e32 vcc, v93, v123
	s_and_saveexec_b64 s[0:1], s[54:55]
	s_cbranch_execz .LBB0_256
	s_lshl_b32 s57, s56, 2
	v_mbcnt_lo_u32_b32 v125, s54, 0
	s_add_i32 s57, s8, s57
	v_mbcnt_hi_u32_b32 v125, s55, v125
	v_add_u32_e32 v124, 0x940, v0
	v_lshl_add_u32 v125, v125, 2, s57
	ds_write_b32 v125, v124 offset:16896
.LBB0_256:
	s_or_b64 exec, exec, s[0:1]
	s_bcnt1_i32_b64 s0, s[52:53]
	v_mbcnt_lo_u32_b32 v124, vcc_lo, 0
	s_add_i32 s4, s4, s0
	v_mbcnt_hi_u32_b32 v124, vcc_hi, v124
	v_add_u32_e32 v124, s4, v124
	s_movk_i32 s0, 0x100
	v_cmp_gt_i32_e64 s[0:1], s0, v124
	s_and_b64 s[52:53], vcc, s[0:1]
	s_and_saveexec_b64 s[0:1], s[52:53]
	v_lshl_add_u32 v124, v124, 2, s8
	v_add_u32_e32 v125, 0x940, v0
	ds_write_b32 v124, v125 offset:16896
	s_or_b64 exec, exec, s[0:1]
	s_bcnt1_i32_b64 s0, s[54:55]
	s_add_i32 s56, s56, s0
	v_cmp_gt_u32_e64 s[54:55], v92, v123
	v_cmp_eq_u32_e64 s[52:53], v92, v123
	s_and_saveexec_b64 s[0:1], s[54:55]
	s_cbranch_execz .LBB0_260
	s_lshl_b32 s57, s56, 2
	v_mbcnt_lo_u32_b32 v125, s54, 0
	s_add_i32 s57, s8, s57
	v_mbcnt_hi_u32_b32 v125, s55, v125
	v_add_u32_e32 v124, 0x980, v0
	v_lshl_add_u32 v125, v125, 2, s57
	ds_write_b32 v125, v124 offset:16896
; __device__ __forceinline__ void topk_row(const Params& p, int r, int lane, __attribute__((address_space(3))) int* out) {
;     ...
;     int base_gt = 0, base_eq = cgt;
; #pragma unroll
;     for (int blk = 0; blk < 8; ++blk) {
;       if (blk * 16 < nch) {
; #pragma unroll
;         for (int ii = 0; ii < 16; ++ii) {
;           const int i = blk * 16 + ii;
;           const bool g = key[i] > Tv, e = key[i] == Tv;
;           const unsigned long long mg = __ballot(g), me = __ballot(e);
;           const int pg = base_gt + mbcnt64(mg);
;           if (g) out[pg] = i * 64 + lo;
;           base_gt += __popcll(mg);
;           const int pe = base_eq + mbcnt64(me);
;           if (e && pe < 256) out[pe] = i * 64 + lo;
;           base_eq += __popcll(me);
;         }
.LBB0_260:
	s_or_b64 exec, exec, s[0:1]
	s_bcnt1_i32_b64 s0, vcc
	v_mbcnt_lo_u32_b32 v124, s52, 0
	s_add_i32 s4, s4, s0
	v_mbcnt_hi_u32_b32 v124, s53, v124
	v_add_u32_e32 v124, s4, v124
	s_movk_i32 s0, 0x100
	v_cmp_gt_i32_e32 vcc, s0, v124
	s_and_b64 s[58:59], s[52:53], vcc
	s_and_saveexec_b64 s[0:1], s[58:59]
	v_lshl_add_u32 v124, v124, 2, s8
	v_add_u32_e32 v125, 0x980, v0
	ds_write_b32 v124, v125 offset:16896
	s_or_b64 exec, exec, s[0:1]
	s_bcnt1_i32_b64 s0, s[54:55]
	s_add_i32 s56, s56, s0
	v_cmp_gt_u32_e64 s[54:55], v91, v123
	v_cmp_eq_u32_e32 vcc, v91, v123
	s_and_saveexec_b64 s[0:1], s[54:55]
	s_cbranch_execz .LBB0_264
	s_lshl_b32 s57, s56, 2
	v_mbcnt_lo_u32_b32 v125, s54, 0
	s_add_i32 s57, s8, s57
	v_mbcnt_hi_u32_b32 v125, s55, v125
	v_add_u32_e32 v124, 0x9c0, v0
	v_lshl_add_u32 v125, v125, 2, s57
	ds_write_b32 v125, v124 offset:16896
.LBB0_264:
	s_or_b64 exec, exec, s[0:1]
	s_bcnt1_i32_b64 s0, s[52:53]
	v_mbcnt_lo_u32_b32 v124, vcc_lo, 0
	s_add_i32 s4, s4, s0
	v_mbcnt_hi_u32_b32 v124, vcc_hi, v124
	v_add_u32_e32 v124, s4, v124
	s_movk_i32 s0, 0x100
	v_cmp_gt_i32_e64 s[0:1], s0, v124
	s_and_b64 s[52:53], vcc, s[0:1]
	s_and_saveexec_b64 s[0:1], s[52:53]
	v_lshl_add_u32 v124, v124, 2, s8
	v_add_u32_e32 v125, 0x9c0, v0
	ds_write_b32 v124, v125 offset:16896
	s_or_b64 exec, exec, s[0:1]
	s_bcnt1_i32_b64 s0, s[54:55]
	s_add_i32 s56, s56, s0
	v_cmp_gt_u32_e64 s[54:55], v90, v123
	v_cmp_eq_u32_e64 s[52:53], v90, v123
	s_and_saveexec_b64 s[0:1], s[54:55]
	s_cbranch_execz .LBB0_268
	s_lshl_b32 s57, s56, 2
	v_mbcnt_lo_u32_b32 v125, s54, 0
	s_add_i32 s57, s8, s57
	v_mbcnt_hi_u32_b32 v125, s55, v125
	v_add_u32_e32 v124, 0xa00, v0
	v_lshl_add_u32 v125, v125, 2, s57
	ds_write_b32 v125, v124 offset:16896
.LBB0_268:
	s_or_b64 exec, exec, s[0:1]
	s_bcnt1_i32_b64 s0, vcc
	v_mbcnt_lo_u32_b32 v124, s52, 0
	s_add_i32 s4, s4, s0
	v_mbcnt_hi_u32_b32 v124, s53, v124
	v_add_u32_e32 v124, s4, v124
	s_movk_i32 s0, 0x100
	v_cmp_gt_i32_e32 vcc, s0, v124
	s_and_b64 s[58:59], s[52:53], vcc
	s_and_saveexec_b64 s[0:1], s[58:59]
	v_lshl_add_u32 v124, v124, 2, s8
	v_add_u32_e32 v125, 0xa00, v0
	ds_write_b32 v124, v125 offset:16896
	s_or_b64 exec, exec, s[0:1]
	s_bcnt1_i32_b64 s0, s[54:55]
	s_add_i32 s56, s56, s0
	v_cmp_gt_u32_e64 s[54:55], v89, v123
	v_cmp_eq_u32_e32 vcc, v89, v123
	s_and_saveexec_b64 s[0:1], s[54:55]
	s_cbranch_execz .LBB0_272
	s_lshl_b32 s57, s56, 2
	v_mbcnt_lo_u32_b32 v125, s54, 0
	s_add_i32 s57, s8, s57
	v_mbcnt_hi_u32_b32 v125, s55, v125
	v_add_u32_e32 v124, 0xa40, v0
	v_lshl_add_u32 v125, v125, 2, s57
	ds_write_b32 v125, v124 offset:16896
.LBB0_272:
	s_or_b64 exec, exec, s[0:1]
	s_bcnt1_i32_b64 s0, s[52:53]
	v_mbcnt_lo_u32_b32 v124, vcc_lo, 0
	s_add_i32 s4, s4, s0
	v_mbcnt_hi_u32_b32 v124, vcc_hi, v124
	v_add_u32_e32 v124, s4, v124
	s_movk_i32 s0, 0x100
	v_cmp_gt_i32_e64 s[0:1], s0, v124
	s_and_b64 s[52:53], vcc, s[0:1]
	s_and_saveexec_b64 s[0:1], s[52:53]
	v_lshl_add_u32 v124, v124, 2, s8
	v_add_u32_e32 v125, 0xa40, v0
	ds_write_b32 v124, v125 offset:16896
	s_or_b64 exec, exec, s[0:1]
	s_bcnt1_i32_b64 s0, s[54:55]
	s_add_i32 s56, s56, s0
	v_cmp_gt_u32_e64 s[54:55], v88, v123
	v_cmp_eq_u32_e64 s[52:53], v88, v123
	s_and_saveexec_b64 s[0:1], s[54:55]
	s_cbranch_execz .LBB0_276
	s_lshl_b32 s57, s56, 2
	v_mbcnt_lo_u32_b32 v125, s54, 0
	s_add_i32 s57, s8, s57
	v_mbcnt_hi_u32_b32 v125, s55, v125
	v_add_u32_e32 v124, 0xa80, v0
	v_lshl_add_u32 v125, v125, 2, s57
	ds_write_b32 v125, v124 offset:16896
.LBB0_276:
	s_or_b64 exec, exec, s[0:1]
	s_bcnt1_i32_b64 s0, vcc
	v_mbcnt_lo_u32_b32 v124, s52, 0
	s_add_i32 s4, s4, s0
	v_mbcnt_hi_u32_b32 v124, s53, v124
	v_add_u32_e32 v124, s4, v124
	s_movk_i32 s0, 0x100
	v_cmp_gt_i32_e32 vcc, s0, v124
	s_and_b64 s[58:59], s[52:53], vcc
	s_and_saveexec_b64 s[0:1], s[58:59]
	v_lshl_add_u32 v124, v124, 2, s8
	v_add_u32_e32 v125, 0xa80, v0
	ds_write_b32 v124, v125 offset:16896
	s_or_b64 exec, exec, s[0:1]
	s_bcnt1_i32_b64 s0, s[54:55]
	s_add_i32 s56, s56, s0
	v_cmp_gt_u32_e64 s[54:55], v87, v123
	v_cmp_eq_u32_e32 vcc, v87, v123
	s_and_saveexec_b64 s[0:1], s[54:55]
	s_cbranch_execz .LBB0_280
	s_lshl_b32 s57, s56, 2
	v_mbcnt_lo_u32_b32 v125, s54, 0
	s_add_i32 s57, s8, s57
	v_mbcnt_hi_u32_b32 v125, s55, v125
	v_add_u32_e32 v124, 0xac0, v0
	v_lshl_add_u32 v125, v125, 2, s57
	ds_write_b32 v125, v124 offset:16896
.LBB0_280:
	s_or_b64 exec, exec, s[0:1]
	s_bcnt1_i32_b64 s0, s[52:53]
	v_mbcnt_lo_u32_b32 v124, vcc_lo, 0
	s_add_i32 s4, s4, s0
	v_mbcnt_hi_u32_b32 v124, vcc_hi, v124
	v_add_u32_e32 v124, s4, v124
	s_movk_i32 s0, 0x100
	v_cmp_gt_i32_e64 s[0:1], s0, v124
	s_and_b64 s[52:53], vcc, s[0:1]
	s_and_saveexec_b64 s[0:1], s[52:53]
	v_lshl_add_u32 v124, v124, 2, s8
	v_add_u32_e32 v125, 0xac0, v0
	ds_write_b32 v124, v125 offset:16896
	s_or_b64 exec, exec, s[0:1]
	s_bcnt1_i32_b64 s0, s[54:55]
	s_add_i32 s56, s56, s0
	v_cmp_gt_u32_e64 s[54:55], v86, v123
	v_cmp_eq_u32_e64 s[52:53], v86, v123
	s_and_saveexec_b64 s[0:1], s[54:55]
	s_cbranch_execz .LBB0_284
	s_lshl_b32 s57, s56, 2
	v_mbcnt_lo_u32_b32 v125, s54, 0
	s_add_i32 s57, s8, s57
	v_mbcnt_hi_u32_b32 v125, s55, v125
	v_add_u32_e32 v124, 0xb00, v0
	v_lshl_add_u32 v125, v125, 2, s57
	ds_write_b32 v125, v124 offset:16896
.LBB0_284:
	s_or_b64 exec, exec, s[0:1]
	s_bcnt1_i32_b64 s0, vcc
	v_mbcnt_lo_u32_b32 v124, s52, 0
	s_add_i32 s4, s4, s0
	v_mbcnt_hi_u32_b32 v124, s53, v124
	v_add_u32_e32 v124, s4, v124
	s_movk_i32 s0, 0x100
	v_cmp_gt_i32_e32 vcc, s0, v124
	s_and_b64 s[58:59], s[52:53], vcc
	s_and_saveexec_b64 s[0:1], s[58:59]
	v_lshl_add_u32 v124, v124, 2, s8
	v_add_u32_e32 v125, 0xb00, v0
	ds_write_b32 v124, v125 offset:16896
	s_or_b64 exec, exec, s[0:1]
	s_bcnt1_i32_b64 s0, s[54:55]
	s_add_i32 s56, s56, s0
	v_cmp_gt_u32_e64 s[54:55], v85, v123
	v_cmp_eq_u32_e32 vcc, v85, v123
	s_and_saveexec_b64 s[0:1], s[54:55]
	s_cbranch_execz .LBB0_288
	s_lshl_b32 s57, s56, 2
	v_mbcnt_lo_u32_b32 v125, s54, 0
	s_add_i32 s57, s8, s57
	v_mbcnt_hi_u32_b32 v125, s55, v125
	v_add_u32_e32 v124, 0xb40, v0
	v_lshl_add_u32 v125, v125, 2, s57
	ds_write_b32 v125, v124 offset:16896
; __device__ __forceinline__ void topk_row(const Params& p, int r, int lane, __attribute__((address_space(3))) int* out) {
;     ...
;     int base_gt = 0, base_eq = cgt;
; #pragma unroll
;     for (int blk = 0; blk < 8; ++blk) {
;       if (blk * 16 < nch) {
; #pragma unroll
;         for (int ii = 0; ii < 16; ++ii) {
;           const int i = blk * 16 + ii;
;           const bool g = key[i] > Tv, e = key[i] == Tv;
;           const unsigned long long mg = __ballot(g), me = __ballot(e);
;           const int pg = base_gt + mbcnt64(mg);
;           if (g) out[pg] = i * 64 + lo;
;           base_gt += __popcll(mg);
;           const int pe = base_eq + mbcnt64(me);
;           if (e && pe < 256) out[pe] = i * 64 + lo;
;           base_eq += __popcll(me);
;         }
.LBB0_288:
	s_or_b64 exec, exec, s[0:1]
	s_bcnt1_i32_b64 s0, s[52:53]
	v_mbcnt_lo_u32_b32 v124, vcc_lo, 0
	s_add_i32 s4, s4, s0
	v_mbcnt_hi_u32_b32 v124, vcc_hi, v124
	v_add_u32_e32 v124, s4, v124
	s_movk_i32 s0, 0x100
	v_cmp_gt_i32_e64 s[0:1], s0, v124
	s_and_b64 s[52:53], vcc, s[0:1]
	s_and_saveexec_b64 s[0:1], s[52:53]
	v_lshl_add_u32 v124, v124, 2, s8
	v_add_u32_e32 v125, 0xb40, v0
	ds_write_b32 v124, v125 offset:16896
	s_or_b64 exec, exec, s[0:1]
	s_bcnt1_i32_b64 s0, s[54:55]
	s_add_i32 s56, s56, s0
	v_cmp_gt_u32_e64 s[54:55], v84, v123
	v_cmp_eq_u32_e64 s[52:53], v84, v123
	s_and_saveexec_b64 s[0:1], s[54:55]
	s_cbranch_execz .LBB0_292
	s_lshl_b32 s57, s56, 2
	v_mbcnt_lo_u32_b32 v125, s54, 0
	s_add_i32 s57, s8, s57
	v_mbcnt_hi_u32_b32 v125, s55, v125
	v_add_u32_e32 v124, 0xb80, v0
	v_lshl_add_u32 v125, v125, 2, s57
	ds_write_b32 v125, v124 offset:16896
.LBB0_292:
	s_or_b64 exec, exec, s[0:1]
	s_bcnt1_i32_b64 s0, vcc
	v_mbcnt_lo_u32_b32 v124, s52, 0
	s_add_i32 s4, s4, s0
	v_mbcnt_hi_u32_b32 v124, s53, v124
	v_add_u32_e32 v124, s4, v124
	s_movk_i32 s0, 0x100
	v_cmp_gt_i32_e32 vcc, s0, v124
	s_and_b64 s[58:59], s[52:53], vcc
	s_and_saveexec_b64 s[0:1], s[58:59]
	v_lshl_add_u32 v124, v124, 2, s8
	v_add_u32_e32 v125, 0xb80, v0
	ds_write_b32 v124, v125 offset:16896
	s_or_b64 exec, exec, s[0:1]
	s_bcnt1_i32_b64 s0, s[54:55]
	s_add_i32 s56, s56, s0
	v_cmp_gt_u32_e64 s[54:55], v83, v123
	v_cmp_eq_u32_e32 vcc, v83, v123
	s_and_saveexec_b64 s[0:1], s[54:55]
	s_cbranch_execz .LBB0_296
	s_lshl_b32 s57, s56, 2
	v_mbcnt_lo_u32_b32 v125, s54, 0
	s_add_i32 s57, s8, s57
	v_mbcnt_hi_u32_b32 v125, s55, v125
	v_add_u32_e32 v124, 0xbc0, v0
	v_lshl_add_u32 v125, v125, 2, s57
	ds_write_b32 v125, v124 offset:16896
.LBB0_296:
	s_or_b64 exec, exec, s[0:1]
	s_bcnt1_i32_b64 s0, s[52:53]
	v_mbcnt_lo_u32_b32 v124, vcc_lo, 0
	s_add_i32 s4, s4, s0
	v_mbcnt_hi_u32_b32 v124, vcc_hi, v124
	v_add_u32_e32 v124, s4, v124
	s_movk_i32 s0, 0x100
	v_cmp_gt_i32_e64 s[0:1], s0, v124
	s_and_b64 s[52:53], vcc, s[0:1]
	s_and_saveexec_b64 s[0:1], s[52:53]
	v_lshl_add_u32 v124, v124, 2, s8
	v_add_u32_e32 v125, 0xbc0, v0
	ds_write_b32 v124, v125 offset:16896
	s_or_b64 exec, exec, s[0:1]
	s_bcnt1_i32_b64 s0, s[54:55]
	s_add_i32 s54, s56, s0
	s_bcnt1_i32_b64 s0, vcc
	s_add_i32 s4, s4, s0
.LBB0_299:
	v_readlane_b32 s0, v244, 2
	v_readlane_b32 s1, v244, 3
	s_and_b64 vcc, exec, s[0:1]
	s_cbranch_vccnz .LBB0_365
	v_cmp_gt_u32_e32 vcc, v82, v123
	v_cmp_eq_u32_e64 s[52:53], v82, v123
	s_and_saveexec_b64 s[0:1], vcc
	s_cbranch_execz .LBB0_302
	s_lshl_b32 s55, s54, 2
	v_mbcnt_lo_u32_b32 v125, vcc_lo, 0
	s_add_i32 s55, s8, s55
	v_mbcnt_hi_u32_b32 v125, vcc_hi, v125
	v_add_u32_e32 v124, 0xc00, v0
	v_lshl_add_u32 v125, v125, 2, s55
	ds_write_b32 v125, v124 offset:16896
.LBB0_302:
	s_or_b64 exec, exec, s[0:1]
	v_mbcnt_lo_u32_b32 v124, s52, 0
	v_mbcnt_hi_u32_b32 v124, s53, v124
	v_add_u32_e32 v124, s4, v124
	s_movk_i32 s0, 0x100
	v_cmp_gt_i32_e64 s[0:1], s0, v124
	s_and_b64 s[56:57], s[52:53], s[0:1]
	s_and_saveexec_b64 s[0:1], s[56:57]
	v_lshl_add_u32 v124, v124, 2, s8
	v_add_u32_e32 v125, 0xc00, v0
	ds_write_b32 v124, v125 offset:16896
	s_or_b64 exec, exec, s[0:1]
	s_bcnt1_i32_b64 s0, vcc
	s_add_i32 s56, s54, s0
	v_cmp_gt_u32_e64 s[54:55], v81, v123
	v_cmp_eq_u32_e32 vcc, v81, v123
	s_and_saveexec_b64 s[0:1], s[54:55]
	s_cbranch_execz .LBB0_306
	s_lshl_b32 s57, s56, 2
	v_mbcnt_lo_u32_b32 v125, s54, 0
	s_add_i32 s57, s8, s57
	v_mbcnt_hi_u32_b32 v125, s55, v125
	v_add_u32_e32 v124, 0xc40, v0
	v_lshl_add_u32 v125, v125, 2, s57
	ds_write_b32 v125, v124 offset:16896
.LBB0_306:
	s_or_b64 exec, exec, s[0:1]
	s_bcnt1_i32_b64 s0, s[52:53]
	v_mbcnt_lo_u32_b32 v124, vcc_lo, 0
	s_add_i32 s4, s4, s0
	v_mbcnt_hi_u32_b32 v124, vcc_hi, v124
	v_add_u32_e32 v124, s4, v124
	s_movk_i32 s0, 0x100
	v_cmp_gt_i32_e64 s[0:1], s0, v124
	s_and_b64 s[52:53], vcc, s[0:1]
	s_and_saveexec_b64 s[0:1], s[52:53]
	v_lshl_add_u32 v124, v124, 2, s8
	v_add_u32_e32 v125, 0xc40, v0
	ds_write_b32 v124, v125 offset:16896
	s_or_b64 exec, exec, s[0:1]
	s_bcnt1_i32_b64 s0, s[54:55]
	s_add_i32 s56, s56, s0
	v_cmp_gt_u32_e64 s[54:55], v80, v123
	v_cmp_eq_u32_e64 s[52:53], v80, v123
	s_and_saveexec_b64 s[0:1], s[54:55]
	s_cbranch_execz .LBB0_310
	s_lshl_b32 s57, s56, 2
	v_mbcnt_lo_u32_b32 v125, s54, 0
	s_add_i32 s57, s8, s57
	v_mbcnt_hi_u32_b32 v125, s55, v125
	v_add_u32_e32 v124, 0xc80, v0
	v_lshl_add_u32 v125, v125, 2, s57
	ds_write_b32 v125, v124 offset:16896
.LBB0_310:
	s_or_b64 exec, exec, s[0:1]
	s_bcnt1_i32_b64 s0, vcc
	v_mbcnt_lo_u32_b32 v124, s52, 0
	s_add_i32 s4, s4, s0
	v_mbcnt_hi_u32_b32 v124, s53, v124
	v_add_u32_e32 v124, s4, v124
	s_movk_i32 s0, 0x100
	v_cmp_gt_i32_e32 vcc, s0, v124
	s_and_b64 s[58:59], s[52:53], vcc
	s_and_saveexec_b64 s[0:1], s[58:59]
	v_lshl_add_u32 v124, v124, 2, s8
	v_add_u32_e32 v125, 0xc80, v0
	ds_write_b32 v124, v125 offset:16896
	s_or_b64 exec, exec, s[0:1]
	s_bcnt1_i32_b64 s0, s[54:55]
	s_add_i32 s56, s56, s0
	v_cmp_gt_u32_e64 s[54:55], v79, v123
	v_cmp_eq_u32_e32 vcc, v79, v123
	s_and_saveexec_b64 s[0:1], s[54:55]
	s_cbranch_execz .LBB0_314
	s_lshl_b32 s57, s56, 2
	v_mbcnt_lo_u32_b32 v125, s54, 0
	s_add_i32 s57, s8, s57
	v_mbcnt_hi_u32_b32 v125, s55, v125
	v_add_u32_e32 v124, 0xcc0, v0
	v_lshl_add_u32 v125, v125, 2, s57
	ds_write_b32 v125, v124 offset:16896
; __device__ __forceinline__ void topk_row(const Params& p, int r, int lane, __attribute__((address_space(3))) int* out) {
;     ...
;     int base_gt = 0, base_eq = cgt;
; #pragma unroll
;     for (int blk = 0; blk < 8; ++blk) {
;       if (blk * 16 < nch) {
; #pragma unroll
;         for (int ii = 0; ii < 16; ++ii) {
;           const int i = blk * 16 + ii;
;           const bool g = key[i] > Tv, e = key[i] == Tv;
;           const unsigned long long mg = __ballot(g), me = __ballot(e);
;           const int pg = base_gt + mbcnt64(mg);
;           if (g) out[pg] = i * 64 + lo;
;           base_gt += __popcll(mg);
;           const int pe = base_eq + mbcnt64(me);
;           if (e && pe < 256) out[pe] = i * 64 + lo;
;           base_eq += __popcll(me);
;         }
.LBB0_314:
	s_or_b64 exec, exec, s[0:1]
	s_bcnt1_i32_b64 s0, s[52:53]
	v_mbcnt_lo_u32_b32 v124, vcc_lo, 0
	s_add_i32 s4, s4, s0
	v_mbcnt_hi_u32_b32 v124, vcc_hi, v124
	v_add_u32_e32 v124, s4, v124
	s_movk_i32 s0, 0x100
	v_cmp_gt_i32_e64 s[0:1], s0, v124
	s_and_b64 s[52:53], vcc, s[0:1]
	s_and_saveexec_b64 s[0:1], s[52:53]
	v_lshl_add_u32 v124, v124, 2, s8
	v_add_u32_e32 v125, 0xcc0, v0
	ds_write_b32 v124, v125 offset:16896
	s_or_b64 exec, exec, s[0:1]
	s_bcnt1_i32_b64 s0, s[54:55]
	s_add_i32 s56, s56, s0
	v_cmp_gt_u32_e64 s[54:55], v78, v123
	v_cmp_eq_u32_e64 s[52:53], v78, v123
	s_and_saveexec_b64 s[0:1], s[54:55]
	s_cbranch_execz .LBB0_318
	s_lshl_b32 s57, s56, 2
	v_mbcnt_lo_u32_b32 v125, s54, 0
	s_add_i32 s57, s8, s57
	v_mbcnt_hi_u32_b32 v125, s55, v125
	v_add_u32_e32 v124, 0xd00, v0
	v_lshl_add_u32 v125, v125, 2, s57
	ds_write_b32 v125, v124 offset:16896
.LBB0_318:
	s_or_b64 exec, exec, s[0:1]
	s_bcnt1_i32_b64 s0, vcc
	v_mbcnt_lo_u32_b32 v124, s52, 0
	s_add_i32 s4, s4, s0
	v_mbcnt_hi_u32_b32 v124, s53, v124
	v_add_u32_e32 v124, s4, v124
	s_movk_i32 s0, 0x100
	v_cmp_gt_i32_e32 vcc, s0, v124
	s_and_b64 s[58:59], s[52:53], vcc
	s_and_saveexec_b64 s[0:1], s[58:59]
	v_lshl_add_u32 v124, v124, 2, s8
	v_add_u32_e32 v125, 0xd00, v0
	ds_write_b32 v124, v125 offset:16896
	s_or_b64 exec, exec, s[0:1]
	s_bcnt1_i32_b64 s0, s[54:55]
	s_add_i32 s56, s56, s0
	v_cmp_gt_u32_e64 s[54:55], v77, v123
	v_cmp_eq_u32_e32 vcc, v77, v123
	s_and_saveexec_b64 s[0:1], s[54:55]
	s_cbranch_execz .LBB0_322
	s_lshl_b32 s57, s56, 2
	v_mbcnt_lo_u32_b32 v125, s54, 0
	s_add_i32 s57, s8, s57
	v_mbcnt_hi_u32_b32 v125, s55, v125
	v_add_u32_e32 v124, 0xd40, v0
	v_lshl_add_u32 v125, v125, 2, s57
	ds_write_b32 v125, v124 offset:16896
.LBB0_322:
	s_or_b64 exec, exec, s[0:1]
	s_bcnt1_i32_b64 s0, s[52:53]
	v_mbcnt_lo_u32_b32 v124, vcc_lo, 0
	s_add_i32 s4, s4, s0
	v_mbcnt_hi_u32_b32 v124, vcc_hi, v124
	v_add_u32_e32 v124, s4, v124
	s_movk_i32 s0, 0x100
	v_cmp_gt_i32_e64 s[0:1], s0, v124
	s_and_b64 s[52:53], vcc, s[0:1]
	s_and_saveexec_b64 s[0:1], s[52:53]
	v_lshl_add_u32 v124, v124, 2, s8
	v_add_u32_e32 v125, 0xd40, v0
	ds_write_b32 v124, v125 offset:16896
	s_or_b64 exec, exec, s[0:1]
	s_bcnt1_i32_b64 s0, s[54:55]
	s_add_i32 s56, s56, s0
	v_cmp_gt_u32_e64 s[54:55], v76, v123
	v_cmp_eq_u32_e64 s[52:53], v76, v123
	s_and_saveexec_b64 s[0:1], s[54:55]
	s_cbranch_execz .LBB0_326
	s_lshl_b32 s57, s56, 2
	v_mbcnt_lo_u32_b32 v125, s54, 0
	s_add_i32 s57, s8, s57
	v_mbcnt_hi_u32_b32 v125, s55, v125
	v_add_u32_e32 v124, 0xd80, v0
	v_lshl_add_u32 v125, v125, 2, s57
	ds_write_b32 v125, v124 offset:16896
.LBB0_326:
	s_or_b64 exec, exec, s[0:1]
	s_bcnt1_i32_b64 s0, vcc
	v_mbcnt_lo_u32_b32 v124, s52, 0
	s_add_i32 s4, s4, s0
	v_mbcnt_hi_u32_b32 v124, s53, v124
	v_add_u32_e32 v124, s4, v124
	s_movk_i32 s0, 0x100
	v_cmp_gt_i32_e32 vcc, s0, v124
	s_and_b64 s[58:59], s[52:53], vcc
	s_and_saveexec_b64 s[0:1], s[58:59]
	v_lshl_add_u32 v124, v124, 2, s8
	v_add_u32_e32 v125, 0xd80, v0
	ds_write_b32 v124, v125 offset:16896
	s_or_b64 exec, exec, s[0:1]
	s_bcnt1_i32_b64 s0, s[54:55]
	s_add_i32 s56, s56, s0
	v_cmp_gt_u32_e64 s[54:55], v75, v123
	v_cmp_eq_u32_e32 vcc, v75, v123
	s_and_saveexec_b64 s[0:1], s[54:55]
	s_cbranch_execz .LBB0_330
	s_lshl_b32 s57, s56, 2
	v_mbcnt_lo_u32_b32 v125, s54, 0
	s_add_i32 s57, s8, s57
	v_mbcnt_hi_u32_b32 v125, s55, v125
	v_add_u32_e32 v124, 0xdc0, v0
	v_lshl_add_u32 v125, v125, 2, s57
	ds_write_b32 v125, v124 offset:16896
.LBB0_330:
	s_or_b64 exec, exec, s[0:1]
	s_bcnt1_i32_b64 s0, s[52:53]
	v_mbcnt_lo_u32_b32 v124, vcc_lo, 0
	s_add_i32 s4, s4, s0
	v_mbcnt_hi_u32_b32 v124, vcc_hi, v124
	v_add_u32_e32 v124, s4, v124
	s_movk_i32 s0, 0x100
	v_cmp_gt_i32_e64 s[0:1], s0, v124
	s_and_b64 s[52:53], vcc, s[0:1]
	s_and_saveexec_b64 s[0:1], s[52:53]
	v_lshl_add_u32 v124, v124, 2, s8
	v_add_u32_e32 v125, 0xdc0, v0
	ds_write_b32 v124, v125 offset:16896
	s_or_b64 exec, exec, s[0:1]
	s_bcnt1_i32_b64 s0, s[54:55]
	s_add_i32 s56, s56, s0
	v_cmp_gt_u32_e64 s[54:55], v74, v123
	v_cmp_eq_u32_e64 s[52:53], v74, v123
	s_and_saveexec_b64 s[0:1], s[54:55]
	s_cbranch_execz .LBB0_334
	s_lshl_b32 s57, s56, 2
	v_mbcnt_lo_u32_b32 v125, s54, 0
	s_add_i32 s57, s8, s57
	v_mbcnt_hi_u32_b32 v125, s55, v125
	v_add_u32_e32 v124, 0xe00, v0
	v_lshl_add_u32 v125, v125, 2, s57
	ds_write_b32 v125, v124 offset:16896
.LBB0_334:
	s_or_b64 exec, exec, s[0:1]
	s_bcnt1_i32_b64 s0, vcc
	v_mbcnt_lo_u32_b32 v124, s52, 0
	s_add_i32 s4, s4, s0
	v_mbcnt_hi_u32_b32 v124, s53, v124
	v_add_u32_e32 v124, s4, v124
	s_movk_i32 s0, 0x100
	v_cmp_gt_i32_e32 vcc, s0, v124
	s_and_b64 s[58:59], s[52:53], vcc
	s_and_saveexec_b64 s[0:1], s[58:59]
	v_lshl_add_u32 v124, v124, 2, s8
	v_add_u32_e32 v125, 0xe00, v0
	ds_write_b32 v124, v125 offset:16896
	s_or_b64 exec, exec, s[0:1]
	s_bcnt1_i32_b64 s0, s[54:55]
	s_add_i32 s56, s56, s0
	v_cmp_gt_u32_e64 s[54:55], v73, v123
	v_cmp_eq_u32_e32 vcc, v73, v123
	s_and_saveexec_b64 s[0:1], s[54:55]
	s_cbranch_execz .LBB0_338
	s_lshl_b32 s57, s56, 2
	v_mbcnt_lo_u32_b32 v125, s54, 0
	s_add_i32 s57, s8, s57
	v_mbcnt_hi_u32_b32 v125, s55, v125
	v_add_u32_e32 v124, 0xe40, v0
	v_lshl_add_u32 v125, v125, 2, s57
	ds_write_b32 v125, v124 offset:16896
.LBB0_338:
	s_or_b64 exec, exec, s[0:1]
	s_bcnt1_i32_b64 s0, s[52:53]
	v_mbcnt_lo_u32_b32 v124, vcc_lo, 0
	s_add_i32 s4, s4, s0
	v_mbcnt_hi_u32_b32 v124, vcc_hi, v124
	v_add_u32_e32 v124, s4, v124
	s_movk_i32 s0, 0x100
	v_cmp_gt_i32_e64 s[0:1], s0, v124
	s_and_b64 s[52:53], vcc, s[0:1]
	s_and_saveexec_b64 s[0:1], s[52:53]
	v_lshl_add_u32 v124, v124, 2, s8
	v_add_u32_e32 v125, 0xe40, v0
	ds_write_b32 v124, v125 offset:16896
	s_or_b64 exec, exec, s[0:1]
	s_bcnt1_i32_b64 s0, s[54:55]
	s_add_i32 s56, s56, s0
	v_cmp_gt_u32_e64 s[54:55], v72, v123
	v_cmp_eq_u32_e64 s[52:53], v72, v123
	s_and_saveexec_b64 s[0:1], s[54:55]
	s_cbranch_execz .LBB0_342
	s_lshl_b32 s57, s56, 2
	v_mbcnt_lo_u32_b32 v125, s54, 0
	s_add_i32 s57, s8, s57
	v_mbcnt_hi_u32_b32 v125, s55, v125
	v_add_u32_e32 v124, 0xe80, v0
	v_lshl_add_u32 v125, v125, 2, s57
	ds_write_b32 v125, v124 offset:16896
; __device__ __forceinline__ void topk_row(const Params& p, int r, int lane, __attribute__((address_space(3))) int* out) {
;     ...
;     int base_gt = 0, base_eq = cgt;
; #pragma unroll
;     for (int blk = 0; blk < 8; ++blk) {
;       if (blk * 16 < nch) {
; #pragma unroll
;         for (int ii = 0; ii < 16; ++ii) {
;           const int i = blk * 16 + ii;
;           const bool g = key[i] > Tv, e = key[i] == Tv;
;           const unsigned long long mg = __ballot(g), me = __ballot(e);
;           const int pg = base_gt + mbcnt64(mg);
;           if (g) out[pg] = i * 64 + lo;
;           base_gt += __popcll(mg);
;           const int pe = base_eq + mbcnt64(me);
;           if (e && pe < 256) out[pe] = i * 64 + lo;
;           base_eq += __popcll(me);
;         }
.LBB0_342:
	s_or_b64 exec, exec, s[0:1]
	s_bcnt1_i32_b64 s0, vcc
	v_mbcnt_lo_u32_b32 v124, s52, 0
	s_add_i32 s4, s4, s0
	v_mbcnt_hi_u32_b32 v124, s53, v124
	v_add_u32_e32 v124, s4, v124
	s_movk_i32 s0, 0x100
	v_cmp_gt_i32_e32 vcc, s0, v124
	s_and_b64 s[58:59], s[52:53], vcc
	s_and_saveexec_b64 s[0:1], s[58:59]
	v_lshl_add_u32 v124, v124, 2, s8
	v_add_u32_e32 v125, 0xe80, v0
	ds_write_b32 v124, v125 offset:16896
	s_or_b64 exec, exec, s[0:1]
	s_bcnt1_i32_b64 s0, s[54:55]
	s_add_i32 s56, s56, s0
	v_cmp_gt_u32_e64 s[54:55], v71, v123
	v_cmp_eq_u32_e32 vcc, v71, v123
	s_and_saveexec_b64 s[0:1], s[54:55]
	s_cbranch_execz .LBB0_346
	s_lshl_b32 s57, s56, 2
	v_mbcnt_lo_u32_b32 v125, s54, 0
	s_add_i32 s57, s8, s57
	v_mbcnt_hi_u32_b32 v125, s55, v125
	v_add_u32_e32 v124, 0xec0, v0
	v_lshl_add_u32 v125, v125, 2, s57
	ds_write_b32 v125, v124 offset:16896
.LBB0_346:
	s_or_b64 exec, exec, s[0:1]
	s_bcnt1_i32_b64 s0, s[52:53]
	v_mbcnt_lo_u32_b32 v124, vcc_lo, 0
	s_add_i32 s4, s4, s0
	v_mbcnt_hi_u32_b32 v124, vcc_hi, v124
	v_add_u32_e32 v124, s4, v124
	s_movk_i32 s0, 0x100
	v_cmp_gt_i32_e64 s[0:1], s0, v124
	s_and_b64 s[52:53], vcc, s[0:1]
	s_and_saveexec_b64 s[0:1], s[52:53]
	v_lshl_add_u32 v124, v124, 2, s8
	v_add_u32_e32 v125, 0xec0, v0
	ds_write_b32 v124, v125 offset:16896
	s_or_b64 exec, exec, s[0:1]
	s_bcnt1_i32_b64 s0, s[54:55]
	s_add_i32 s56, s56, s0
	v_cmp_gt_u32_e64 s[54:55], v70, v123
	v_cmp_eq_u32_e64 s[52:53], v70, v123
	s_and_saveexec_b64 s[0:1], s[54:55]
	s_cbranch_execz .LBB0_350
	s_lshl_b32 s57, s56, 2
	v_mbcnt_lo_u32_b32 v125, s54, 0
	s_add_i32 s57, s8, s57
	v_mbcnt_hi_u32_b32 v125, s55, v125
	v_add_u32_e32 v124, 0xf00, v0
	v_lshl_add_u32 v125, v125, 2, s57
	ds_write_b32 v125, v124 offset:16896
.LBB0_350:
	s_or_b64 exec, exec, s[0:1]
	s_bcnt1_i32_b64 s0, vcc
	v_mbcnt_lo_u32_b32 v124, s52, 0
	s_add_i32 s4, s4, s0
	v_mbcnt_hi_u32_b32 v124, s53, v124
	v_add_u32_e32 v124, s4, v124
	s_movk_i32 s0, 0x100
	v_cmp_gt_i32_e32 vcc, s0, v124
	s_and_b64 s[58:59], s[52:53], vcc
	s_and_saveexec_b64 s[0:1], s[58:59]
	v_lshl_add_u32 v124, v124, 2, s8
	v_add_u32_e32 v125, 0xf00, v0
	ds_write_b32 v124, v125 offset:16896
	s_or_b64 exec, exec, s[0:1]
	s_bcnt1_i32_b64 s0, s[54:55]
	s_add_i32 s56, s56, s0
	v_cmp_gt_u32_e64 s[54:55], v69, v123
	v_cmp_eq_u32_e32 vcc, v69, v123
	s_and_saveexec_b64 s[0:1], s[54:55]
	s_cbranch_execz .LBB0_354
	s_lshl_b32 s57, s56, 2
	v_mbcnt_lo_u32_b32 v125, s54, 0
	s_add_i32 s57, s8, s57
	v_mbcnt_hi_u32_b32 v125, s55, v125
	v_add_u32_e32 v124, 0xf40, v0
	v_lshl_add_u32 v125, v125, 2, s57
	ds_write_b32 v125, v124 offset:16896
.LBB0_354:
	s_or_b64 exec, exec, s[0:1]
	s_bcnt1_i32_b64 s0, s[52:53]
	v_mbcnt_lo_u32_b32 v124, vcc_lo, 0
	s_add_i32 s4, s4, s0
	v_mbcnt_hi_u32_b32 v124, vcc_hi, v124
	v_add_u32_e32 v124, s4, v124
	s_movk_i32 s0, 0x100
	v_cmp_gt_i32_e64 s[0:1], s0, v124
	s_and_b64 s[52:53], vcc, s[0:1]
	s_and_saveexec_b64 s[0:1], s[52:53]
	v_lshl_add_u32 v124, v124, 2, s8
	v_add_u32_e32 v125, 0xf40, v0
	ds_write_b32 v124, v125 offset:16896
	s_or_b64 exec, exec, s[0:1]
	s_bcnt1_i32_b64 s0, s[54:55]
	s_add_i32 s56, s56, s0
	v_cmp_gt_u32_e64 s[54:55], v68, v123
	v_cmp_eq_u32_e64 s[52:53], v68, v123
	s_and_saveexec_b64 s[0:1], s[54:55]
	s_cbranch_execz .LBB0_358
	s_lshl_b32 s57, s56, 2
	v_mbcnt_lo_u32_b32 v125, s54, 0
	s_add_i32 s57, s8, s57
	v_mbcnt_hi_u32_b32 v125, s55, v125
	v_add_u32_e32 v124, 0xf80, v0
	v_lshl_add_u32 v125, v125, 2, s57
	ds_write_b32 v125, v124 offset:16896
.LBB0_358:
	s_or_b64 exec, exec, s[0:1]
	s_bcnt1_i32_b64 s0, vcc
	v_mbcnt_lo_u32_b32 v124, s52, 0
	s_add_i32 s4, s4, s0
	v_mbcnt_hi_u32_b32 v124, s53, v124
	v_add_u32_e32 v124, s4, v124
	s_movk_i32 s0, 0x100
	v_cmp_gt_i32_e32 vcc, s0, v124
	s_and_b64 s[58:59], s[52:53], vcc
	s_and_saveexec_b64 s[0:1], s[58:59]
	v_lshl_add_u32 v124, v124, 2, s8
	v_add_u32_e32 v125, 0xf80, v0
	ds_write_b32 v124, v125 offset:16896
	s_or_b64 exec, exec, s[0:1]
	s_bcnt1_i32_b64 s0, s[54:55]
	s_add_i32 s56, s56, s0
	v_cmp_gt_u32_e64 s[54:55], v67, v123
	v_cmp_eq_u32_e32 vcc, v67, v123
	s_and_saveexec_b64 s[0:1], s[54:55]
	s_cbranch_execz .LBB0_362
	s_lshl_b32 s57, s56, 2
	v_mbcnt_lo_u32_b32 v125, s54, 0
	s_add_i32 s57, s8, s57
	v_mbcnt_hi_u32_b32 v125, s55, v125
	v_add_u32_e32 v124, 0xfc0, v0
	v_lshl_add_u32 v125, v125, 2, s57
	ds_write_b32 v125, v124 offset:16896
.LBB0_362:
	s_or_b64 exec, exec, s[0:1]
	s_bcnt1_i32_b64 s0, s[52:53]
	v_mbcnt_lo_u32_b32 v124, vcc_lo, 0
	s_add_i32 s4, s4, s0
	v_mbcnt_hi_u32_b32 v124, vcc_hi, v124
	v_add_u32_e32 v124, s4, v124
	s_movk_i32 s0, 0x100
	v_cmp_gt_i32_e64 s[0:1], s0, v124
	s_and_b64 s[52:53], vcc, s[0:1]
	s_and_saveexec_b64 s[0:1], s[52:53]
	v_lshl_add_u32 v124, v124, 2, s8
	v_add_u32_e32 v125, 0xfc0, v0
	ds_write_b32 v124, v125 offset:16896
	s_or_b64 exec, exec, s[0:1]
	s_bcnt1_i32_b64 s0, s[54:55]
	s_add_i32 s54, s56, s0
	s_bcnt1_i32_b64 s0, vcc
	s_add_i32 s4, s4, s0
.LBB0_365:
	v_readlane_b32 s0, v244, 4
	v_readlane_b32 s1, v244, 5
	s_and_b64 vcc, exec, s[0:1]
	s_cbranch_vccnz .LBB0_431
	v_cmp_gt_u32_e32 vcc, v66, v123
	v_cmp_eq_u32_e64 s[52:53], v66, v123
	s_and_saveexec_b64 s[0:1], vcc
	s_cbranch_execz .LBB0_368
	s_lshl_b32 s55, s54, 2
	v_mbcnt_lo_u32_b32 v125, vcc_lo, 0
	s_add_i32 s55, s8, s55
	v_mbcnt_hi_u32_b32 v125, vcc_hi, v125
	v_add_u32_e32 v124, 0x1000, v0
	v_lshl_add_u32 v125, v125, 2, s55
	ds_write_b32 v125, v124 offset:16896
; __device__ __forceinline__ void topk_row(const Params& p, int r, int lane, __attribute__((address_space(3))) int* out) {
;     ...
;     int base_gt = 0, base_eq = cgt;
; #pragma unroll
;     for (int blk = 0; blk < 8; ++blk) {
;       if (blk * 16 < nch) {
; #pragma unroll
;         for (int ii = 0; ii < 16; ++ii) {
;           const int i = blk * 16 + ii;
;           const bool g = key[i] > Tv, e = key[i] == Tv;
;           const unsigned long long mg = __ballot(g), me = __ballot(e);
;           const int pg = base_gt + mbcnt64(mg);
;           if (g) out[pg] = i * 64 + lo;
;           base_gt += __popcll(mg);
;           const int pe = base_eq + mbcnt64(me);
;           if (e && pe < 256) out[pe] = i * 64 + lo;
;           base_eq += __popcll(me);
;         }
.LBB0_368:
	s_or_b64 exec, exec, s[0:1]
	v_mbcnt_lo_u32_b32 v124, s52, 0
	v_mbcnt_hi_u32_b32 v124, s53, v124
	v_add_u32_e32 v124, s4, v124
	s_movk_i32 s0, 0x100
	v_cmp_gt_i32_e64 s[0:1], s0, v124
	s_and_b64 s[56:57], s[52:53], s[0:1]
	s_and_saveexec_b64 s[0:1], s[56:57]
	v_lshl_add_u32 v124, v124, 2, s8
	v_add_u32_e32 v125, 0x1000, v0
	ds_write_b32 v124, v125 offset:16896
	s_or_b64 exec, exec, s[0:1]
	s_bcnt1_i32_b64 s0, vcc
	s_add_i32 s56, s54, s0
	v_cmp_gt_u32_e64 s[54:55], v65, v123
	v_cmp_eq_u32_e32 vcc, v65, v123
	s_and_saveexec_b64 s[0:1], s[54:55]
	s_cbranch_execz .LBB0_372
	s_lshl_b32 s57, s56, 2
	v_mbcnt_lo_u32_b32 v125, s54, 0
	s_add_i32 s57, s8, s57
	v_mbcnt_hi_u32_b32 v125, s55, v125
	v_add_u32_e32 v124, 0x1040, v0
	v_lshl_add_u32 v125, v125, 2, s57
	ds_write_b32 v125, v124 offset:16896
.LBB0_372:
	s_or_b64 exec, exec, s[0:1]
	s_bcnt1_i32_b64 s0, s[52:53]
	v_mbcnt_lo_u32_b32 v124, vcc_lo, 0
	s_add_i32 s4, s4, s0
	v_mbcnt_hi_u32_b32 v124, vcc_hi, v124
	v_add_u32_e32 v124, s4, v124
	s_movk_i32 s0, 0x100
	v_cmp_gt_i32_e64 s[0:1], s0, v124
	s_and_b64 s[52:53], vcc, s[0:1]
	s_and_saveexec_b64 s[0:1], s[52:53]
	v_lshl_add_u32 v124, v124, 2, s8
	v_add_u32_e32 v125, 0x1040, v0
	ds_write_b32 v124, v125 offset:16896
	s_or_b64 exec, exec, s[0:1]
	s_bcnt1_i32_b64 s0, s[54:55]
	s_add_i32 s56, s56, s0
	v_cmp_gt_u32_e64 s[54:55], v64, v123
	v_cmp_eq_u32_e64 s[52:53], v64, v123
	s_and_saveexec_b64 s[0:1], s[54:55]
	s_cbranch_execz .LBB0_376
	s_lshl_b32 s57, s56, 2
	v_mbcnt_lo_u32_b32 v125, s54, 0
	s_add_i32 s57, s8, s57
	v_mbcnt_hi_u32_b32 v125, s55, v125
	v_add_u32_e32 v124, 0x1080, v0
	v_lshl_add_u32 v125, v125, 2, s57
	ds_write_b32 v125, v124 offset:16896
.LBB0_376:
	s_or_b64 exec, exec, s[0:1]
	s_bcnt1_i32_b64 s0, vcc
	v_mbcnt_lo_u32_b32 v124, s52, 0
	s_add_i32 s4, s4, s0
	v_mbcnt_hi_u32_b32 v124, s53, v124
	v_add_u32_e32 v124, s4, v124
	s_movk_i32 s0, 0x100
	v_cmp_gt_i32_e32 vcc, s0, v124
	s_and_b64 s[58:59], s[52:53], vcc
	s_and_saveexec_b64 s[0:1], s[58:59]
	v_lshl_add_u32 v124, v124, 2, s8
	v_add_u32_e32 v125, 0x1080, v0
	ds_write_b32 v124, v125 offset:16896
	s_or_b64 exec, exec, s[0:1]
	s_bcnt1_i32_b64 s0, s[54:55]
	s_add_i32 s56, s56, s0
	v_cmp_gt_u32_e64 s[54:55], v63, v123
	v_cmp_eq_u32_e32 vcc, v63, v123
	s_and_saveexec_b64 s[0:1], s[54:55]
	s_cbranch_execz .LBB0_380
	s_lshl_b32 s57, s56, 2
	v_mbcnt_lo_u32_b32 v125, s54, 0
	s_add_i32 s57, s8, s57
	v_mbcnt_hi_u32_b32 v125, s55, v125
	v_add_u32_e32 v124, 0x10c0, v0
	v_lshl_add_u32 v125, v125, 2, s57
	ds_write_b32 v125, v124 offset:16896
.LBB0_380:
	s_or_b64 exec, exec, s[0:1]
	s_bcnt1_i32_b64 s0, s[52:53]
	v_mbcnt_lo_u32_b32 v124, vcc_lo, 0
	s_add_i32 s4, s4, s0
	v_mbcnt_hi_u32_b32 v124, vcc_hi, v124
	v_add_u32_e32 v124, s4, v124
	s_movk_i32 s0, 0x100
	v_cmp_gt_i32_e64 s[0:1], s0, v124
	s_and_b64 s[52:53], vcc, s[0:1]
	s_and_saveexec_b64 s[0:1], s[52:53]
	v_lshl_add_u32 v124, v124, 2, s8
	v_add_u32_e32 v125, 0x10c0, v0
	ds_write_b32 v124, v125 offset:16896
	s_or_b64 exec, exec, s[0:1]
	s_bcnt1_i32_b64 s0, s[54:55]
	s_add_i32 s56, s56, s0
	v_cmp_gt_u32_e64 s[54:55], v62, v123
	v_cmp_eq_u32_e64 s[52:53], v62, v123
	s_and_saveexec_b64 s[0:1], s[54:55]
	s_cbranch_execz .LBB0_384
	s_lshl_b32 s57, s56, 2
	v_mbcnt_lo_u32_b32 v125, s54, 0
	s_add_i32 s57, s8, s57
	v_mbcnt_hi_u32_b32 v125, s55, v125
	v_add_u32_e32 v124, 0x1100, v0
	v_lshl_add_u32 v125, v125, 2, s57
	ds_write_b32 v125, v124 offset:16896
.LBB0_384:
	s_or_b64 exec, exec, s[0:1]
	s_bcnt1_i32_b64 s0, vcc
	v_mbcnt_lo_u32_b32 v124, s52, 0
	s_add_i32 s4, s4, s0
	v_mbcnt_hi_u32_b32 v124, s53, v124
	v_add_u32_e32 v124, s4, v124
	s_movk_i32 s0, 0x100
	v_cmp_gt_i32_e32 vcc, s0, v124
	s_and_b64 s[58:59], s[52:53], vcc
	s_and_saveexec_b64 s[0:1], s[58:59]
	v_lshl_add_u32 v124, v124, 2, s8
	v_add_u32_e32 v125, 0x1100, v0
	ds_write_b32 v124, v125 offset:16896
	s_or_b64 exec, exec, s[0:1]
	s_bcnt1_i32_b64 s0, s[54:55]
	s_add_i32 s56, s56, s0
	v_cmp_gt_u32_e64 s[54:55], v61, v123
	v_cmp_eq_u32_e32 vcc, v61, v123
	s_and_saveexec_b64 s[0:1], s[54:55]
	s_cbranch_execz .LBB0_388
	s_lshl_b32 s57, s56, 2
	v_mbcnt_lo_u32_b32 v125, s54, 0
	s_add_i32 s57, s8, s57
	v_mbcnt_hi_u32_b32 v125, s55, v125
	v_add_u32_e32 v124, 0x1140, v0
	v_lshl_add_u32 v125, v125, 2, s57
	ds_write_b32 v125, v124 offset:16896
.LBB0_388:
	s_or_b64 exec, exec, s[0:1]
	s_bcnt1_i32_b64 s0, s[52:53]
	v_mbcnt_lo_u32_b32 v124, vcc_lo, 0
	s_add_i32 s4, s4, s0
	v_mbcnt_hi_u32_b32 v124, vcc_hi, v124
	v_add_u32_e32 v124, s4, v124
	s_movk_i32 s0, 0x100
	v_cmp_gt_i32_e64 s[0:1], s0, v124
	s_and_b64 s[52:53], vcc, s[0:1]
	s_and_saveexec_b64 s[0:1], s[52:53]
	v_lshl_add_u32 v124, v124, 2, s8
	v_add_u32_e32 v125, 0x1140, v0
	ds_write_b32 v124, v125 offset:16896
	s_or_b64 exec, exec, s[0:1]
	s_bcnt1_i32_b64 s0, s[54:55]
	s_add_i32 s56, s56, s0
	v_cmp_gt_u32_e64 s[54:55], v60, v123
	v_cmp_eq_u32_e64 s[52:53], v60, v123
	s_and_saveexec_b64 s[0:1], s[54:55]
	s_cbranch_execz .LBB0_392
	s_lshl_b32 s57, s56, 2
	v_mbcnt_lo_u32_b32 v125, s54, 0
	s_add_i32 s57, s8, s57
	v_mbcnt_hi_u32_b32 v125, s55, v125
	v_add_u32_e32 v124, 0x1180, v0
	v_lshl_add_u32 v125, v125, 2, s57
	ds_write_b32 v125, v124 offset:16896
.LBB0_392:
	s_or_b64 exec, exec, s[0:1]
	s_bcnt1_i32_b64 s0, vcc
	v_mbcnt_lo_u32_b32 v124, s52, 0
	s_add_i32 s4, s4, s0
	v_mbcnt_hi_u32_b32 v124, s53, v124
	v_add_u32_e32 v124, s4, v124
	s_movk_i32 s0, 0x100
	v_cmp_gt_i32_e32 vcc, s0, v124
	s_and_b64 s[58:59], s[52:53], vcc
	s_and_saveexec_b64 s[0:1], s[58:59]
	v_lshl_add_u32 v124, v124, 2, s8
	v_add_u32_e32 v125, 0x1180, v0
	ds_write_b32 v124, v125 offset:16896
	s_or_b64 exec, exec, s[0:1]
	s_bcnt1_i32_b64 s0, s[54:55]
	s_add_i32 s56, s56, s0
	v_cmp_gt_u32_e64 s[54:55], v59, v123
	v_cmp_eq_u32_e32 vcc, v59, v123
	s_and_saveexec_b64 s[0:1], s[54:55]
	s_cbranch_execz .LBB0_396
	s_lshl_b32 s57, s56, 2
	v_mbcnt_lo_u32_b32 v125, s54, 0
	s_add_i32 s57, s8, s57
	v_mbcnt_hi_u32_b32 v125, s55, v125
	v_add_u32_e32 v124, 0x11c0, v0
	v_lshl_add_u32 v125, v125, 2, s57
	ds_write_b32 v125, v124 offset:16896
; __device__ __forceinline__ void topk_row(const Params& p, int r, int lane, __attribute__((address_space(3))) int* out) {
;     ...
;     int base_gt = 0, base_eq = cgt;
; #pragma unroll
;     for (int blk = 0; blk < 8; ++blk) {
;       if (blk * 16 < nch) {
; #pragma unroll
;         for (int ii = 0; ii < 16; ++ii) {
;           const int i = blk * 16 + ii;
;           const bool g = key[i] > Tv, e = key[i] == Tv;
;           const unsigned long long mg = __ballot(g), me = __ballot(e);
;           const int pg = base_gt + mbcnt64(mg);
;           if (g) out[pg] = i * 64 + lo;
;           base_gt += __popcll(mg);
;           const int pe = base_eq + mbcnt64(me);
;           if (e && pe < 256) out[pe] = i * 64 + lo;
;           base_eq += __popcll(me);
;         }
;       }
;     }
.LBB0_396:
	s_or_b64 exec, exec, s[0:1]
	s_bcnt1_i32_b64 s0, s[52:53]
	v_mbcnt_lo_u32_b32 v124, vcc_lo, 0
	s_add_i32 s4, s4, s0
	v_mbcnt_hi_u32_b32 v124, vcc_hi, v124
	v_add_u32_e32 v124, s4, v124
	s_movk_i32 s0, 0x100
	v_cmp_gt_i32_e64 s[0:1], s0, v124
	s_and_b64 s[52:53], vcc, s[0:1]
	s_and_saveexec_b64 s[0:1], s[52:53]
	v_lshl_add_u32 v124, v124, 2, s8
	v_add_u32_e32 v125, 0x11c0, v0
	ds_write_b32 v124, v125 offset:16896
	s_or_b64 exec, exec, s[0:1]
	s_bcnt1_i32_b64 s0, s[54:55]
	s_add_i32 s56, s56, s0
	v_cmp_gt_u32_e64 s[54:55], v58, v123
	v_cmp_eq_u32_e64 s[52:53], v58, v123
	s_and_saveexec_b64 s[0:1], s[54:55]
	s_cbranch_execz .LBB0_400
	s_lshl_b32 s57, s56, 2
	v_mbcnt_lo_u32_b32 v125, s54, 0
	s_add_i32 s57, s8, s57
	v_mbcnt_hi_u32_b32 v125, s55, v125
	v_add_u32_e32 v124, 0x1200, v0
	v_lshl_add_u32 v125, v125, 2, s57
	ds_write_b32 v125, v124 offset:16896
.LBB0_400:
	s_or_b64 exec, exec, s[0:1]
	s_bcnt1_i32_b64 s0, vcc
	v_mbcnt_lo_u32_b32 v124, s52, 0
	s_add_i32 s4, s4, s0
	v_mbcnt_hi_u32_b32 v124, s53, v124
	v_add_u32_e32 v124, s4, v124
	s_movk_i32 s0, 0x100
	v_cmp_gt_i32_e32 vcc, s0, v124
	s_and_b64 s[58:59], s[52:53], vcc
	s_and_saveexec_b64 s[0:1], s[58:59]
	v_lshl_add_u32 v124, v124, 2, s8
	v_add_u32_e32 v125, 0x1200, v0
	ds_write_b32 v124, v125 offset:16896
	s_or_b64 exec, exec, s[0:1]
	s_bcnt1_i32_b64 s0, s[54:55]
	s_add_i32 s56, s56, s0
	v_cmp_gt_u32_e64 s[54:55], v57, v123
	v_cmp_eq_u32_e32 vcc, v57, v123
	s_and_saveexec_b64 s[0:1], s[54:55]
	s_cbranch_execz .LBB0_404
	s_lshl_b32 s57, s56, 2
	v_mbcnt_lo_u32_b32 v125, s54, 0
	s_add_i32 s57, s8, s57
	v_mbcnt_hi_u32_b32 v125, s55, v125
	v_add_u32_e32 v124, 0x1240, v0
	v_lshl_add_u32 v125, v125, 2, s57
	ds_write_b32 v125, v124 offset:16896
.LBB0_404:
	s_or_b64 exec, exec, s[0:1]
	s_bcnt1_i32_b64 s0, s[52:53]
	v_mbcnt_lo_u32_b32 v124, vcc_lo, 0
	s_add_i32 s4, s4, s0
	v_mbcnt_hi_u32_b32 v124, vcc_hi, v124
	v_add_u32_e32 v124, s4, v124
	s_movk_i32 s0, 0x100
	v_cmp_gt_i32_e64 s[0:1], s0, v124
	s_and_b64 s[52:53], vcc, s[0:1]
	s_and_saveexec_b64 s[0:1], s[52:53]
	v_lshl_add_u32 v124, v124, 2, s8
	v_add_u32_e32 v125, 0x1240, v0
	ds_write_b32 v124, v125 offset:16896
	s_or_b64 exec, exec, s[0:1]
	s_bcnt1_i32_b64 s0, s[54:55]
	s_add_i32 s56, s56, s0
	v_cmp_gt_u32_e64 s[54:55], v56, v123
	v_cmp_eq_u32_e64 s[52:53], v56, v123
	s_and_saveexec_b64 s[0:1], s[54:55]
	s_cbranch_execz .LBB0_408
	s_lshl_b32 s57, s56, 2
	v_mbcnt_lo_u32_b32 v125, s54, 0
	s_add_i32 s57, s8, s57
	v_mbcnt_hi_u32_b32 v125, s55, v125
	v_add_u32_e32 v124, 0x1280, v0
	v_lshl_add_u32 v125, v125, 2, s57
	ds_write_b32 v125, v124 offset:16896
.LBB0_408:
	s_or_b64 exec, exec, s[0:1]
	s_bcnt1_i32_b64 s0, vcc
	v_mbcnt_lo_u32_b32 v124, s52, 0
	s_add_i32 s4, s4, s0
	v_mbcnt_hi_u32_b32 v124, s53, v124
	v_add_u32_e32 v124, s4, v124
	s_movk_i32 s0, 0x100
	v_cmp_gt_i32_e32 vcc, s0, v124
	s_and_b64 s[58:59], s[52:53], vcc
	s_and_saveexec_b64 s[0:1], s[58:59]
	v_lshl_add_u32 v124, v124, 2, s8
	v_add_u32_e32 v125, 0x1280, v0
	ds_write_b32 v124, v125 offset:16896
	s_or_b64 exec, exec, s[0:1]
	s_bcnt1_i32_b64 s0, s[54:55]
	s_add_i32 s56, s56, s0
	v_cmp_gt_u32_e64 s[54:55], v55, v123
	v_cmp_eq_u32_e32 vcc, v55, v123
	s_and_saveexec_b64 s[0:1], s[54:55]
	s_cbranch_execz .LBB0_412
	s_lshl_b32 s57, s56, 2
	v_mbcnt_lo_u32_b32 v125, s54, 0
	s_add_i32 s57, s8, s57
	v_mbcnt_hi_u32_b32 v125, s55, v125
	v_add_u32_e32 v124, 0x12c0, v0
	v_lshl_add_u32 v125, v125, 2, s57
	ds_write_b32 v125, v124 offset:16896
.LBB0_412:
	s_or_b64 exec, exec, s[0:1]
	s_bcnt1_i32_b64 s0, s[52:53]
	v_mbcnt_lo_u32_b32 v124, vcc_lo, 0
	s_add_i32 s4, s4, s0
	v_mbcnt_hi_u32_b32 v124, vcc_hi, v124
	v_add_u32_e32 v124, s4, v124
	s_movk_i32 s0, 0x100
	v_cmp_gt_i32_e64 s[0:1], s0, v124
	s_and_b64 s[52:53], vcc, s[0:1]
	s_and_saveexec_b64 s[0:1], s[52:53]
	v_lshl_add_u32 v124, v124, 2, s8
	v_add_u32_e32 v125, 0x12c0, v0
	ds_write_b32 v124, v125 offset:16896
	s_or_b64 exec, exec, s[0:1]
	s_bcnt1_i32_b64 s0, s[54:55]
	s_add_i32 s56, s56, s0
	v_cmp_gt_u32_e64 s[54:55], v54, v123
	v_cmp_eq_u32_e64 s[52:53], v54, v123
	s_and_saveexec_b64 s[0:1], s[54:55]
	s_cbranch_execz .LBB0_416
	s_lshl_b32 s57, s56, 2
	v_mbcnt_lo_u32_b32 v125, s54, 0
	s_add_i32 s57, s8, s57
	v_mbcnt_hi_u32_b32 v125, s55, v125
	v_add_u32_e32 v124, 0x1300, v0
	v_lshl_add_u32 v125, v125, 2, s57
	ds_write_b32 v125, v124 offset:16896
.LBB0_416:
	s_or_b64 exec, exec, s[0:1]
	s_bcnt1_i32_b64 s0, vcc
	v_mbcnt_lo_u32_b32 v124, s52, 0
	s_add_i32 s4, s4, s0
	v_mbcnt_hi_u32_b32 v124, s53, v124
	v_add_u32_e32 v124, s4, v124
	s_movk_i32 s0, 0x100
	v_cmp_gt_i32_e32 vcc, s0, v124
	s_and_b64 s[58:59], s[52:53], vcc
	s_and_saveexec_b64 s[0:1], s[58:59]
	v_lshl_add_u32 v124, v124, 2, s8
	v_add_u32_e32 v125, 0x1300, v0
	ds_write_b32 v124, v125 offset:16896
	s_or_b64 exec, exec, s[0:1]
	s_bcnt1_i32_b64 s0, s[54:55]
	s_add_i32 s56, s56, s0
	v_cmp_gt_u32_e64 s[54:55], v53, v123
	v_cmp_eq_u32_e32 vcc, v53, v123
	s_and_saveexec_b64 s[0:1], s[54:55]
	s_cbranch_execz .LBB0_420
	s_lshl_b32 s57, s56, 2
	v_mbcnt_lo_u32_b32 v125, s54, 0
	s_add_i32 s57, s8, s57
	v_mbcnt_hi_u32_b32 v125, s55, v125
	v_add_u32_e32 v124, 0x1340, v0
	v_lshl_add_u32 v125, v125, 2, s57
	ds_write_b32 v125, v124 offset:16896
.LBB0_420:
	s_or_b64 exec, exec, s[0:1]
	s_bcnt1_i32_b64 s0, s[52:53]
	v_mbcnt_lo_u32_b32 v124, vcc_lo, 0
	s_add_i32 s4, s4, s0
	v_mbcnt_hi_u32_b32 v124, vcc_hi, v124
	v_add_u32_e32 v124, s4, v124
	s_movk_i32 s0, 0x100
	v_cmp_gt_i32_e64 s[0:1], s0, v124
	s_and_b64 s[52:53], vcc, s[0:1]
	s_and_saveexec_b64 s[0:1], s[52:53]
	v_lshl_add_u32 v124, v124, 2, s8
	v_add_u32_e32 v125, 0x1340, v0
	ds_write_b32 v124, v125 offset:16896
	s_or_b64 exec, exec, s[0:1]
	s_bcnt1_i32_b64 s0, s[54:55]
	s_add_i32 s56, s56, s0
	v_cmp_gt_u32_e64 s[54:55], v52, v123
	v_cmp_eq_u32_e64 s[52:53], v52, v123
	s_and_saveexec_b64 s[0:1], s[54:55]
	s_cbranch_execz .LBB0_424
	s_lshl_b32 s57, s56, 2
	v_mbcnt_lo_u32_b32 v125, s54, 0
	s_add_i32 s57, s8, s57
	v_mbcnt_hi_u32_b32 v125, s55, v125
	v_add_u32_e32 v124, 0x1380, v0
	v_lshl_add_u32 v125, v125, 2, s57
	ds_write_b32 v125, v124 offset:16896
; __device__ __forceinline__ void topk_row(const Params& p, int r, int lane, __attribute__((address_space(3))) int* out) {
;     ...
;     int base_gt = 0, base_eq = cgt;
; #pragma unroll
;     for (int blk = 0; blk < 8; ++blk) {
;       if (blk * 16 < nch) {
; #pragma unroll
;         for (int ii = 0; ii < 16; ++ii) {
;           const int i = blk * 16 + ii;
;           const bool g = key[i] > Tv, e = key[i] == Tv;
;           const unsigned long long mg = __ballot(g), me = __ballot(e);
;           const int pg = base_gt + mbcnt64(mg);
;           if (g) out[pg] = i * 64 + lo;
;           base_gt += __popcll(mg);
;           const int pe = base_eq + mbcnt64(me);
;           if (e && pe < 256) out[pe] = i * 64 + lo;
;           base_eq += __popcll(me);
;         }
;       }
;     }
.LBB0_424:
	s_or_b64 exec, exec, s[0:1]
	s_bcnt1_i32_b64 s0, vcc
	v_mbcnt_lo_u32_b32 v124, s52, 0
	s_add_i32 s4, s4, s0
	v_mbcnt_hi_u32_b32 v124, s53, v124
	v_add_u32_e32 v124, s4, v124
	s_movk_i32 s0, 0x100
	v_cmp_gt_i32_e32 vcc, s0, v124
	s_and_b64 s[58:59], s[52:53], vcc
	s_and_saveexec_b64 s[0:1], s[58:59]
	v_lshl_add_u32 v124, v124, 2, s8
	v_add_u32_e32 v125, 0x1380, v0
	ds_write_b32 v124, v125 offset:16896
	s_or_b64 exec, exec, s[0:1]
	s_bcnt1_i32_b64 s0, s[54:55]
	s_add_i32 s56, s56, s0
	v_cmp_gt_u32_e64 s[54:55], v51, v123
	v_cmp_eq_u32_e32 vcc, v51, v123
	s_and_saveexec_b64 s[0:1], s[54:55]
	s_cbranch_execz .LBB0_428
	s_lshl_b32 s57, s56, 2
	v_mbcnt_lo_u32_b32 v125, s54, 0
	s_add_i32 s57, s8, s57
	v_mbcnt_hi_u32_b32 v125, s55, v125
	v_add_u32_e32 v124, 0x13c0, v0
	v_lshl_add_u32 v125, v125, 2, s57
	ds_write_b32 v125, v124 offset:16896
.LBB0_428:
	s_or_b64 exec, exec, s[0:1]
	s_bcnt1_i32_b64 s0, s[52:53]
	v_mbcnt_lo_u32_b32 v124, vcc_lo, 0
	s_add_i32 s4, s4, s0
	v_mbcnt_hi_u32_b32 v124, vcc_hi, v124
	v_add_u32_e32 v124, s4, v124
	s_movk_i32 s0, 0x100
	v_cmp_gt_i32_e64 s[0:1], s0, v124
	s_and_b64 s[52:53], vcc, s[0:1]
	s_and_saveexec_b64 s[0:1], s[52:53]
	v_lshl_add_u32 v124, v124, 2, s8
	v_add_u32_e32 v125, 0x13c0, v0
	ds_write_b32 v124, v125 offset:16896
	s_or_b64 exec, exec, s[0:1]
	s_bcnt1_i32_b64 s0, s[54:55]
	s_add_i32 s54, s56, s0
	s_bcnt1_i32_b64 s0, vcc
	s_add_i32 s4, s4, s0
.LBB0_431:
	v_readlane_b32 s0, v244, 6
	v_readlane_b32 s1, v244, 7
	s_and_b64 vcc, exec, s[0:1]
	s_cbranch_vccnz .LBB0_497
	v_cmp_gt_u32_e32 vcc, v50, v123
	v_cmp_eq_u32_e64 s[52:53], v50, v123
	s_and_saveexec_b64 s[0:1], vcc
	s_cbranch_execz .LBB0_434
	s_lshl_b32 s55, s54, 2
	v_mbcnt_lo_u32_b32 v125, vcc_lo, 0
	s_add_i32 s55, s8, s55
	v_mbcnt_hi_u32_b32 v125, vcc_hi, v125
	v_add_u32_e32 v124, 0x1400, v0
	v_lshl_add_u32 v125, v125, 2, s55
	ds_write_b32 v125, v124 offset:16896
.LBB0_434:
	s_or_b64 exec, exec, s[0:1]
	v_mbcnt_lo_u32_b32 v124, s52, 0
	v_mbcnt_hi_u32_b32 v124, s53, v124
	v_add_u32_e32 v124, s4, v124
	s_movk_i32 s0, 0x100
	v_cmp_gt_i32_e64 s[0:1], s0, v124
	s_and_b64 s[56:57], s[52:53], s[0:1]
	s_and_saveexec_b64 s[0:1], s[56:57]
	v_lshl_add_u32 v124, v124, 2, s8
	v_add_u32_e32 v125, 0x1400, v0
	ds_write_b32 v124, v125 offset:16896
	s_or_b64 exec, exec, s[0:1]
	s_bcnt1_i32_b64 s0, vcc
	s_add_i32 s56, s54, s0
	v_cmp_gt_u32_e64 s[54:55], v49, v123
	v_cmp_eq_u32_e32 vcc, v49, v123
	s_and_saveexec_b64 s[0:1], s[54:55]
	s_cbranch_execz .LBB0_438
	s_lshl_b32 s57, s56, 2
	v_mbcnt_lo_u32_b32 v125, s54, 0
	s_add_i32 s57, s8, s57
	v_mbcnt_hi_u32_b32 v125, s55, v125
	v_add_u32_e32 v124, 0x1440, v0
	v_lshl_add_u32 v125, v125, 2, s57
	ds_write_b32 v125, v124 offset:16896
.LBB0_438:
	s_or_b64 exec, exec, s[0:1]
	s_bcnt1_i32_b64 s0, s[52:53]
	v_mbcnt_lo_u32_b32 v124, vcc_lo, 0
	s_add_i32 s4, s4, s0
	v_mbcnt_hi_u32_b32 v124, vcc_hi, v124
	v_add_u32_e32 v124, s4, v124
	s_movk_i32 s0, 0x100
	v_cmp_gt_i32_e64 s[0:1], s0, v124
	s_and_b64 s[52:53], vcc, s[0:1]
	s_and_saveexec_b64 s[0:1], s[52:53]
	v_lshl_add_u32 v124, v124, 2, s8
	v_add_u32_e32 v125, 0x1440, v0
	ds_write_b32 v124, v125 offset:16896
	s_or_b64 exec, exec, s[0:1]
	s_bcnt1_i32_b64 s0, s[54:55]
	s_add_i32 s56, s56, s0
	v_cmp_gt_u32_e64 s[54:55], v48, v123
	v_cmp_eq_u32_e64 s[52:53], v48, v123
	s_and_saveexec_b64 s[0:1], s[54:55]
	s_cbranch_execz .LBB0_442
	s_lshl_b32 s57, s56, 2
	v_mbcnt_lo_u32_b32 v125, s54, 0
	s_add_i32 s57, s8, s57
	v_mbcnt_hi_u32_b32 v125, s55, v125
	v_add_u32_e32 v124, 0x1480, v0
	v_lshl_add_u32 v125, v125, 2, s57
	ds_write_b32 v125, v124 offset:16896
.LBB0_442:
	s_or_b64 exec, exec, s[0:1]
	s_bcnt1_i32_b64 s0, vcc
	v_mbcnt_lo_u32_b32 v124, s52, 0
	s_add_i32 s4, s4, s0
	v_mbcnt_hi_u32_b32 v124, s53, v124
	v_add_u32_e32 v124, s4, v124
	s_movk_i32 s0, 0x100
	v_cmp_gt_i32_e32 vcc, s0, v124
	s_and_b64 s[58:59], s[52:53], vcc
	s_and_saveexec_b64 s[0:1], s[58:59]
	v_lshl_add_u32 v124, v124, 2, s8
	v_add_u32_e32 v125, 0x1480, v0
	ds_write_b32 v124, v125 offset:16896
	s_or_b64 exec, exec, s[0:1]
	s_bcnt1_i32_b64 s0, s[54:55]
	s_add_i32 s56, s56, s0
	v_cmp_gt_u32_e64 s[54:55], v47, v123
	v_cmp_eq_u32_e32 vcc, v47, v123
	s_and_saveexec_b64 s[0:1], s[54:55]
	s_cbranch_execz .LBB0_446
	s_lshl_b32 s57, s56, 2
	v_mbcnt_lo_u32_b32 v125, s54, 0
	s_add_i32 s57, s8, s57
	v_mbcnt_hi_u32_b32 v125, s55, v125
	v_add_u32_e32 v124, 0x14c0, v0
	v_lshl_add_u32 v125, v125, 2, s57
	ds_write_b32 v125, v124 offset:16896
.LBB0_446:
	s_or_b64 exec, exec, s[0:1]
	s_bcnt1_i32_b64 s0, s[52:53]
	v_mbcnt_lo_u32_b32 v124, vcc_lo, 0
	s_add_i32 s4, s4, s0
	v_mbcnt_hi_u32_b32 v124, vcc_hi, v124
	v_add_u32_e32 v124, s4, v124
	s_movk_i32 s0, 0x100
	v_cmp_gt_i32_e64 s[0:1], s0, v124
	s_and_b64 s[52:53], vcc, s[0:1]
	s_and_saveexec_b64 s[0:1], s[52:53]
	v_lshl_add_u32 v124, v124, 2, s8
	v_add_u32_e32 v125, 0x14c0, v0
	ds_write_b32 v124, v125 offset:16896
	s_or_b64 exec, exec, s[0:1]
	s_bcnt1_i32_b64 s0, s[54:55]
	s_add_i32 s56, s56, s0
	v_cmp_gt_u32_e64 s[54:55], v46, v123
	v_cmp_eq_u32_e64 s[52:53], v46, v123
	s_and_saveexec_b64 s[0:1], s[54:55]
	s_cbranch_execz .LBB0_450
	s_lshl_b32 s57, s56, 2
	v_mbcnt_lo_u32_b32 v125, s54, 0
	s_add_i32 s57, s8, s57
	v_mbcnt_hi_u32_b32 v125, s55, v125
	v_add_u32_e32 v124, 0x1500, v0
	v_lshl_add_u32 v125, v125, 2, s57
	ds_write_b32 v125, v124 offset:16896
; __device__ __forceinline__ void topk_row(const Params& p, int r, int lane, __attribute__((address_space(3))) int* out) {
;     ...
;     int base_gt = 0, base_eq = cgt;
; #pragma unroll
;     for (int blk = 0; blk < 8; ++blk) {
;       if (blk * 16 < nch) {
; #pragma unroll
;         for (int ii = 0; ii < 16; ++ii) {
;           const int i = blk * 16 + ii;
;           const bool g = key[i] > Tv, e = key[i] == Tv;
;           const unsigned long long mg = __ballot(g), me = __ballot(e);
;           const int pg = base_gt + mbcnt64(mg);
;           if (g) out[pg] = i * 64 + lo;
;           base_gt += __popcll(mg);
;           const int pe = base_eq + mbcnt64(me);
;           if (e && pe < 256) out[pe] = i * 64 + lo;
;           base_eq += __popcll(me);
;         }
;       }
;     }
.LBB0_450:
	s_or_b64 exec, exec, s[0:1]
	s_bcnt1_i32_b64 s0, vcc
	v_mbcnt_lo_u32_b32 v124, s52, 0
	s_add_i32 s4, s4, s0
	v_mbcnt_hi_u32_b32 v124, s53, v124
	v_add_u32_e32 v124, s4, v124
	s_movk_i32 s0, 0x100
	v_cmp_gt_i32_e32 vcc, s0, v124
	s_and_b64 s[58:59], s[52:53], vcc
	s_and_saveexec_b64 s[0:1], s[58:59]
	v_lshl_add_u32 v124, v124, 2, s8
	v_add_u32_e32 v125, 0x1500, v0
	ds_write_b32 v124, v125 offset:16896
	s_or_b64 exec, exec, s[0:1]
	s_bcnt1_i32_b64 s0, s[54:55]
	s_add_i32 s56, s56, s0
	v_cmp_gt_u32_e64 s[54:55], v45, v123
	v_cmp_eq_u32_e32 vcc, v45, v123
	s_and_saveexec_b64 s[0:1], s[54:55]
	s_cbranch_execz .LBB0_454
	s_lshl_b32 s57, s56, 2
	v_mbcnt_lo_u32_b32 v125, s54, 0
	s_add_i32 s57, s8, s57
	v_mbcnt_hi_u32_b32 v125, s55, v125
	v_add_u32_e32 v124, 0x1540, v0
	v_lshl_add_u32 v125, v125, 2, s57
	ds_write_b32 v125, v124 offset:16896
.LBB0_454:
	s_or_b64 exec, exec, s[0:1]
	s_bcnt1_i32_b64 s0, s[52:53]
	v_mbcnt_lo_u32_b32 v124, vcc_lo, 0
	s_add_i32 s4, s4, s0
	v_mbcnt_hi_u32_b32 v124, vcc_hi, v124
	v_add_u32_e32 v124, s4, v124
	s_movk_i32 s0, 0x100
	v_cmp_gt_i32_e64 s[0:1], s0, v124
	s_and_b64 s[52:53], vcc, s[0:1]
	s_and_saveexec_b64 s[0:1], s[52:53]
	v_lshl_add_u32 v124, v124, 2, s8
	v_add_u32_e32 v125, 0x1540, v0
	ds_write_b32 v124, v125 offset:16896
	s_or_b64 exec, exec, s[0:1]
	s_bcnt1_i32_b64 s0, s[54:55]
	s_add_i32 s56, s56, s0
	v_cmp_gt_u32_e64 s[54:55], v44, v123
	v_cmp_eq_u32_e64 s[52:53], v44, v123
	s_and_saveexec_b64 s[0:1], s[54:55]
	s_cbranch_execz .LBB0_458
	s_lshl_b32 s57, s56, 2
	v_mbcnt_lo_u32_b32 v125, s54, 0
	s_add_i32 s57, s8, s57
	v_mbcnt_hi_u32_b32 v125, s55, v125
	v_add_u32_e32 v124, 0x1580, v0
	v_lshl_add_u32 v125, v125, 2, s57
	ds_write_b32 v125, v124 offset:16896
.LBB0_458:
	s_or_b64 exec, exec, s[0:1]
	s_bcnt1_i32_b64 s0, vcc
	v_mbcnt_lo_u32_b32 v124, s52, 0
	s_add_i32 s4, s4, s0
	v_mbcnt_hi_u32_b32 v124, s53, v124
	v_add_u32_e32 v124, s4, v124
	s_movk_i32 s0, 0x100
	v_cmp_gt_i32_e32 vcc, s0, v124
	s_and_b64 s[58:59], s[52:53], vcc
	s_and_saveexec_b64 s[0:1], s[58:59]
	v_lshl_add_u32 v124, v124, 2, s8
	v_add_u32_e32 v125, 0x1580, v0
	ds_write_b32 v124, v125 offset:16896
	s_or_b64 exec, exec, s[0:1]
	s_bcnt1_i32_b64 s0, s[54:55]
	s_add_i32 s56, s56, s0
	v_cmp_gt_u32_e64 s[54:55], v43, v123
	v_cmp_eq_u32_e32 vcc, v43, v123
	s_and_saveexec_b64 s[0:1], s[54:55]
	s_cbranch_execz .LBB0_462
	s_lshl_b32 s57, s56, 2
	v_mbcnt_lo_u32_b32 v125, s54, 0
	s_add_i32 s57, s8, s57
	v_mbcnt_hi_u32_b32 v125, s55, v125
	v_add_u32_e32 v124, 0x15c0, v0
	v_lshl_add_u32 v125, v125, 2, s57
	ds_write_b32 v125, v124 offset:16896
.LBB0_462:
	s_or_b64 exec, exec, s[0:1]
	s_bcnt1_i32_b64 s0, s[52:53]
	v_mbcnt_lo_u32_b32 v124, vcc_lo, 0
	s_add_i32 s4, s4, s0
	v_mbcnt_hi_u32_b32 v124, vcc_hi, v124
	v_add_u32_e32 v124, s4, v124
	s_movk_i32 s0, 0x100
	v_cmp_gt_i32_e64 s[0:1], s0, v124
	s_and_b64 s[52:53], vcc, s[0:1]
	s_and_saveexec_b64 s[0:1], s[52:53]
	v_lshl_add_u32 v124, v124, 2, s8
	v_add_u32_e32 v125, 0x15c0, v0
	ds_write_b32 v124, v125 offset:16896
	s_or_b64 exec, exec, s[0:1]
	s_bcnt1_i32_b64 s0, s[54:55]
	s_add_i32 s56, s56, s0
	v_cmp_gt_u32_e64 s[54:55], v42, v123
	v_cmp_eq_u32_e64 s[52:53], v42, v123
	s_and_saveexec_b64 s[0:1], s[54:55]
	s_cbranch_execz .LBB0_466
	s_lshl_b32 s57, s56, 2
	v_mbcnt_lo_u32_b32 v125, s54, 0
	s_add_i32 s57, s8, s57
	v_mbcnt_hi_u32_b32 v125, s55, v125
	v_add_u32_e32 v124, 0x1600, v0
	v_lshl_add_u32 v125, v125, 2, s57
	ds_write_b32 v125, v124 offset:16896
.LBB0_466:
	s_or_b64 exec, exec, s[0:1]
	s_bcnt1_i32_b64 s0, vcc
	v_mbcnt_lo_u32_b32 v124, s52, 0
	s_add_i32 s4, s4, s0
	v_mbcnt_hi_u32_b32 v124, s53, v124
	v_add_u32_e32 v124, s4, v124
	s_movk_i32 s0, 0x100
	v_cmp_gt_i32_e32 vcc, s0, v124
	s_and_b64 s[58:59], s[52:53], vcc
	s_and_saveexec_b64 s[0:1], s[58:59]
	v_lshl_add_u32 v124, v124, 2, s8
	v_add_u32_e32 v125, 0x1600, v0
	ds_write_b32 v124, v125 offset:16896
	s_or_b64 exec, exec, s[0:1]
	s_bcnt1_i32_b64 s0, s[54:55]
	s_add_i32 s56, s56, s0
	v_cmp_gt_u32_e64 s[54:55], v41, v123
	v_cmp_eq_u32_e32 vcc, v41, v123
	s_and_saveexec_b64 s[0:1], s[54:55]
	s_cbranch_execz .LBB0_470
	s_lshl_b32 s57, s56, 2
	v_mbcnt_lo_u32_b32 v125, s54, 0
	s_add_i32 s57, s8, s57
	v_mbcnt_hi_u32_b32 v125, s55, v125
	v_add_u32_e32 v124, 0x1640, v0
	v_lshl_add_u32 v125, v125, 2, s57
	ds_write_b32 v125, v124 offset:16896
.LBB0_470:
	s_or_b64 exec, exec, s[0:1]
	s_bcnt1_i32_b64 s0, s[52:53]
	v_mbcnt_lo_u32_b32 v124, vcc_lo, 0
	s_add_i32 s4, s4, s0
	v_mbcnt_hi_u32_b32 v124, vcc_hi, v124
	v_add_u32_e32 v124, s4, v124
	s_movk_i32 s0, 0x100
	v_cmp_gt_i32_e64 s[0:1], s0, v124
	s_and_b64 s[52:53], vcc, s[0:1]
	s_and_saveexec_b64 s[0:1], s[52:53]
	v_lshl_add_u32 v124, v124, 2, s8
	v_add_u32_e32 v125, 0x1640, v0
	ds_write_b32 v124, v125 offset:16896
	s_or_b64 exec, exec, s[0:1]
	s_bcnt1_i32_b64 s0, s[54:55]
	s_add_i32 s56, s56, s0
	v_cmp_gt_u32_e64 s[54:55], v40, v123
	v_cmp_eq_u32_e64 s[52:53], v40, v123
	s_and_saveexec_b64 s[0:1], s[54:55]
	s_cbranch_execz .LBB0_474
	s_lshl_b32 s57, s56, 2
	v_mbcnt_lo_u32_b32 v125, s54, 0
	s_add_i32 s57, s8, s57
	v_mbcnt_hi_u32_b32 v125, s55, v125
	v_add_u32_e32 v124, 0x1680, v0
	v_lshl_add_u32 v125, v125, 2, s57
	ds_write_b32 v125, v124 offset:16896
.LBB0_474:
	s_or_b64 exec, exec, s[0:1]
	s_bcnt1_i32_b64 s0, vcc
	v_mbcnt_lo_u32_b32 v124, s52, 0
	s_add_i32 s4, s4, s0
	v_mbcnt_hi_u32_b32 v124, s53, v124
	v_add_u32_e32 v124, s4, v124
	s_movk_i32 s0, 0x100
	v_cmp_gt_i32_e32 vcc, s0, v124
	s_and_b64 s[58:59], s[52:53], vcc
	s_and_saveexec_b64 s[0:1], s[58:59]
	v_lshl_add_u32 v124, v124, 2, s8
	v_add_u32_e32 v125, 0x1680, v0
	ds_write_b32 v124, v125 offset:16896
	s_or_b64 exec, exec, s[0:1]
	s_bcnt1_i32_b64 s0, s[54:55]
	s_add_i32 s56, s56, s0
	v_cmp_gt_u32_e64 s[54:55], v39, v123
	v_cmp_eq_u32_e32 vcc, v39, v123
	s_and_saveexec_b64 s[0:1], s[54:55]
	s_cbranch_execz .LBB0_478
	s_lshl_b32 s57, s56, 2
	v_mbcnt_lo_u32_b32 v125, s54, 0
	s_add_i32 s57, s8, s57
	v_mbcnt_hi_u32_b32 v125, s55, v125
	v_add_u32_e32 v124, 0x16c0, v0
	v_lshl_add_u32 v125, v125, 2, s57
	ds_write_b32 v125, v124 offset:16896
; __device__ __forceinline__ void topk_row(const Params& p, int r, int lane, __attribute__((address_space(3))) int* out) {
;     ...
;     int base_gt = 0, base_eq = cgt;
; #pragma unroll
;     for (int blk = 0; blk < 8; ++blk) {
;       if (blk * 16 < nch) {
; #pragma unroll
;         for (int ii = 0; ii < 16; ++ii) {
;           const int i = blk * 16 + ii;
;           const bool g = key[i] > Tv, e = key[i] == Tv;
;           const unsigned long long mg = __ballot(g), me = __ballot(e);
;           const int pg = base_gt + mbcnt64(mg);
;           if (g) out[pg] = i * 64 + lo;
;           base_gt += __popcll(mg);
;           const int pe = base_eq + mbcnt64(me);
;           if (e && pe < 256) out[pe] = i * 64 + lo;
;           base_eq += __popcll(me);
;         }
;       }
;     }
.LBB0_478:
	s_or_b64 exec, exec, s[0:1]
	s_bcnt1_i32_b64 s0, s[52:53]
	v_mbcnt_lo_u32_b32 v124, vcc_lo, 0
	s_add_i32 s4, s4, s0
	v_mbcnt_hi_u32_b32 v124, vcc_hi, v124
	v_add_u32_e32 v124, s4, v124
	s_movk_i32 s0, 0x100
	v_cmp_gt_i32_e64 s[0:1], s0, v124
	s_and_b64 s[52:53], vcc, s[0:1]
	s_and_saveexec_b64 s[0:1], s[52:53]
	v_lshl_add_u32 v124, v124, 2, s8
	v_add_u32_e32 v125, 0x16c0, v0
	ds_write_b32 v124, v125 offset:16896
	s_or_b64 exec, exec, s[0:1]
	s_bcnt1_i32_b64 s0, s[54:55]
	s_add_i32 s56, s56, s0
	v_cmp_gt_u32_e64 s[54:55], v38, v123
	v_cmp_eq_u32_e64 s[52:53], v38, v123
	s_and_saveexec_b64 s[0:1], s[54:55]
	s_cbranch_execz .LBB0_482
	s_lshl_b32 s57, s56, 2
	v_mbcnt_lo_u32_b32 v125, s54, 0
	s_add_i32 s57, s8, s57
	v_mbcnt_hi_u32_b32 v125, s55, v125
	v_add_u32_e32 v124, 0x1700, v0
	v_lshl_add_u32 v125, v125, 2, s57
	ds_write_b32 v125, v124 offset:16896
.LBB0_482:
	s_or_b64 exec, exec, s[0:1]
	s_bcnt1_i32_b64 s0, vcc
	v_mbcnt_lo_u32_b32 v124, s52, 0
	s_add_i32 s4, s4, s0
	v_mbcnt_hi_u32_b32 v124, s53, v124
	v_add_u32_e32 v124, s4, v124
	s_movk_i32 s0, 0x100
	v_cmp_gt_i32_e32 vcc, s0, v124
	s_and_b64 s[58:59], s[52:53], vcc
	s_and_saveexec_b64 s[0:1], s[58:59]
	v_lshl_add_u32 v124, v124, 2, s8
	v_add_u32_e32 v125, 0x1700, v0
	ds_write_b32 v124, v125 offset:16896
	s_or_b64 exec, exec, s[0:1]
	s_bcnt1_i32_b64 s0, s[54:55]
	s_add_i32 s56, s56, s0
	v_cmp_gt_u32_e64 s[54:55], v37, v123
	v_cmp_eq_u32_e32 vcc, v37, v123
	s_and_saveexec_b64 s[0:1], s[54:55]
	s_cbranch_execz .LBB0_486
	s_lshl_b32 s57, s56, 2
	v_mbcnt_lo_u32_b32 v125, s54, 0
	s_add_i32 s57, s8, s57
	v_mbcnt_hi_u32_b32 v125, s55, v125
	v_add_u32_e32 v124, 0x1740, v0
	v_lshl_add_u32 v125, v125, 2, s57
	ds_write_b32 v125, v124 offset:16896
.LBB0_486:
	s_or_b64 exec, exec, s[0:1]
	s_bcnt1_i32_b64 s0, s[52:53]
	v_mbcnt_lo_u32_b32 v124, vcc_lo, 0
	s_add_i32 s4, s4, s0
	v_mbcnt_hi_u32_b32 v124, vcc_hi, v124
	v_add_u32_e32 v124, s4, v124
	s_movk_i32 s0, 0x100
	v_cmp_gt_i32_e64 s[0:1], s0, v124
	s_and_b64 s[52:53], vcc, s[0:1]
	s_and_saveexec_b64 s[0:1], s[52:53]
	v_lshl_add_u32 v124, v124, 2, s8
	v_add_u32_e32 v125, 0x1740, v0
	ds_write_b32 v124, v125 offset:16896
	s_or_b64 exec, exec, s[0:1]
	s_bcnt1_i32_b64 s0, s[54:55]
	s_add_i32 s56, s56, s0
	v_cmp_gt_u32_e64 s[54:55], v36, v123
	v_cmp_eq_u32_e64 s[52:53], v36, v123
	s_and_saveexec_b64 s[0:1], s[54:55]
	s_cbranch_execz .LBB0_490
	s_lshl_b32 s57, s56, 2
	v_mbcnt_lo_u32_b32 v125, s54, 0
	s_add_i32 s57, s8, s57
	v_mbcnt_hi_u32_b32 v125, s55, v125
	v_add_u32_e32 v124, 0x1780, v0
	v_lshl_add_u32 v125, v125, 2, s57
	ds_write_b32 v125, v124 offset:16896
.LBB0_490:
	s_or_b64 exec, exec, s[0:1]
	s_bcnt1_i32_b64 s0, vcc
	v_mbcnt_lo_u32_b32 v124, s52, 0
	s_add_i32 s4, s4, s0
	v_mbcnt_hi_u32_b32 v124, s53, v124
	v_add_u32_e32 v124, s4, v124
	s_movk_i32 s0, 0x100
	v_cmp_gt_i32_e32 vcc, s0, v124
	s_and_b64 s[58:59], s[52:53], vcc
	s_and_saveexec_b64 s[0:1], s[58:59]
	v_lshl_add_u32 v124, v124, 2, s8
	v_add_u32_e32 v125, 0x1780, v0
	ds_write_b32 v124, v125 offset:16896
	s_or_b64 exec, exec, s[0:1]
	s_bcnt1_i32_b64 s0, s[54:55]
	s_add_i32 s56, s56, s0
	v_cmp_gt_u32_e64 s[54:55], v35, v123
	v_cmp_eq_u32_e32 vcc, v35, v123
	s_and_saveexec_b64 s[0:1], s[54:55]
	s_cbranch_execz .LBB0_494
	s_lshl_b32 s57, s56, 2
	v_mbcnt_lo_u32_b32 v125, s54, 0
	s_add_i32 s57, s8, s57
	v_mbcnt_hi_u32_b32 v125, s55, v125
	v_add_u32_e32 v124, 0x17c0, v0
	v_lshl_add_u32 v125, v125, 2, s57
	ds_write_b32 v125, v124 offset:16896
.LBB0_494:
	s_or_b64 exec, exec, s[0:1]
	s_bcnt1_i32_b64 s0, s[52:53]
	v_mbcnt_lo_u32_b32 v124, vcc_lo, 0
	s_add_i32 s4, s4, s0
	v_mbcnt_hi_u32_b32 v124, vcc_hi, v124
	v_add_u32_e32 v124, s4, v124
	s_movk_i32 s0, 0x100
	v_cmp_gt_i32_e64 s[0:1], s0, v124
	s_and_b64 s[52:53], vcc, s[0:1]
	s_and_saveexec_b64 s[0:1], s[52:53]
	v_lshl_add_u32 v124, v124, 2, s8
	v_add_u32_e32 v125, 0x17c0, v0
	ds_write_b32 v124, v125 offset:16896
	s_or_b64 exec, exec, s[0:1]
	s_bcnt1_i32_b64 s0, s[54:55]
	s_add_i32 s54, s56, s0
	s_bcnt1_i32_b64 s0, vcc
	s_add_i32 s4, s4, s0
.LBB0_497:
	v_readlane_b32 s0, v244, 8
	v_readlane_b32 s1, v244, 9
	s_and_b64 vcc, exec, s[0:1]
	s_cbranch_vccnz .LBB0_563
	v_cmp_gt_u32_e32 vcc, v34, v123
	v_cmp_eq_u32_e64 s[52:53], v34, v123
	s_and_saveexec_b64 s[0:1], vcc
	s_cbranch_execz .LBB0_500
	s_lshl_b32 s55, s54, 2
	v_mbcnt_lo_u32_b32 v125, vcc_lo, 0
	s_add_i32 s55, s8, s55
	v_mbcnt_hi_u32_b32 v125, vcc_hi, v125
	v_add_u32_e32 v124, 0x1800, v0
	v_lshl_add_u32 v125, v125, 2, s55
	ds_write_b32 v125, v124 offset:16896
.LBB0_500:
	s_or_b64 exec, exec, s[0:1]
	v_mbcnt_lo_u32_b32 v124, s52, 0
	v_mbcnt_hi_u32_b32 v124, s53, v124
	v_add_u32_e32 v124, s4, v124
	s_movk_i32 s0, 0x100
	v_cmp_gt_i32_e64 s[0:1], s0, v124
	s_and_b64 s[56:57], s[52:53], s[0:1]
	s_and_saveexec_b64 s[0:1], s[56:57]
	v_lshl_add_u32 v124, v124, 2, s8
	v_add_u32_e32 v125, 0x1800, v0
	ds_write_b32 v124, v125 offset:16896
	s_or_b64 exec, exec, s[0:1]
	s_bcnt1_i32_b64 s0, vcc
	s_add_i32 s56, s54, s0
	v_cmp_gt_u32_e64 s[54:55], v32, v123
	v_cmp_eq_u32_e32 vcc, v32, v123
	s_and_saveexec_b64 s[0:1], s[54:55]
	s_cbranch_execz .LBB0_504
	s_lshl_b32 s57, s56, 2
	v_mbcnt_lo_u32_b32 v125, s54, 0
	s_add_i32 s57, s8, s57
	v_mbcnt_hi_u32_b32 v125, s55, v125
	v_add_u32_e32 v124, 0x1840, v0
	v_lshl_add_u32 v125, v125, 2, s57
	ds_write_b32 v125, v124 offset:16896
; __device__ __forceinline__ void topk_row(const Params& p, int r, int lane, __attribute__((address_space(3))) int* out) {
;     ...
;     int base_gt = 0, base_eq = cgt;
; #pragma unroll
;     for (int blk = 0; blk < 8; ++blk) {
;       if (blk * 16 < nch) {
; #pragma unroll
;         for (int ii = 0; ii < 16; ++ii) {
;           const int i = blk * 16 + ii;
;           const bool g = key[i] > Tv, e = key[i] == Tv;
;           const unsigned long long mg = __ballot(g), me = __ballot(e);
;           const int pg = base_gt + mbcnt64(mg);
;           if (g) out[pg] = i * 64 + lo;
;           base_gt += __popcll(mg);
;           const int pe = base_eq + mbcnt64(me);
;           if (e && pe < 256) out[pe] = i * 64 + lo;
;           base_eq += __popcll(me);
;         }
;       }
;     }
.LBB0_504:
	s_or_b64 exec, exec, s[0:1]
	s_bcnt1_i32_b64 s0, s[52:53]
	v_mbcnt_lo_u32_b32 v124, vcc_lo, 0
	s_add_i32 s4, s4, s0
	v_mbcnt_hi_u32_b32 v124, vcc_hi, v124
	v_add_u32_e32 v124, s4, v124
	s_movk_i32 s0, 0x100
	v_cmp_gt_i32_e64 s[0:1], s0, v124
	s_and_b64 s[52:53], vcc, s[0:1]
	s_and_saveexec_b64 s[0:1], s[52:53]
	v_lshl_add_u32 v124, v124, 2, s8
	v_add_u32_e32 v125, 0x1840, v0
	ds_write_b32 v124, v125 offset:16896
	s_or_b64 exec, exec, s[0:1]
	s_bcnt1_i32_b64 s0, s[54:55]
	s_add_i32 s56, s56, s0
	v_cmp_gt_u32_e64 s[54:55], v31, v123
	v_cmp_eq_u32_e64 s[52:53], v31, v123
	s_and_saveexec_b64 s[0:1], s[54:55]
	s_cbranch_execz .LBB0_508
	s_lshl_b32 s57, s56, 2
	v_mbcnt_lo_u32_b32 v125, s54, 0
	s_add_i32 s57, s8, s57
	v_mbcnt_hi_u32_b32 v125, s55, v125
	v_add_u32_e32 v124, 0x1880, v0
	v_lshl_add_u32 v125, v125, 2, s57
	ds_write_b32 v125, v124 offset:16896
.LBB0_508:
	s_or_b64 exec, exec, s[0:1]
	s_bcnt1_i32_b64 s0, vcc
	v_mbcnt_lo_u32_b32 v124, s52, 0
	s_add_i32 s4, s4, s0
	v_mbcnt_hi_u32_b32 v124, s53, v124
	v_add_u32_e32 v124, s4, v124
	s_movk_i32 s0, 0x100
	v_cmp_gt_i32_e32 vcc, s0, v124
	s_and_b64 s[58:59], s[52:53], vcc
	s_and_saveexec_b64 s[0:1], s[58:59]
	v_lshl_add_u32 v124, v124, 2, s8
	v_add_u32_e32 v125, 0x1880, v0
	ds_write_b32 v124, v125 offset:16896
	s_or_b64 exec, exec, s[0:1]
	s_bcnt1_i32_b64 s0, s[54:55]
	s_add_i32 s56, s56, s0
	v_cmp_gt_u32_e64 s[54:55], v30, v123
	v_cmp_eq_u32_e32 vcc, v30, v123
	s_and_saveexec_b64 s[0:1], s[54:55]
	s_cbranch_execz .LBB0_512
	s_lshl_b32 s57, s56, 2
	v_mbcnt_lo_u32_b32 v125, s54, 0
	s_add_i32 s57, s8, s57
	v_mbcnt_hi_u32_b32 v125, s55, v125
	v_add_u32_e32 v124, 0x18c0, v0
	v_lshl_add_u32 v125, v125, 2, s57
	ds_write_b32 v125, v124 offset:16896
.LBB0_512:
	s_or_b64 exec, exec, s[0:1]
	s_bcnt1_i32_b64 s0, s[52:53]
	v_mbcnt_lo_u32_b32 v124, vcc_lo, 0
	s_add_i32 s4, s4, s0
	v_mbcnt_hi_u32_b32 v124, vcc_hi, v124
	v_add_u32_e32 v124, s4, v124
	s_movk_i32 s0, 0x100
	v_cmp_gt_i32_e64 s[0:1], s0, v124
	s_and_b64 s[52:53], vcc, s[0:1]
	s_and_saveexec_b64 s[0:1], s[52:53]
	v_lshl_add_u32 v124, v124, 2, s8
	v_add_u32_e32 v125, 0x18c0, v0
	ds_write_b32 v124, v125 offset:16896
	s_or_b64 exec, exec, s[0:1]
	s_bcnt1_i32_b64 s0, s[54:55]
	s_add_i32 s56, s56, s0
	v_cmp_gt_u32_e64 s[54:55], v29, v123
	v_cmp_eq_u32_e64 s[52:53], v29, v123
	s_and_saveexec_b64 s[0:1], s[54:55]
	s_cbranch_execz .LBB0_516
	s_lshl_b32 s57, s56, 2
	v_mbcnt_lo_u32_b32 v125, s54, 0
	s_add_i32 s57, s8, s57
	v_mbcnt_hi_u32_b32 v125, s55, v125
	v_add_u32_e32 v124, 0x1900, v0
	v_lshl_add_u32 v125, v125, 2, s57
	ds_write_b32 v125, v124 offset:16896
.LBB0_516:
	s_or_b64 exec, exec, s[0:1]
	s_bcnt1_i32_b64 s0, vcc
	v_mbcnt_lo_u32_b32 v124, s52, 0
	s_add_i32 s4, s4, s0
	v_mbcnt_hi_u32_b32 v124, s53, v124
	v_add_u32_e32 v124, s4, v124
	s_movk_i32 s0, 0x100
	v_cmp_gt_i32_e32 vcc, s0, v124
	s_and_b64 s[58:59], s[52:53], vcc
	s_and_saveexec_b64 s[0:1], s[58:59]
	v_lshl_add_u32 v124, v124, 2, s8
	v_add_u32_e32 v125, 0x1900, v0
	ds_write_b32 v124, v125 offset:16896
	s_or_b64 exec, exec, s[0:1]
	s_bcnt1_i32_b64 s0, s[54:55]
	s_add_i32 s56, s56, s0
	v_cmp_gt_u32_e64 s[54:55], v28, v123
	v_cmp_eq_u32_e32 vcc, v28, v123
	s_and_saveexec_b64 s[0:1], s[54:55]
	s_cbranch_execz .LBB0_520
	s_lshl_b32 s57, s56, 2
	v_mbcnt_lo_u32_b32 v125, s54, 0
	s_add_i32 s57, s8, s57
	v_mbcnt_hi_u32_b32 v125, s55, v125
	v_add_u32_e32 v124, 0x1940, v0
	v_lshl_add_u32 v125, v125, 2, s57
	ds_write_b32 v125, v124 offset:16896
.LBB0_520:
	s_or_b64 exec, exec, s[0:1]
	s_bcnt1_i32_b64 s0, s[52:53]
	v_mbcnt_lo_u32_b32 v124, vcc_lo, 0
	s_add_i32 s4, s4, s0
	v_mbcnt_hi_u32_b32 v124, vcc_hi, v124
	v_add_u32_e32 v124, s4, v124
	s_movk_i32 s0, 0x100
	v_cmp_gt_i32_e64 s[0:1], s0, v124
	s_and_b64 s[52:53], vcc, s[0:1]
	s_and_saveexec_b64 s[0:1], s[52:53]
	v_lshl_add_u32 v124, v124, 2, s8
	v_add_u32_e32 v125, 0x1940, v0
	ds_write_b32 v124, v125 offset:16896
	s_or_b64 exec, exec, s[0:1]
	s_bcnt1_i32_b64 s0, s[54:55]
	s_add_i32 s56, s56, s0
	v_cmp_gt_u32_e64 s[54:55], v27, v123
	v_cmp_eq_u32_e64 s[52:53], v27, v123
	s_and_saveexec_b64 s[0:1], s[54:55]
	s_cbranch_execz .LBB0_524
	s_lshl_b32 s57, s56, 2
	v_mbcnt_lo_u32_b32 v125, s54, 0
	s_add_i32 s57, s8, s57
	v_mbcnt_hi_u32_b32 v125, s55, v125
	v_add_u32_e32 v124, 0x1980, v0
	v_lshl_add_u32 v125, v125, 2, s57
	ds_write_b32 v125, v124 offset:16896
.LBB0_524:
	s_or_b64 exec, exec, s[0:1]
	s_bcnt1_i32_b64 s0, vcc
	v_mbcnt_lo_u32_b32 v124, s52, 0
	s_add_i32 s4, s4, s0
	v_mbcnt_hi_u32_b32 v124, s53, v124
	v_add_u32_e32 v124, s4, v124
	s_movk_i32 s0, 0x100
	v_cmp_gt_i32_e32 vcc, s0, v124
	s_and_b64 s[58:59], s[52:53], vcc
	s_and_saveexec_b64 s[0:1], s[58:59]
	v_lshl_add_u32 v124, v124, 2, s8
	v_add_u32_e32 v125, 0x1980, v0
	ds_write_b32 v124, v125 offset:16896
	s_or_b64 exec, exec, s[0:1]
	s_bcnt1_i32_b64 s0, s[54:55]
	s_add_i32 s56, s56, s0
	v_cmp_gt_u32_e64 s[54:55], v26, v123
	v_cmp_eq_u32_e32 vcc, v26, v123
	s_and_saveexec_b64 s[0:1], s[54:55]
	s_cbranch_execz .LBB0_528
	s_lshl_b32 s57, s56, 2
	v_mbcnt_lo_u32_b32 v125, s54, 0
	s_add_i32 s57, s8, s57
	v_mbcnt_hi_u32_b32 v125, s55, v125
	v_add_u32_e32 v124, 0x19c0, v0
	v_lshl_add_u32 v125, v125, 2, s57
	ds_write_b32 v125, v124 offset:16896
.LBB0_528:
	s_or_b64 exec, exec, s[0:1]
	s_bcnt1_i32_b64 s0, s[52:53]
	v_mbcnt_lo_u32_b32 v124, vcc_lo, 0
	s_add_i32 s4, s4, s0
	v_mbcnt_hi_u32_b32 v124, vcc_hi, v124
	v_add_u32_e32 v124, s4, v124
	s_movk_i32 s0, 0x100
	v_cmp_gt_i32_e64 s[0:1], s0, v124
	s_and_b64 s[52:53], vcc, s[0:1]
	s_and_saveexec_b64 s[0:1], s[52:53]
	v_lshl_add_u32 v124, v124, 2, s8
	v_add_u32_e32 v125, 0x19c0, v0
	ds_write_b32 v124, v125 offset:16896
	s_or_b64 exec, exec, s[0:1]
	s_bcnt1_i32_b64 s0, s[54:55]
	s_add_i32 s56, s56, s0
	v_cmp_gt_u32_e64 s[54:55], v25, v123
	v_cmp_eq_u32_e64 s[52:53], v25, v123
	s_and_saveexec_b64 s[0:1], s[54:55]
	s_cbranch_execz .LBB0_532
	s_lshl_b32 s57, s56, 2
	v_mbcnt_lo_u32_b32 v125, s54, 0
	s_add_i32 s57, s8, s57
	v_mbcnt_hi_u32_b32 v125, s55, v125
	v_add_u32_e32 v124, 0x1a00, v0
	v_lshl_add_u32 v125, v125, 2, s57
	ds_write_b32 v125, v124 offset:16896
; __device__ __forceinline__ void topk_row(const Params& p, int r, int lane, __attribute__((address_space(3))) int* out) {
;     ...
;     int base_gt = 0, base_eq = cgt;
; #pragma unroll
;     for (int blk = 0; blk < 8; ++blk) {
;       if (blk * 16 < nch) {
; #pragma unroll
;         for (int ii = 0; ii < 16; ++ii) {
;           const int i = blk * 16 + ii;
;           const bool g = key[i] > Tv, e = key[i] == Tv;
;           const unsigned long long mg = __ballot(g), me = __ballot(e);
;           const int pg = base_gt + mbcnt64(mg);
;           if (g) out[pg] = i * 64 + lo;
;           base_gt += __popcll(mg);
;           const int pe = base_eq + mbcnt64(me);
;           if (e && pe < 256) out[pe] = i * 64 + lo;
;           base_eq += __popcll(me);
;         }
;       }
;     }
.LBB0_532:
	s_or_b64 exec, exec, s[0:1]
	s_bcnt1_i32_b64 s0, vcc
	v_mbcnt_lo_u32_b32 v124, s52, 0
	s_add_i32 s4, s4, s0
	v_mbcnt_hi_u32_b32 v124, s53, v124
	v_add_u32_e32 v124, s4, v124
	s_movk_i32 s0, 0x100
	v_cmp_gt_i32_e32 vcc, s0, v124
	s_and_b64 s[58:59], s[52:53], vcc
	s_and_saveexec_b64 s[0:1], s[58:59]
	v_lshl_add_u32 v124, v124, 2, s8
	v_add_u32_e32 v125, 0x1a00, v0
	ds_write_b32 v124, v125 offset:16896
	s_or_b64 exec, exec, s[0:1]
	s_bcnt1_i32_b64 s0, s[54:55]
	s_add_i32 s56, s56, s0
	v_cmp_gt_u32_e64 s[54:55], v24, v123
	v_cmp_eq_u32_e32 vcc, v24, v123
	s_and_saveexec_b64 s[0:1], s[54:55]
	s_cbranch_execz .LBB0_536
	s_lshl_b32 s57, s56, 2
	v_mbcnt_lo_u32_b32 v125, s54, 0
	s_add_i32 s57, s8, s57
	v_mbcnt_hi_u32_b32 v125, s55, v125
	v_add_u32_e32 v124, 0x1a40, v0
	v_lshl_add_u32 v125, v125, 2, s57
	ds_write_b32 v125, v124 offset:16896
.LBB0_536:
	s_or_b64 exec, exec, s[0:1]
	s_bcnt1_i32_b64 s0, s[52:53]
	v_mbcnt_lo_u32_b32 v124, vcc_lo, 0
	s_add_i32 s4, s4, s0
	v_mbcnt_hi_u32_b32 v124, vcc_hi, v124
	v_add_u32_e32 v124, s4, v124
	s_movk_i32 s0, 0x100
	v_cmp_gt_i32_e64 s[0:1], s0, v124
	s_and_b64 s[52:53], vcc, s[0:1]
	s_and_saveexec_b64 s[0:1], s[52:53]
	v_lshl_add_u32 v124, v124, 2, s8
	v_add_u32_e32 v125, 0x1a40, v0
	ds_write_b32 v124, v125 offset:16896
	s_or_b64 exec, exec, s[0:1]
	s_bcnt1_i32_b64 s0, s[54:55]
	s_add_i32 s56, s56, s0
	v_cmp_gt_u32_e64 s[54:55], v23, v123
	v_cmp_eq_u32_e64 s[52:53], v23, v123
	s_and_saveexec_b64 s[0:1], s[54:55]
	s_cbranch_execz .LBB0_540
	s_lshl_b32 s57, s56, 2
	v_mbcnt_lo_u32_b32 v125, s54, 0
	s_add_i32 s57, s8, s57
	v_mbcnt_hi_u32_b32 v125, s55, v125
	v_add_u32_e32 v124, 0x1a80, v0
	v_lshl_add_u32 v125, v125, 2, s57
	ds_write_b32 v125, v124 offset:16896
.LBB0_540:
	s_or_b64 exec, exec, s[0:1]
	s_bcnt1_i32_b64 s0, vcc
	v_mbcnt_lo_u32_b32 v124, s52, 0
	s_add_i32 s4, s4, s0
	v_mbcnt_hi_u32_b32 v124, s53, v124
	v_add_u32_e32 v124, s4, v124
	s_movk_i32 s0, 0x100
	v_cmp_gt_i32_e32 vcc, s0, v124
	s_and_b64 s[58:59], s[52:53], vcc
	s_and_saveexec_b64 s[0:1], s[58:59]
	v_lshl_add_u32 v124, v124, 2, s8
	v_add_u32_e32 v125, 0x1a80, v0
	ds_write_b32 v124, v125 offset:16896
	s_or_b64 exec, exec, s[0:1]
	s_bcnt1_i32_b64 s0, s[54:55]
	s_add_i32 s56, s56, s0
	v_cmp_gt_u32_e64 s[54:55], v22, v123
	v_cmp_eq_u32_e32 vcc, v22, v123
	s_and_saveexec_b64 s[0:1], s[54:55]
	s_cbranch_execz .LBB0_544
	s_lshl_b32 s57, s56, 2
	v_mbcnt_lo_u32_b32 v125, s54, 0
	s_add_i32 s57, s8, s57
	v_mbcnt_hi_u32_b32 v125, s55, v125
	v_add_u32_e32 v124, 0x1ac0, v0
	v_lshl_add_u32 v125, v125, 2, s57
	ds_write_b32 v125, v124 offset:16896
.LBB0_544:
	s_or_b64 exec, exec, s[0:1]
	s_bcnt1_i32_b64 s0, s[52:53]
	v_mbcnt_lo_u32_b32 v124, vcc_lo, 0
	s_add_i32 s4, s4, s0
	v_mbcnt_hi_u32_b32 v124, vcc_hi, v124
	v_add_u32_e32 v124, s4, v124
	s_movk_i32 s0, 0x100
	v_cmp_gt_i32_e64 s[0:1], s0, v124
	s_and_b64 s[52:53], vcc, s[0:1]
	s_and_saveexec_b64 s[0:1], s[52:53]
	v_lshl_add_u32 v124, v124, 2, s8
	v_add_u32_e32 v125, 0x1ac0, v0
	ds_write_b32 v124, v125 offset:16896
	s_or_b64 exec, exec, s[0:1]
	s_bcnt1_i32_b64 s0, s[54:55]
	s_add_i32 s56, s56, s0
	v_cmp_gt_u32_e64 s[54:55], v21, v123
	v_cmp_eq_u32_e64 s[52:53], v21, v123
	s_and_saveexec_b64 s[0:1], s[54:55]
	s_cbranch_execz .LBB0_548
	s_lshl_b32 s57, s56, 2
	v_mbcnt_lo_u32_b32 v125, s54, 0
	s_add_i32 s57, s8, s57
	v_mbcnt_hi_u32_b32 v125, s55, v125
	v_add_u32_e32 v124, 0x1b00, v0
	v_lshl_add_u32 v125, v125, 2, s57
	ds_write_b32 v125, v124 offset:16896
.LBB0_548:
	s_or_b64 exec, exec, s[0:1]
	s_bcnt1_i32_b64 s0, vcc
	v_mbcnt_lo_u32_b32 v124, s52, 0
	s_add_i32 s4, s4, s0
	v_mbcnt_hi_u32_b32 v124, s53, v124
	v_add_u32_e32 v124, s4, v124
	s_movk_i32 s0, 0x100
	v_cmp_gt_i32_e32 vcc, s0, v124
	s_and_b64 s[58:59], s[52:53], vcc
	s_and_saveexec_b64 s[0:1], s[58:59]
	v_lshl_add_u32 v124, v124, 2, s8
	v_add_u32_e32 v125, 0x1b00, v0
	ds_write_b32 v124, v125 offset:16896
	s_or_b64 exec, exec, s[0:1]
	s_bcnt1_i32_b64 s0, s[54:55]
	s_add_i32 s56, s56, s0
	v_cmp_gt_u32_e64 s[54:55], v20, v123
	v_cmp_eq_u32_e32 vcc, v20, v123
	s_and_saveexec_b64 s[0:1], s[54:55]
	s_cbranch_execz .LBB0_552
	s_lshl_b32 s57, s56, 2
	v_mbcnt_lo_u32_b32 v125, s54, 0
	s_add_i32 s57, s8, s57
	v_mbcnt_hi_u32_b32 v125, s55, v125
	v_add_u32_e32 v124, 0x1b40, v0
	v_lshl_add_u32 v125, v125, 2, s57
	ds_write_b32 v125, v124 offset:16896
.LBB0_552:
	s_or_b64 exec, exec, s[0:1]
	s_bcnt1_i32_b64 s0, s[52:53]
	v_mbcnt_lo_u32_b32 v124, vcc_lo, 0
	s_add_i32 s4, s4, s0
	v_mbcnt_hi_u32_b32 v124, vcc_hi, v124
	v_add_u32_e32 v124, s4, v124
	s_movk_i32 s0, 0x100
	v_cmp_gt_i32_e64 s[0:1], s0, v124
	s_and_b64 s[52:53], vcc, s[0:1]
	s_and_saveexec_b64 s[0:1], s[52:53]
	v_lshl_add_u32 v124, v124, 2, s8
	v_add_u32_e32 v125, 0x1b40, v0
	ds_write_b32 v124, v125 offset:16896
	s_or_b64 exec, exec, s[0:1]
	s_bcnt1_i32_b64 s0, s[54:55]
	s_add_i32 s56, s56, s0
	v_cmp_gt_u32_e64 s[54:55], v19, v123
	v_cmp_eq_u32_e64 s[52:53], v19, v123
	s_and_saveexec_b64 s[0:1], s[54:55]
	s_cbranch_execz .LBB0_556
	s_lshl_b32 s57, s56, 2
	v_mbcnt_lo_u32_b32 v125, s54, 0
	s_add_i32 s57, s8, s57
	v_mbcnt_hi_u32_b32 v125, s55, v125
	v_add_u32_e32 v124, 0x1b80, v0
	v_lshl_add_u32 v125, v125, 2, s57
	ds_write_b32 v125, v124 offset:16896
.LBB0_556:
	s_or_b64 exec, exec, s[0:1]
	s_bcnt1_i32_b64 s0, vcc
	v_mbcnt_lo_u32_b32 v124, s52, 0
	s_add_i32 s4, s4, s0
	v_mbcnt_hi_u32_b32 v124, s53, v124
	v_add_u32_e32 v124, s4, v124
	s_movk_i32 s0, 0x100
	v_cmp_gt_i32_e32 vcc, s0, v124
	s_and_b64 s[58:59], s[52:53], vcc
	s_and_saveexec_b64 s[0:1], s[58:59]
	v_lshl_add_u32 v124, v124, 2, s8
	v_add_u32_e32 v125, 0x1b80, v0
	ds_write_b32 v124, v125 offset:16896
	s_or_b64 exec, exec, s[0:1]
	s_bcnt1_i32_b64 s0, s[54:55]
	s_add_i32 s56, s56, s0
	v_cmp_gt_u32_e64 s[54:55], v18, v123
	v_cmp_eq_u32_e32 vcc, v18, v123
	s_and_saveexec_b64 s[0:1], s[54:55]
	s_cbranch_execz .LBB0_560
	s_lshl_b32 s57, s56, 2
	v_mbcnt_lo_u32_b32 v125, s54, 0
	s_add_i32 s57, s8, s57
	v_mbcnt_hi_u32_b32 v125, s55, v125
	v_add_u32_e32 v124, 0x1bc0, v0
	v_lshl_add_u32 v125, v125, 2, s57
	ds_write_b32 v125, v124 offset:16896
; __device__ __forceinline__ void topk_row(const Params& p, int r, int lane, __attribute__((address_space(3))) int* out) {
;     ...
;     int base_gt = 0, base_eq = cgt;
; #pragma unroll
;     for (int blk = 0; blk < 8; ++blk) {
;       if (blk * 16 < nch) {
; #pragma unroll
;         for (int ii = 0; ii < 16; ++ii) {
;           const int i = blk * 16 + ii;
;           const bool g = key[i] > Tv, e = key[i] == Tv;
;           const unsigned long long mg = __ballot(g), me = __ballot(e);
;           const int pg = base_gt + mbcnt64(mg);
;           if (g) out[pg] = i * 64 + lo;
;           base_gt += __popcll(mg);
;           const int pe = base_eq + mbcnt64(me);
;           if (e && pe < 256) out[pe] = i * 64 + lo;
;           base_eq += __popcll(me);
;         }
;       }
;     }
.LBB0_560:
	s_or_b64 exec, exec, s[0:1]
	s_bcnt1_i32_b64 s0, s[52:53]
	v_mbcnt_lo_u32_b32 v124, vcc_lo, 0
	s_add_i32 s4, s4, s0
	v_mbcnt_hi_u32_b32 v124, vcc_hi, v124
	v_add_u32_e32 v124, s4, v124
	s_movk_i32 s0, 0x100
	v_cmp_gt_i32_e64 s[0:1], s0, v124
	s_and_b64 s[52:53], vcc, s[0:1]
	s_and_saveexec_b64 s[0:1], s[52:53]
	v_lshl_add_u32 v124, v124, 2, s8
	v_add_u32_e32 v125, 0x1bc0, v0
	ds_write_b32 v124, v125 offset:16896
	s_or_b64 exec, exec, s[0:1]
	s_bcnt1_i32_b64 s0, s[54:55]
	s_add_i32 s54, s56, s0
	s_bcnt1_i32_b64 s0, vcc
	s_add_i32 s4, s4, s0
.LBB0_563:
	v_readlane_b32 s0, v244, 10
	v_readlane_b32 s1, v244, 11
	s_and_b64 vcc, exec, s[0:1]
	s_cbranch_vccnz .LBB0_629
	v_cmp_gt_u32_e32 vcc, v17, v123
	v_cmp_eq_u32_e64 s[52:53], v17, v123
	s_and_saveexec_b64 s[0:1], vcc
	s_cbranch_execz .LBB0_566
	s_lshl_b32 s55, s54, 2
	v_mbcnt_lo_u32_b32 v125, vcc_lo, 0
	s_add_i32 s55, s8, s55
	v_mbcnt_hi_u32_b32 v125, vcc_hi, v125
	v_add_u32_e32 v124, 0x1c00, v0
	v_lshl_add_u32 v125, v125, 2, s55
	ds_write_b32 v125, v124 offset:16896
.LBB0_566:
	s_or_b64 exec, exec, s[0:1]
	v_mbcnt_lo_u32_b32 v124, s52, 0
	v_mbcnt_hi_u32_b32 v124, s53, v124
	v_add_u32_e32 v124, s4, v124
	s_movk_i32 s0, 0x100
	v_cmp_gt_i32_e64 s[0:1], s0, v124
	s_and_b64 s[56:57], s[52:53], s[0:1]
	s_and_saveexec_b64 s[0:1], s[56:57]
	v_lshl_add_u32 v124, v124, 2, s8
	v_add_u32_e32 v125, 0x1c00, v0
	ds_write_b32 v124, v125 offset:16896
	s_or_b64 exec, exec, s[0:1]
	s_bcnt1_i32_b64 s0, vcc
	s_add_i32 s56, s54, s0
	v_cmp_gt_u32_e64 s[54:55], v16, v123
	v_cmp_eq_u32_e32 vcc, v16, v123
	s_and_saveexec_b64 s[0:1], s[54:55]
	s_cbranch_execz .LBB0_570
	s_lshl_b32 s57, s56, 2
	v_mbcnt_lo_u32_b32 v125, s54, 0
	s_add_i32 s57, s8, s57
	v_mbcnt_hi_u32_b32 v125, s55, v125
	v_add_u32_e32 v124, 0x1c40, v0
	v_lshl_add_u32 v125, v125, 2, s57
	ds_write_b32 v125, v124 offset:16896
.LBB0_570:
	s_or_b64 exec, exec, s[0:1]
	s_bcnt1_i32_b64 s0, s[52:53]
	v_mbcnt_lo_u32_b32 v124, vcc_lo, 0
	s_add_i32 s4, s4, s0
	v_mbcnt_hi_u32_b32 v124, vcc_hi, v124
	v_add_u32_e32 v124, s4, v124
	s_movk_i32 s0, 0x100
	v_cmp_gt_i32_e64 s[0:1], s0, v124
	s_and_b64 s[52:53], vcc, s[0:1]
	s_and_saveexec_b64 s[0:1], s[52:53]
	v_lshl_add_u32 v124, v124, 2, s8
	v_add_u32_e32 v125, 0x1c40, v0
	ds_write_b32 v124, v125 offset:16896
	s_or_b64 exec, exec, s[0:1]
	s_bcnt1_i32_b64 s0, s[54:55]
	s_add_i32 s56, s56, s0
	v_cmp_gt_u32_e64 s[54:55], v15, v123
	v_cmp_eq_u32_e64 s[52:53], v15, v123
	s_and_saveexec_b64 s[0:1], s[54:55]
	s_cbranch_execz .LBB0_574
	s_lshl_b32 s57, s56, 2
	v_mbcnt_lo_u32_b32 v125, s54, 0
	s_add_i32 s57, s8, s57
	v_mbcnt_hi_u32_b32 v125, s55, v125
	v_add_u32_e32 v124, 0x1c80, v0
	v_lshl_add_u32 v125, v125, 2, s57
	ds_write_b32 v125, v124 offset:16896
.LBB0_574:
	s_or_b64 exec, exec, s[0:1]
	s_bcnt1_i32_b64 s0, vcc
	v_mbcnt_lo_u32_b32 v124, s52, 0
	s_add_i32 s4, s4, s0
	v_mbcnt_hi_u32_b32 v124, s53, v124
	v_add_u32_e32 v124, s4, v124
	s_movk_i32 s0, 0x100
	v_cmp_gt_i32_e32 vcc, s0, v124
	s_and_b64 s[58:59], s[52:53], vcc
	s_and_saveexec_b64 s[0:1], s[58:59]
	v_lshl_add_u32 v124, v124, 2, s8
	v_add_u32_e32 v125, 0x1c80, v0
	ds_write_b32 v124, v125 offset:16896
	s_or_b64 exec, exec, s[0:1]
	s_bcnt1_i32_b64 s0, s[54:55]
	s_add_i32 s56, s56, s0
	v_cmp_gt_u32_e64 s[54:55], v14, v123
	v_cmp_eq_u32_e32 vcc, v14, v123
	s_and_saveexec_b64 s[0:1], s[54:55]
	s_cbranch_execz .LBB0_578
	s_lshl_b32 s57, s56, 2
	v_mbcnt_lo_u32_b32 v125, s54, 0
	s_add_i32 s57, s8, s57
	v_mbcnt_hi_u32_b32 v125, s55, v125
	v_add_u32_e32 v124, 0x1cc0, v0
	v_lshl_add_u32 v125, v125, 2, s57
	ds_write_b32 v125, v124 offset:16896
.LBB0_578:
	s_or_b64 exec, exec, s[0:1]
	s_bcnt1_i32_b64 s0, s[52:53]
	v_mbcnt_lo_u32_b32 v124, vcc_lo, 0
	s_add_i32 s4, s4, s0
	v_mbcnt_hi_u32_b32 v124, vcc_hi, v124
	v_add_u32_e32 v124, s4, v124
	s_movk_i32 s0, 0x100
	v_cmp_gt_i32_e64 s[0:1], s0, v124
	s_and_b64 s[52:53], vcc, s[0:1]
	s_and_saveexec_b64 s[0:1], s[52:53]
	v_lshl_add_u32 v124, v124, 2, s8
	v_add_u32_e32 v125, 0x1cc0, v0
	ds_write_b32 v124, v125 offset:16896
	s_or_b64 exec, exec, s[0:1]
	s_bcnt1_i32_b64 s0, s[54:55]
	s_add_i32 s56, s56, s0
	v_cmp_gt_u32_e64 s[54:55], v13, v123
	v_cmp_eq_u32_e64 s[52:53], v13, v123
	s_and_saveexec_b64 s[0:1], s[54:55]
	s_cbranch_execz .LBB0_582
	s_lshl_b32 s57, s56, 2
	v_mbcnt_lo_u32_b32 v125, s54, 0
	s_add_i32 s57, s8, s57
	v_mbcnt_hi_u32_b32 v125, s55, v125
	v_add_u32_e32 v124, 0x1d00, v0
	v_lshl_add_u32 v125, v125, 2, s57
	ds_write_b32 v125, v124 offset:16896
.LBB0_582:
	s_or_b64 exec, exec, s[0:1]
	s_bcnt1_i32_b64 s0, vcc
	v_mbcnt_lo_u32_b32 v124, s52, 0
	s_add_i32 s4, s4, s0
	v_mbcnt_hi_u32_b32 v124, s53, v124
	v_add_u32_e32 v124, s4, v124
	s_movk_i32 s0, 0x100
	v_cmp_gt_i32_e32 vcc, s0, v124
	s_and_b64 s[58:59], s[52:53], vcc
	s_and_saveexec_b64 s[0:1], s[58:59]
	v_lshl_add_u32 v124, v124, 2, s8
	v_add_u32_e32 v125, 0x1d00, v0
	ds_write_b32 v124, v125 offset:16896
	s_or_b64 exec, exec, s[0:1]
	s_bcnt1_i32_b64 s0, s[54:55]
	s_add_i32 s56, s56, s0
	v_cmp_gt_u32_e64 s[54:55], v12, v123
	v_cmp_eq_u32_e32 vcc, v12, v123
	s_and_saveexec_b64 s[0:1], s[54:55]
	s_cbranch_execz .LBB0_586
	s_lshl_b32 s57, s56, 2
	v_mbcnt_lo_u32_b32 v125, s54, 0
	s_add_i32 s57, s8, s57
	v_mbcnt_hi_u32_b32 v125, s55, v125
	v_add_u32_e32 v124, 0x1d40, v0
	v_lshl_add_u32 v125, v125, 2, s57
	ds_write_b32 v125, v124 offset:16896
; __device__ __forceinline__ void topk_row(const Params& p, int r, int lane, __attribute__((address_space(3))) int* out) {
;     ...
;     int base_gt = 0, base_eq = cgt;
; #pragma unroll
;     for (int blk = 0; blk < 8; ++blk) {
;       if (blk * 16 < nch) {
; #pragma unroll
;         for (int ii = 0; ii < 16; ++ii) {
;           const int i = blk * 16 + ii;
;           const bool g = key[i] > Tv, e = key[i] == Tv;
;           const unsigned long long mg = __ballot(g), me = __ballot(e);
;           const int pg = base_gt + mbcnt64(mg);
;           if (g) out[pg] = i * 64 + lo;
;           base_gt += __popcll(mg);
;           const int pe = base_eq + mbcnt64(me);
;           if (e && pe < 256) out[pe] = i * 64 + lo;
;           base_eq += __popcll(me);
;         }
;       }
;     }
.LBB0_586:
	s_or_b64 exec, exec, s[0:1]
	s_bcnt1_i32_b64 s0, s[52:53]
	v_mbcnt_lo_u32_b32 v124, vcc_lo, 0
	s_add_i32 s4, s4, s0
	v_mbcnt_hi_u32_b32 v124, vcc_hi, v124
	v_add_u32_e32 v124, s4, v124
	s_movk_i32 s0, 0x100
	v_cmp_gt_i32_e64 s[0:1], s0, v124
	s_and_b64 s[52:53], vcc, s[0:1]
	s_and_saveexec_b64 s[0:1], s[52:53]
	v_lshl_add_u32 v124, v124, 2, s8
	v_add_u32_e32 v125, 0x1d40, v0
	ds_write_b32 v124, v125 offset:16896
	s_or_b64 exec, exec, s[0:1]
	s_bcnt1_i32_b64 s0, s[54:55]
	s_add_i32 s56, s56, s0
	v_cmp_gt_u32_e64 s[54:55], v11, v123
	v_cmp_eq_u32_e64 s[52:53], v11, v123
	s_and_saveexec_b64 s[0:1], s[54:55]
	s_cbranch_execz .LBB0_590
	s_lshl_b32 s57, s56, 2
	v_mbcnt_lo_u32_b32 v125, s54, 0
	s_add_i32 s57, s8, s57
	v_mbcnt_hi_u32_b32 v125, s55, v125
	v_add_u32_e32 v124, 0x1d80, v0
	v_lshl_add_u32 v125, v125, 2, s57
	ds_write_b32 v125, v124 offset:16896
.LBB0_590:
	s_or_b64 exec, exec, s[0:1]
	s_bcnt1_i32_b64 s0, vcc
	v_mbcnt_lo_u32_b32 v124, s52, 0
	s_add_i32 s4, s4, s0
	v_mbcnt_hi_u32_b32 v124, s53, v124
	v_add_u32_e32 v124, s4, v124
	s_movk_i32 s0, 0x100
	v_cmp_gt_i32_e32 vcc, s0, v124
	s_and_b64 s[58:59], s[52:53], vcc
	s_and_saveexec_b64 s[0:1], s[58:59]
	v_lshl_add_u32 v124, v124, 2, s8
	v_add_u32_e32 v125, 0x1d80, v0
	ds_write_b32 v124, v125 offset:16896
	s_or_b64 exec, exec, s[0:1]
	s_bcnt1_i32_b64 s0, s[54:55]
	s_add_i32 s56, s56, s0
	v_cmp_gt_u32_e64 s[54:55], v10, v123
	v_cmp_eq_u32_e32 vcc, v10, v123
	s_and_saveexec_b64 s[0:1], s[54:55]
	s_cbranch_execz .LBB0_594
	s_lshl_b32 s57, s56, 2
	v_mbcnt_lo_u32_b32 v125, s54, 0
	s_add_i32 s57, s8, s57
	v_mbcnt_hi_u32_b32 v125, s55, v125
	v_add_u32_e32 v124, 0x1dc0, v0
	v_lshl_add_u32 v125, v125, 2, s57
	ds_write_b32 v125, v124 offset:16896
.LBB0_594:
	s_or_b64 exec, exec, s[0:1]
	s_bcnt1_i32_b64 s0, s[52:53]
	v_mbcnt_lo_u32_b32 v124, vcc_lo, 0
	s_add_i32 s4, s4, s0
	v_mbcnt_hi_u32_b32 v124, vcc_hi, v124
	v_add_u32_e32 v124, s4, v124
	s_movk_i32 s0, 0x100
	v_cmp_gt_i32_e64 s[0:1], s0, v124
	s_and_b64 s[52:53], vcc, s[0:1]
	s_and_saveexec_b64 s[0:1], s[52:53]
	v_lshl_add_u32 v124, v124, 2, s8
	v_add_u32_e32 v125, 0x1dc0, v0
	ds_write_b32 v124, v125 offset:16896
	s_or_b64 exec, exec, s[0:1]
	s_bcnt1_i32_b64 s0, s[54:55]
	s_add_i32 s56, s56, s0
	v_cmp_gt_u32_e64 s[54:55], v9, v123
	v_cmp_eq_u32_e64 s[52:53], v9, v123
	s_and_saveexec_b64 s[0:1], s[54:55]
	s_cbranch_execz .LBB0_598
	s_lshl_b32 s57, s56, 2
	v_mbcnt_lo_u32_b32 v125, s54, 0
	s_add_i32 s57, s8, s57
	v_mbcnt_hi_u32_b32 v125, s55, v125
	v_add_u32_e32 v124, 0x1e00, v0
	v_lshl_add_u32 v125, v125, 2, s57
	ds_write_b32 v125, v124 offset:16896
.LBB0_598:
	s_or_b64 exec, exec, s[0:1]
	s_bcnt1_i32_b64 s0, vcc
	v_mbcnt_lo_u32_b32 v124, s52, 0
	s_add_i32 s4, s4, s0
	v_mbcnt_hi_u32_b32 v124, s53, v124
	v_add_u32_e32 v124, s4, v124
	s_movk_i32 s0, 0x100
	v_cmp_gt_i32_e32 vcc, s0, v124
	s_and_b64 s[58:59], s[52:53], vcc
	s_and_saveexec_b64 s[0:1], s[58:59]
	v_lshl_add_u32 v124, v124, 2, s8
	v_add_u32_e32 v125, 0x1e00, v0
	ds_write_b32 v124, v125 offset:16896
	s_or_b64 exec, exec, s[0:1]
	s_bcnt1_i32_b64 s0, s[54:55]
	s_add_i32 s56, s56, s0
	v_cmp_gt_u32_e64 s[54:55], v8, v123
	v_cmp_eq_u32_e32 vcc, v8, v123
	s_and_saveexec_b64 s[0:1], s[54:55]
	s_cbranch_execz .LBB0_602
	s_lshl_b32 s57, s56, 2
	v_mbcnt_lo_u32_b32 v125, s54, 0
	s_add_i32 s57, s8, s57
	v_mbcnt_hi_u32_b32 v125, s55, v125
	v_add_u32_e32 v124, 0x1e40, v0
	v_lshl_add_u32 v125, v125, 2, s57
	ds_write_b32 v125, v124 offset:16896
.LBB0_602:
	s_or_b64 exec, exec, s[0:1]
	s_bcnt1_i32_b64 s0, s[52:53]
	v_mbcnt_lo_u32_b32 v124, vcc_lo, 0
	s_add_i32 s4, s4, s0
	v_mbcnt_hi_u32_b32 v124, vcc_hi, v124
	v_add_u32_e32 v124, s4, v124
	s_movk_i32 s0, 0x100
	v_cmp_gt_i32_e64 s[0:1], s0, v124
	s_and_b64 s[52:53], vcc, s[0:1]
	s_and_saveexec_b64 s[0:1], s[52:53]
	v_lshl_add_u32 v124, v124, 2, s8
	v_add_u32_e32 v125, 0x1e40, v0
	ds_write_b32 v124, v125 offset:16896
	s_or_b64 exec, exec, s[0:1]
	s_bcnt1_i32_b64 s0, s[54:55]
	s_add_i32 s56, s56, s0
	v_cmp_gt_u32_e64 s[54:55], v7, v123
	v_cmp_eq_u32_e64 s[52:53], v7, v123
	s_and_saveexec_b64 s[0:1], s[54:55]
	s_cbranch_execz .LBB0_606
	s_lshl_b32 s57, s56, 2
	v_mbcnt_lo_u32_b32 v125, s54, 0
	s_add_i32 s57, s8, s57
	v_mbcnt_hi_u32_b32 v125, s55, v125
	v_add_u32_e32 v124, 0x1e80, v0
	v_lshl_add_u32 v125, v125, 2, s57
	ds_write_b32 v125, v124 offset:16896
; __device__ __forceinline__ void topk_row(const Params& p, int r, int lane, __attribute__((address_space(3))) int* out) {
;     ...
;     int base_gt = 0, base_eq = cgt;
; #pragma unroll
;     for (int blk = 0; blk < 8; ++blk) {
;       if (blk * 16 < nch) {
; #pragma unroll
;         for (int ii = 0; ii < 16; ++ii) {
;           const int i = blk * 16 + ii;
;           const bool g = key[i] > Tv, e = key[i] == Tv;
;           const unsigned long long mg = __ballot(g), me = __ballot(e);
;           const int pg = base_gt + mbcnt64(mg);
;           if (g) out[pg] = i * 64 + lo;
;           base_gt += __popcll(mg);
;           const int pe = base_eq + mbcnt64(me);
;           if (e && pe < 256) out[pe] = i * 64 + lo;
;           base_eq += __popcll(me);
;         }
;       }
;     }
.LBB0_606:
	s_or_b64 exec, exec, s[0:1]
	s_bcnt1_i32_b64 s0, vcc
	v_mbcnt_lo_u32_b32 v124, s52, 0
	s_add_i32 s4, s4, s0
	v_mbcnt_hi_u32_b32 v124, s53, v124
	v_add_u32_e32 v124, s4, v124
	s_movk_i32 s0, 0x100
	v_cmp_gt_i32_e32 vcc, s0, v124
	s_and_b64 s[58:59], s[52:53], vcc
	s_and_saveexec_b64 s[0:1], s[58:59]
	v_lshl_add_u32 v124, v124, 2, s8
	v_add_u32_e32 v125, 0x1e80, v0
	ds_write_b32 v124, v125 offset:16896
	s_or_b64 exec, exec, s[0:1]
	s_bcnt1_i32_b64 s0, s[54:55]
	s_add_i32 s56, s56, s0
	v_cmp_gt_u32_e64 s[54:55], v6, v123
	v_cmp_eq_u32_e32 vcc, v6, v123
	s_and_saveexec_b64 s[0:1], s[54:55]
	s_cbranch_execz .LBB0_610
	s_lshl_b32 s57, s56, 2
	v_mbcnt_lo_u32_b32 v125, s54, 0
	s_add_i32 s57, s8, s57
	v_mbcnt_hi_u32_b32 v125, s55, v125
	v_add_u32_e32 v124, 0x1ec0, v0
	v_lshl_add_u32 v125, v125, 2, s57
	ds_write_b32 v125, v124 offset:16896
.LBB0_610:
	s_or_b64 exec, exec, s[0:1]
	s_bcnt1_i32_b64 s0, s[52:53]
	v_mbcnt_lo_u32_b32 v124, vcc_lo, 0
	s_add_i32 s4, s4, s0
	v_mbcnt_hi_u32_b32 v124, vcc_hi, v124
	v_add_u32_e32 v124, s4, v124
	s_movk_i32 s0, 0x100
	v_cmp_gt_i32_e64 s[0:1], s0, v124
	s_and_b64 s[52:53], vcc, s[0:1]
	s_and_saveexec_b64 s[0:1], s[52:53]
	v_lshl_add_u32 v124, v124, 2, s8
	v_add_u32_e32 v125, 0x1ec0, v0
	ds_write_b32 v124, v125 offset:16896
	s_or_b64 exec, exec, s[0:1]
	s_bcnt1_i32_b64 s0, s[54:55]
	s_add_i32 s56, s56, s0
	v_cmp_gt_u32_e64 s[54:55], v5, v123
	v_cmp_eq_u32_e64 s[52:53], v5, v123
	s_and_saveexec_b64 s[0:1], s[54:55]
	s_cbranch_execz .LBB0_614
	s_lshl_b32 s57, s56, 2
	v_mbcnt_lo_u32_b32 v125, s54, 0
	s_add_i32 s57, s8, s57
	v_mbcnt_hi_u32_b32 v125, s55, v125
	v_add_u32_e32 v124, 0x1f00, v0
	v_lshl_add_u32 v125, v125, 2, s57
	ds_write_b32 v125, v124 offset:16896
.LBB0_614:
	s_or_b64 exec, exec, s[0:1]
	s_bcnt1_i32_b64 s0, vcc
	v_mbcnt_lo_u32_b32 v124, s52, 0
	s_add_i32 s4, s4, s0
	v_mbcnt_hi_u32_b32 v124, s53, v124
	v_add_u32_e32 v124, s4, v124
	s_movk_i32 s0, 0x100
	v_cmp_gt_i32_e32 vcc, s0, v124
	s_and_b64 s[58:59], s[52:53], vcc
	s_and_saveexec_b64 s[0:1], s[58:59]
	v_lshl_add_u32 v124, v124, 2, s8
	v_add_u32_e32 v125, 0x1f00, v0
	ds_write_b32 v124, v125 offset:16896
	s_or_b64 exec, exec, s[0:1]
	s_bcnt1_i32_b64 s0, s[54:55]
	s_add_i32 s56, s56, s0
	v_cmp_gt_u32_e32 vcc, v3, v123
	v_cmp_eq_u32_e64 s[54:55], v3, v123
	s_and_saveexec_b64 s[0:1], vcc
	s_cbranch_execz .LBB0_618
	s_lshl_b32 s57, s56, 2
	v_mbcnt_lo_u32_b32 v125, vcc_lo, 0
	s_add_i32 s57, s8, s57
	v_mbcnt_hi_u32_b32 v125, vcc_hi, v125
	v_add_u32_e32 v124, 0x1f40, v0
	v_lshl_add_u32 v125, v125, 2, s57
	ds_write_b32 v125, v124 offset:16896
.LBB0_618:
	s_or_b64 exec, exec, s[0:1]
	s_bcnt1_i32_b64 s0, s[52:53]
	v_mbcnt_lo_u32_b32 v124, s54, 0
	s_add_i32 s58, s4, s0
	v_mbcnt_hi_u32_b32 v124, s55, v124
	v_add_u32_e32 v124, s58, v124
	s_movk_i32 s0, 0x100
	v_cmp_gt_i32_e64 s[0:1], s0, v124
	s_and_b64 s[52:53], s[54:55], s[0:1]
	s_and_saveexec_b64 s[0:1], s[52:53]
	v_lshl_add_u32 v124, v124, 2, s8
	v_add_u32_e32 v125, 0x1f40, v0
	ds_write_b32 v124, v125 offset:16896
	s_or_b64 exec, exec, s[0:1]
	s_bcnt1_i32_b64 s0, vcc
	s_add_i32 s4, s56, s0
	v_cmp_gt_u32_e64 s[52:53], v2, v123
	v_cmp_eq_u32_e32 vcc, v2, v123
	s_and_saveexec_b64 s[0:1], s[52:53]
	s_cbranch_execz .LBB0_622
	s_lshl_b32 s56, s4, 2
	v_mbcnt_lo_u32_b32 v125, s52, 0
	s_add_i32 s56, s8, s56
	v_mbcnt_hi_u32_b32 v125, s53, v125
	v_add_u32_e32 v124, 0x1f80, v0
	v_lshl_add_u32 v125, v125, 2, s56
	ds_write_b32 v125, v124 offset:16896
.LBB0_622:
	s_or_b64 exec, exec, s[0:1]
	s_bcnt1_i32_b64 s0, s[54:55]
	v_mbcnt_lo_u32_b32 v124, vcc_lo, 0
	s_add_i32 s58, s58, s0
	v_mbcnt_hi_u32_b32 v124, vcc_hi, v124
	v_add_u32_e32 v124, s58, v124
	s_movk_i32 s0, 0x100
	v_cmp_gt_i32_e64 s[0:1], s0, v124
	s_and_b64 s[54:55], vcc, s[0:1]
	s_and_saveexec_b64 s[0:1], s[54:55]
	v_lshl_add_u32 v124, v124, 2, s8
	v_add_u32_e32 v125, 0x1f80, v0
	ds_write_b32 v124, v125 offset:16896
	s_or_b64 exec, exec, s[0:1]
	v_cmp_gt_u32_e64 s[54:55], v1, v123
	v_cmp_eq_u32_e64 s[0:1], v1, v123
	s_and_saveexec_b64 s[56:57], s[54:55]
	s_cbranch_execz .LBB0_626
	s_bcnt1_i32_b64 s52, s[52:53]
	s_lshl_b32 s4, s4, 2
	s_add_i32 s4, s8, s4
	s_lshl_b32 s52, s52, 2
	v_mbcnt_lo_u32_b32 v124, s54, 0
	s_add_i32 s4, s4, s52
	v_mbcnt_hi_u32_b32 v124, s55, v124
	v_add_u32_e32 v123, 0x1fc0, v0
	v_lshl_add_u32 v124, v124, 2, s4
	ds_write_b32 v124, v123 offset:16896
.LBB0_626:
	s_or_b64 exec, exec, s[56:57]
	s_bcnt1_i32_b64 s4, vcc
	v_mbcnt_lo_u32_b32 v123, s0, 0
	s_add_i32 s58, s58, s4
	v_mbcnt_hi_u32_b32 v123, s1, v123
	v_add_u32_e32 v123, s58, v123
	s_movk_i32 s4, 0x100
	v_cmp_gt_i32_e32 vcc, s4, v123
	s_and_b64 s[52:53], s[0:1], vcc
	s_and_saveexec_b64 s[0:1], s[52:53]
	v_lshl_add_u32 v123, v123, 2, s8
	v_add_u32_e32 v124, 0x1fc0, v0
	ds_write_b32 v123, v124 offset:16896
	s_or_b64 exec, exec, s[0:1]

; __device__ __forceinline__ void topk_row(const Params& p, int r, int lane, __attribute__((address_space(3))) int* out) {
;     ...
;     if (exact) {
;       int base = 0;
; #pragma unroll
;       for (int blk = 0; blk < 8; ++blk) {
;         if (blk * 16 < nch) {
; #pragma unroll
;           for (int ii = 0; ii < 16; ++ii) {
;             const int i = blk * 16 + ii;
;             const bool g = key[i] >= Tv;
;             const unsigned long long mg = __ballot(g);
;             if (g) out[base + mbcnt64(mg)] = i * 64 + lo;
;             base += __popcll(mg);
;           }
;         }
;       }
;       return;
.LBB0_630:
	s_and_b64 vcc, exec, s[0:1]
	s_cbranch_vccz .LBB0_901
	v_cndmask_b32_e64 v123, 0, 1, s[50:51]
	v_cmp_ne_u32_e32 vcc, 0, v123
	s_and_saveexec_b64 s[0:1], s[50:51]
	s_nop 0
	v_mbcnt_lo_u32_b32 v123, vcc_lo, 0
	v_mbcnt_hi_u32_b32 v123, vcc_hi, v123
	v_lshl_add_u32 v123, v123, 2, s8
	ds_write_b32 v123, v0 offset:16896
	s_or_b64 exec, exec, s[0:1]
	s_bcnt1_i32_b64 s4, vcc
	v_cmp_ne_u32_e32 vcc, 0, v122
	s_and_saveexec_b64 s[0:1], s[48:49]
	s_cbranch_execz .LBB0_635
	s_lshl_b32 s48, s4, 2
	v_mbcnt_lo_u32_b32 v123, vcc_lo, 0
	s_add_i32 s48, s8, s48
	v_mbcnt_hi_u32_b32 v123, vcc_hi, v123
	v_add_u32_e32 v122, 64, v0
	v_lshl_add_u32 v123, v123, 2, s48
	ds_write_b32 v123, v122 offset:16896
.LBB0_635:
	s_or_b64 exec, exec, s[0:1]
	s_bcnt1_i32_b64 s0, vcc
	s_add_i32 s4, s0, s4
	v_cmp_ne_u32_e32 vcc, 0, v121
	s_and_saveexec_b64 s[0:1], s[46:47]
	v_readlane_b32 s48, v245, 42
	v_readlane_b32 s50, v245, 44
	v_readlane_b32 s49, v245, 43
	v_readlane_b32 s51, v245, 45
	s_cbranch_execz .LBB0_637
	s_lshl_b32 s46, s4, 2
	v_mbcnt_lo_u32_b32 v122, vcc_lo, 0
	s_add_i32 s46, s8, s46
	v_mbcnt_hi_u32_b32 v122, vcc_hi, v122
	v_add_u32_e32 v121, 0x80, v0
	v_lshl_add_u32 v122, v122, 2, s46
	ds_write_b32 v122, v121 offset:16896
.LBB0_637:
	s_or_b64 exec, exec, s[0:1]
	s_bcnt1_i32_b64 s0, vcc
	v_cndmask_b32_e64 v121, 0, 1, s[44:45]
	s_add_i32 s4, s4, s0
	v_cmp_ne_u32_e32 vcc, 0, v121
	s_and_saveexec_b64 s[0:1], s[44:45]
	s_cbranch_execz .LBB0_639
	s_lshl_b32 s44, s4, 2
	v_mbcnt_lo_u32_b32 v122, vcc_lo, 0
	s_add_i32 s44, s8, s44
	v_mbcnt_hi_u32_b32 v122, vcc_hi, v122
	v_add_u32_e32 v121, 0xc0, v0
	v_lshl_add_u32 v122, v122, 2, s44
	ds_write_b32 v122, v121 offset:16896
.LBB0_639:
	s_or_b64 exec, exec, s[0:1]
	s_bcnt1_i32_b64 s0, vcc
	s_add_i32 s4, s4, s0
	v_cmp_ne_u32_e32 vcc, 0, v120
	s_and_saveexec_b64 s[0:1], s[42:43]
	s_cbranch_execz .LBB0_641
	s_lshl_b32 s42, s4, 2
	v_mbcnt_lo_u32_b32 v121, vcc_lo, 0
	s_add_i32 s42, s8, s42
	v_mbcnt_hi_u32_b32 v121, vcc_hi, v121
	v_add_u32_e32 v120, 0x100, v0
	v_lshl_add_u32 v121, v121, 2, s42
	ds_write_b32 v121, v120 offset:16896
.LBB0_641:
	s_or_b64 exec, exec, s[0:1]
	s_bcnt1_i32_b64 s0, vcc
	v_cndmask_b32_e64 v120, 0, 1, s[40:41]
	s_add_i32 s4, s4, s0
	v_cmp_ne_u32_e32 vcc, 0, v120
	s_and_saveexec_b64 s[0:1], s[40:41]
	s_cbranch_execz .LBB0_643
	s_lshl_b32 s40, s4, 2
	v_mbcnt_lo_u32_b32 v121, vcc_lo, 0
	s_add_i32 s40, s8, s40
	v_mbcnt_hi_u32_b32 v121, vcc_hi, v121
	v_add_u32_e32 v120, 0x140, v0
	v_lshl_add_u32 v121, v121, 2, s40
	ds_write_b32 v121, v120 offset:16896
.LBB0_643:
	s_or_b64 exec, exec, s[0:1]
	s_bcnt1_i32_b64 s0, vcc
	s_add_i32 s4, s4, s0
	v_cmp_ne_u32_e32 vcc, 0, v119
	s_and_saveexec_b64 s[0:1], s[38:39]
	s_cbranch_execz .LBB0_645
	s_lshl_b32 s38, s4, 2
	v_mbcnt_lo_u32_b32 v120, vcc_lo, 0
	s_add_i32 s38, s8, s38
	v_mbcnt_hi_u32_b32 v120, vcc_hi, v120
	v_add_u32_e32 v119, 0x180, v0
	v_lshl_add_u32 v120, v120, 2, s38
	ds_write_b32 v120, v119 offset:16896
.LBB0_645:
	s_or_b64 exec, exec, s[0:1]
	s_bcnt1_i32_b64 s0, vcc
	v_cndmask_b32_e64 v119, 0, 1, s[36:37]
	s_add_i32 s4, s4, s0
	v_cmp_ne_u32_e32 vcc, 0, v119
	s_and_saveexec_b64 s[0:1], s[36:37]
	s_cbranch_execz .LBB0_647
	s_lshl_b32 s36, s4, 2
	v_mbcnt_lo_u32_b32 v120, vcc_lo, 0
	s_add_i32 s36, s8, s36
	v_mbcnt_hi_u32_b32 v120, vcc_hi, v120
	v_add_u32_e32 v119, 0x1c0, v0
	v_lshl_add_u32 v120, v120, 2, s36
	ds_write_b32 v120, v119 offset:16896
.LBB0_647:
	s_or_b64 exec, exec, s[0:1]
	s_bcnt1_i32_b64 s0, vcc
	s_add_i32 s4, s4, s0
	v_cmp_ne_u32_e32 vcc, 0, v118
	s_and_saveexec_b64 s[0:1], s[34:35]
	s_cbranch_execz .LBB0_649
	s_lshl_b32 s34, s4, 2
	v_mbcnt_lo_u32_b32 v119, vcc_lo, 0
	s_add_i32 s34, s8, s34
	v_mbcnt_hi_u32_b32 v119, vcc_hi, v119
	v_add_u32_e32 v118, 0x200, v0
	v_lshl_add_u32 v119, v119, 2, s34
	ds_write_b32 v119, v118 offset:16896
.LBB0_649:
	s_or_b64 exec, exec, s[0:1]
	s_bcnt1_i32_b64 s0, vcc
	v_cndmask_b32_e64 v118, 0, 1, s[30:31]
	s_add_i32 s4, s4, s0
	v_cmp_ne_u32_e32 vcc, 0, v118
	s_and_saveexec_b64 s[0:1], s[30:31]
	s_cbranch_execz .LBB0_651
	s_lshl_b32 s30, s4, 2
	v_mbcnt_lo_u32_b32 v119, vcc_lo, 0
	s_add_i32 s30, s8, s30
	v_mbcnt_hi_u32_b32 v119, vcc_hi, v119
	v_add_u32_e32 v118, 0x240, v0
	v_lshl_add_u32 v119, v119, 2, s30
	ds_write_b32 v119, v118 offset:16896
.LBB0_651:
	s_or_b64 exec, exec, s[0:1]
	s_bcnt1_i32_b64 s0, vcc
	s_add_i32 s4, s4, s0
	v_cmp_ne_u32_e32 vcc, 0, v117
	s_and_saveexec_b64 s[0:1], s[28:29]
	s_cbranch_execz .LBB0_653
	s_lshl_b32 s28, s4, 2
	v_mbcnt_lo_u32_b32 v118, vcc_lo, 0
	s_add_i32 s28, s8, s28
	v_mbcnt_hi_u32_b32 v118, vcc_hi, v118
	v_add_u32_e32 v117, 0x280, v0
	v_lshl_add_u32 v118, v118, 2, s28
	ds_write_b32 v118, v117 offset:16896
.LBB0_653:
	s_or_b64 exec, exec, s[0:1]
	s_bcnt1_i32_b64 s0, vcc
	v_cndmask_b32_e64 v117, 0, 1, s[26:27]
	s_add_i32 s4, s4, s0
	v_cmp_ne_u32_e32 vcc, 0, v117
	s_and_saveexec_b64 s[0:1], s[26:27]
	s_cbranch_execz .LBB0_655
	s_lshl_b32 s26, s4, 2
	v_mbcnt_lo_u32_b32 v118, vcc_lo, 0
	s_add_i32 s26, s8, s26
	v_mbcnt_hi_u32_b32 v118, vcc_hi, v118
	v_add_u32_e32 v117, 0x2c0, v0
	v_lshl_add_u32 v118, v118, 2, s26
	ds_write_b32 v118, v117 offset:16896
.LBB0_655:
	s_or_b64 exec, exec, s[0:1]
	s_bcnt1_i32_b64 s0, vcc
	s_add_i32 s4, s4, s0
	v_cmp_ne_u32_e32 vcc, 0, v116
	s_and_saveexec_b64 s[0:1], s[24:25]
	s_cbranch_execz .LBB0_657
	s_lshl_b32 s24, s4, 2
	v_mbcnt_lo_u32_b32 v117, vcc_lo, 0
	s_add_i32 s24, s8, s24
	v_mbcnt_hi_u32_b32 v117, vcc_hi, v117
	v_add_u32_e32 v116, 0x300, v0
	v_lshl_add_u32 v117, v117, 2, s24
	ds_write_b32 v117, v116 offset:16896
; __device__ __forceinline__ void topk_row(const Params& p, int r, int lane, __attribute__((address_space(3))) int* out) {
;     ...
;     if (exact) {
;       int base = 0;
; #pragma unroll
;       for (int blk = 0; blk < 8; ++blk) {
;         if (blk * 16 < nch) {
; #pragma unroll
;           for (int ii = 0; ii < 16; ++ii) {
;             const int i = blk * 16 + ii;
;             const bool g = key[i] >= Tv;
;             const unsigned long long mg = __ballot(g);
;             if (g) out[base + mbcnt64(mg)] = i * 64 + lo;
;             base += __popcll(mg);
;           }
;         }
;       }
;       return;
.LBB0_657:
	s_or_b64 exec, exec, s[0:1]
	s_bcnt1_i32_b64 s0, vcc
	v_cndmask_b32_e64 v116, 0, 1, s[22:23]
	s_add_i32 s4, s4, s0
	v_cmp_ne_u32_e32 vcc, 0, v116
	s_and_saveexec_b64 s[0:1], s[22:23]
	s_cbranch_execz .LBB0_659
	s_lshl_b32 s22, s4, 2
	v_mbcnt_lo_u32_b32 v117, vcc_lo, 0
	s_add_i32 s22, s8, s22
	v_mbcnt_hi_u32_b32 v117, vcc_hi, v117
	v_add_u32_e32 v116, 0x340, v0
	v_lshl_add_u32 v117, v117, 2, s22
	ds_write_b32 v117, v116 offset:16896
.LBB0_659:
	s_or_b64 exec, exec, s[0:1]
	s_bcnt1_i32_b64 s0, vcc
	s_add_i32 s4, s4, s0
	v_cmp_ne_u32_e32 vcc, 0, v115
	s_and_saveexec_b64 s[0:1], s[20:21]
	s_cbranch_execz .LBB0_661
	s_lshl_b32 s20, s4, 2
	v_mbcnt_lo_u32_b32 v116, vcc_lo, 0
	s_add_i32 s20, s8, s20
	v_mbcnt_hi_u32_b32 v116, vcc_hi, v116
	v_add_u32_e32 v115, 0x380, v0
	v_lshl_add_u32 v116, v116, 2, s20
	ds_write_b32 v116, v115 offset:16896
.LBB0_661:
	s_or_b64 exec, exec, s[0:1]
	s_bcnt1_i32_b64 s0, vcc
	v_cndmask_b32_e64 v115, 0, 1, s[18:19]
	s_add_i32 s4, s4, s0
	v_cmp_ne_u32_e32 vcc, 0, v115
	s_and_saveexec_b64 s[0:1], s[18:19]
	s_cbranch_execz .LBB0_663
	s_lshl_b32 s18, s4, 2
	v_mbcnt_lo_u32_b32 v116, vcc_lo, 0
	s_add_i32 s18, s8, s18
	v_mbcnt_hi_u32_b32 v116, vcc_hi, v116
	v_add_u32_e32 v115, 0x3c0, v0
	v_lshl_add_u32 v116, v116, 2, s18
	ds_write_b32 v116, v115 offset:16896
.LBB0_663:
	s_or_b64 exec, exec, s[0:1]
	s_bcnt1_i32_b64 s0, vcc
	s_and_b64 vcc, exec, s[16:17]
	s_add_i32 s4, s4, s0
	s_cbranch_vccnz .LBB0_697
	v_cmp_ge_u32_e32 vcc, v114, v4
	s_and_saveexec_b64 s[0:1], vcc
	s_cbranch_execz .LBB0_666
	s_lshl_b32 s16, s4, 2
	v_mbcnt_lo_u32_b32 v115, vcc_lo, 0
	s_add_i32 s16, s8, s16
	v_mbcnt_hi_u32_b32 v115, vcc_hi, v115
	v_add_u32_e32 v114, 0x400, v0
	v_lshl_add_u32 v115, v115, 2, s16
	ds_write_b32 v115, v114 offset:16896
.LBB0_666:
	s_or_b64 exec, exec, s[0:1]
	s_bcnt1_i32_b64 s0, vcc
	s_add_i32 s4, s4, s0
	v_cmp_ge_u32_e32 vcc, v113, v4
	s_and_saveexec_b64 s[0:1], vcc
	s_cbranch_execz .LBB0_668
	s_lshl_b32 s16, s4, 2
	v_mbcnt_lo_u32_b32 v114, vcc_lo, 0
	s_add_i32 s16, s8, s16
	v_mbcnt_hi_u32_b32 v114, vcc_hi, v114
	v_add_u32_e32 v113, 0x440, v0
	v_lshl_add_u32 v114, v114, 2, s16
	ds_write_b32 v114, v113 offset:16896
.LBB0_668:
	s_or_b64 exec, exec, s[0:1]
	s_bcnt1_i32_b64 s0, vcc
	s_add_i32 s4, s4, s0
	v_cmp_ge_u32_e32 vcc, v112, v4
	s_and_saveexec_b64 s[0:1], vcc
	s_cbranch_execz .LBB0_670
	s_lshl_b32 s16, s4, 2
	v_mbcnt_lo_u32_b32 v113, vcc_lo, 0
	s_add_i32 s16, s8, s16
	v_mbcnt_hi_u32_b32 v113, vcc_hi, v113
	v_add_u32_e32 v112, 0x480, v0
	v_lshl_add_u32 v113, v113, 2, s16
	ds_write_b32 v113, v112 offset:16896
.LBB0_670:
	s_or_b64 exec, exec, s[0:1]
	s_bcnt1_i32_b64 s0, vcc
	s_add_i32 s4, s4, s0
	v_cmp_ge_u32_e32 vcc, v111, v4
	s_and_saveexec_b64 s[0:1], vcc
	s_cbranch_execz .LBB0_672
	s_lshl_b32 s16, s4, 2
	v_mbcnt_lo_u32_b32 v112, vcc_lo, 0
	s_add_i32 s16, s8, s16
	v_mbcnt_hi_u32_b32 v112, vcc_hi, v112
	v_add_u32_e32 v111, 0x4c0, v0
	v_lshl_add_u32 v112, v112, 2, s16
	ds_write_b32 v112, v111 offset:16896
.LBB0_672:
	s_or_b64 exec, exec, s[0:1]
	s_bcnt1_i32_b64 s0, vcc
	s_add_i32 s4, s4, s0
	v_cmp_ge_u32_e32 vcc, v110, v4
	s_and_saveexec_b64 s[0:1], vcc
	s_cbranch_execz .LBB0_674
	s_lshl_b32 s16, s4, 2
	v_mbcnt_lo_u32_b32 v111, vcc_lo, 0
	s_add_i32 s16, s8, s16
	v_mbcnt_hi_u32_b32 v111, vcc_hi, v111
	v_add_u32_e32 v110, 0x500, v0
	v_lshl_add_u32 v111, v111, 2, s16
	ds_write_b32 v111, v110 offset:16896
.LBB0_674:
	s_or_b64 exec, exec, s[0:1]
	s_bcnt1_i32_b64 s0, vcc
	s_add_i32 s4, s4, s0
	v_cmp_ge_u32_e32 vcc, v109, v4
	s_and_saveexec_b64 s[0:1], vcc
	s_cbranch_execz .LBB0_676
	s_lshl_b32 s16, s4, 2
	v_mbcnt_lo_u32_b32 v110, vcc_lo, 0
	s_add_i32 s16, s8, s16
	v_mbcnt_hi_u32_b32 v110, vcc_hi, v110
	v_add_u32_e32 v109, 0x540, v0
	v_lshl_add_u32 v110, v110, 2, s16
	ds_write_b32 v110, v109 offset:16896
; __device__ __forceinline__ void topk_row(const Params& p, int r, int lane, __attribute__((address_space(3))) int* out) {
;     ...
;     if (exact) {
;       int base = 0;
; #pragma unroll
;       for (int blk = 0; blk < 8; ++blk) {
;         if (blk * 16 < nch) {
; #pragma unroll
;           for (int ii = 0; ii < 16; ++ii) {
;             const int i = blk * 16 + ii;
;             const bool g = key[i] >= Tv;
;             const unsigned long long mg = __ballot(g);
;             if (g) out[base + mbcnt64(mg)] = i * 64 + lo;
;             base += __popcll(mg);
;           }
;         }
;       }
;       return;
.LBB0_676:
	s_or_b64 exec, exec, s[0:1]
	s_bcnt1_i32_b64 s0, vcc
	s_add_i32 s4, s4, s0
	v_cmp_ge_u32_e32 vcc, v108, v4
	s_and_saveexec_b64 s[0:1], vcc
	s_cbranch_execz .LBB0_678
	s_lshl_b32 s16, s4, 2
	v_mbcnt_lo_u32_b32 v109, vcc_lo, 0
	s_add_i32 s16, s8, s16
	v_mbcnt_hi_u32_b32 v109, vcc_hi, v109
	v_add_u32_e32 v108, 0x580, v0
	v_lshl_add_u32 v109, v109, 2, s16
	ds_write_b32 v109, v108 offset:16896
.LBB0_678:
	s_or_b64 exec, exec, s[0:1]
	s_bcnt1_i32_b64 s0, vcc
	s_add_i32 s4, s4, s0
	v_cmp_ge_u32_e32 vcc, v107, v4
	s_and_saveexec_b64 s[0:1], vcc
	s_cbranch_execz .LBB0_680
	s_lshl_b32 s16, s4, 2
	v_mbcnt_lo_u32_b32 v108, vcc_lo, 0
	s_add_i32 s16, s8, s16
	v_mbcnt_hi_u32_b32 v108, vcc_hi, v108
	v_add_u32_e32 v107, 0x5c0, v0
	v_lshl_add_u32 v108, v108, 2, s16
	ds_write_b32 v108, v107 offset:16896
.LBB0_680:
	s_or_b64 exec, exec, s[0:1]
	s_bcnt1_i32_b64 s0, vcc
	s_add_i32 s4, s4, s0
	v_cmp_ge_u32_e32 vcc, v106, v4
	s_and_saveexec_b64 s[0:1], vcc
	s_cbranch_execz .LBB0_682
	s_lshl_b32 s16, s4, 2
	v_mbcnt_lo_u32_b32 v107, vcc_lo, 0
	s_add_i32 s16, s8, s16
	v_mbcnt_hi_u32_b32 v107, vcc_hi, v107
	v_add_u32_e32 v106, 0x600, v0
	v_lshl_add_u32 v107, v107, 2, s16
	ds_write_b32 v107, v106 offset:16896
.LBB0_682:
	s_or_b64 exec, exec, s[0:1]
	s_bcnt1_i32_b64 s0, vcc
	s_add_i32 s4, s4, s0
	v_cmp_ge_u32_e32 vcc, v105, v4
	s_and_saveexec_b64 s[0:1], vcc
	s_cbranch_execz .LBB0_684
	s_lshl_b32 s16, s4, 2
	v_mbcnt_lo_u32_b32 v106, vcc_lo, 0
	s_add_i32 s16, s8, s16
	v_mbcnt_hi_u32_b32 v106, vcc_hi, v106
	v_add_u32_e32 v105, 0x640, v0
	v_lshl_add_u32 v106, v106, 2, s16
	ds_write_b32 v106, v105 offset:16896
.LBB0_684:
	s_or_b64 exec, exec, s[0:1]
	s_bcnt1_i32_b64 s0, vcc
	s_add_i32 s4, s4, s0
	v_cmp_ge_u32_e32 vcc, v104, v4
	s_and_saveexec_b64 s[0:1], vcc
	s_cbranch_execz .LBB0_686
	s_lshl_b32 s16, s4, 2
	v_mbcnt_lo_u32_b32 v105, vcc_lo, 0
	s_add_i32 s16, s8, s16
	v_mbcnt_hi_u32_b32 v105, vcc_hi, v105
	v_add_u32_e32 v104, 0x680, v0
	v_lshl_add_u32 v105, v105, 2, s16
	ds_write_b32 v105, v104 offset:16896
.LBB0_686:
	s_or_b64 exec, exec, s[0:1]
	s_bcnt1_i32_b64 s0, vcc
	s_add_i32 s4, s4, s0
	v_cmp_ge_u32_e32 vcc, v103, v4
	s_and_saveexec_b64 s[0:1], vcc
	s_cbranch_execz .LBB0_688
	s_lshl_b32 s16, s4, 2
	v_mbcnt_lo_u32_b32 v104, vcc_lo, 0
	s_add_i32 s16, s8, s16
	v_mbcnt_hi_u32_b32 v104, vcc_hi, v104
	v_add_u32_e32 v103, 0x6c0, v0
	v_lshl_add_u32 v104, v104, 2, s16
	ds_write_b32 v104, v103 offset:16896
.LBB0_688:
	s_or_b64 exec, exec, s[0:1]
	s_bcnt1_i32_b64 s0, vcc
	s_add_i32 s4, s4, s0
	v_cmp_ge_u32_e32 vcc, v102, v4
	s_and_saveexec_b64 s[0:1], vcc
	s_cbranch_execz .LBB0_690
	s_lshl_b32 s16, s4, 2
	v_mbcnt_lo_u32_b32 v103, vcc_lo, 0
	s_add_i32 s16, s8, s16
	v_mbcnt_hi_u32_b32 v103, vcc_hi, v103
	v_add_u32_e32 v102, 0x700, v0
	v_lshl_add_u32 v103, v103, 2, s16
	ds_write_b32 v103, v102 offset:16896
.LBB0_690:
	s_or_b64 exec, exec, s[0:1]
	s_bcnt1_i32_b64 s0, vcc
	s_add_i32 s4, s4, s0
	v_cmp_ge_u32_e32 vcc, v101, v4
	s_and_saveexec_b64 s[0:1], vcc
	s_cbranch_execz .LBB0_692
	s_lshl_b32 s16, s4, 2
	v_mbcnt_lo_u32_b32 v102, vcc_lo, 0
	s_add_i32 s16, s8, s16
	v_mbcnt_hi_u32_b32 v102, vcc_hi, v102
	v_add_u32_e32 v101, 0x740, v0
	v_lshl_add_u32 v102, v102, 2, s16
	ds_write_b32 v102, v101 offset:16896
.LBB0_692:
	s_or_b64 exec, exec, s[0:1]
	s_bcnt1_i32_b64 s0, vcc
	s_add_i32 s4, s4, s0
	v_cmp_ge_u32_e32 vcc, v100, v4
	s_and_saveexec_b64 s[0:1], vcc
	s_cbranch_execz .LBB0_694
	s_lshl_b32 s16, s4, 2
	v_mbcnt_lo_u32_b32 v101, vcc_lo, 0
	s_add_i32 s16, s8, s16
	v_mbcnt_hi_u32_b32 v101, vcc_hi, v101
	v_add_u32_e32 v100, 0x780, v0
	v_lshl_add_u32 v101, v101, 2, s16
	ds_write_b32 v101, v100 offset:16896
.LBB0_694:
	s_or_b64 exec, exec, s[0:1]
	s_bcnt1_i32_b64 s0, vcc
	s_add_i32 s4, s4, s0
	v_cmp_ge_u32_e32 vcc, v99, v4
	s_and_saveexec_b64 s[0:1], vcc
	s_cbranch_execz .LBB0_696
	s_lshl_b32 s16, s4, 2
	v_mbcnt_lo_u32_b32 v100, vcc_lo, 0
	s_add_i32 s16, s8, s16
	v_mbcnt_hi_u32_b32 v100, vcc_hi, v100
	v_add_u32_e32 v99, 0x7c0, v0
	v_lshl_add_u32 v100, v100, 2, s16
	ds_write_b32 v100, v99 offset:16896

; __device__ __forceinline__ void topk_row(const Params& p, int r, int lane, __attribute__((address_space(3))) int* out) {
;     ...
;     if (exact) {
;       int base = 0;
; #pragma unroll
;       for (int blk = 0; blk < 8; ++blk) {
;         if (blk * 16 < nch) {
; #pragma unroll
;           for (int ii = 0; ii < 16; ++ii) {
;             const int i = blk * 16 + ii;
;             const bool g = key[i] >= Tv;
;             const unsigned long long mg = __ballot(g);
;             if (g) out[base + mbcnt64(mg)] = i * 64 + lo;
;             base += __popcll(mg);
;           }
;         }
;       }
;       return;
.LBB0_697:
	s_and_b64 vcc, exec, s[6:7]
	s_cbranch_vccnz .LBB0_731
	v_cmp_ge_u32_e32 vcc, v98, v4
	s_and_saveexec_b64 s[0:1], vcc
	s_cbranch_execz .LBB0_700
	s_lshl_b32 s6, s4, 2
	v_mbcnt_lo_u32_b32 v99, vcc_lo, 0
	s_add_i32 s6, s8, s6
	v_mbcnt_hi_u32_b32 v99, vcc_hi, v99
	v_add_u32_e32 v98, 0x800, v0
	v_lshl_add_u32 v99, v99, 2, s6
	ds_write_b32 v99, v98 offset:16896
.LBB0_700:
	s_or_b64 exec, exec, s[0:1]
	s_bcnt1_i32_b64 s0, vcc
	s_add_i32 s4, s4, s0
	v_cmp_ge_u32_e32 vcc, v97, v4
	s_and_saveexec_b64 s[0:1], vcc
	s_cbranch_execz .LBB0_702
	s_lshl_b32 s6, s4, 2
	v_mbcnt_lo_u32_b32 v98, vcc_lo, 0
	s_add_i32 s6, s8, s6
	v_mbcnt_hi_u32_b32 v98, vcc_hi, v98
	v_add_u32_e32 v97, 0x840, v0
	v_lshl_add_u32 v98, v98, 2, s6
	ds_write_b32 v98, v97 offset:16896
.LBB0_702:
	s_or_b64 exec, exec, s[0:1]
	s_bcnt1_i32_b64 s0, vcc
	s_add_i32 s4, s4, s0
	v_cmp_ge_u32_e32 vcc, v96, v4
	s_and_saveexec_b64 s[0:1], vcc
	s_cbranch_execz .LBB0_704
	s_lshl_b32 s6, s4, 2
	v_mbcnt_lo_u32_b32 v97, vcc_lo, 0
	s_add_i32 s6, s8, s6
	v_mbcnt_hi_u32_b32 v97, vcc_hi, v97
	v_add_u32_e32 v96, 0x880, v0
	v_lshl_add_u32 v97, v97, 2, s6
	ds_write_b32 v97, v96 offset:16896
.LBB0_704:
	s_or_b64 exec, exec, s[0:1]
	s_bcnt1_i32_b64 s0, vcc
	s_add_i32 s4, s4, s0
	v_cmp_ge_u32_e32 vcc, v95, v4
	s_and_saveexec_b64 s[0:1], vcc
	s_cbranch_execz .LBB0_706
	s_lshl_b32 s6, s4, 2
	v_mbcnt_lo_u32_b32 v96, vcc_lo, 0
	s_add_i32 s6, s8, s6
	v_mbcnt_hi_u32_b32 v96, vcc_hi, v96
	v_add_u32_e32 v95, 0x8c0, v0
	v_lshl_add_u32 v96, v96, 2, s6
	ds_write_b32 v96, v95 offset:16896
.LBB0_706:
	s_or_b64 exec, exec, s[0:1]
	s_bcnt1_i32_b64 s0, vcc
	s_add_i32 s4, s4, s0
	v_cmp_ge_u32_e32 vcc, v94, v4
	s_and_saveexec_b64 s[0:1], vcc
	s_cbranch_execz .LBB0_708
	s_lshl_b32 s6, s4, 2
	v_mbcnt_lo_u32_b32 v95, vcc_lo, 0
	s_add_i32 s6, s8, s6
	v_mbcnt_hi_u32_b32 v95, vcc_hi, v95
	v_add_u32_e32 v94, 0x900, v0
	v_lshl_add_u32 v95, v95, 2, s6
	ds_write_b32 v95, v94 offset:16896
.LBB0_708:
	s_or_b64 exec, exec, s[0:1]
	s_bcnt1_i32_b64 s0, vcc
	s_add_i32 s4, s4, s0
	v_cmp_ge_u32_e32 vcc, v93, v4
	s_and_saveexec_b64 s[0:1], vcc
	s_cbranch_execz .LBB0_710
	s_lshl_b32 s6, s4, 2
	v_mbcnt_lo_u32_b32 v94, vcc_lo, 0
	s_add_i32 s6, s8, s6
	v_mbcnt_hi_u32_b32 v94, vcc_hi, v94
	v_add_u32_e32 v93, 0x940, v0
	v_lshl_add_u32 v94, v94, 2, s6
	ds_write_b32 v94, v93 offset:16896
.LBB0_710:
	s_or_b64 exec, exec, s[0:1]
	s_bcnt1_i32_b64 s0, vcc
	s_add_i32 s4, s4, s0
	v_cmp_ge_u32_e32 vcc, v92, v4
	s_and_saveexec_b64 s[0:1], vcc
	s_cbranch_execz .LBB0_712
	s_lshl_b32 s6, s4, 2
	v_mbcnt_lo_u32_b32 v93, vcc_lo, 0
	s_add_i32 s6, s8, s6
	v_mbcnt_hi_u32_b32 v93, vcc_hi, v93
	v_add_u32_e32 v92, 0x980, v0
	v_lshl_add_u32 v93, v93, 2, s6
	ds_write_b32 v93, v92 offset:16896
.LBB0_712:
	s_or_b64 exec, exec, s[0:1]
	s_bcnt1_i32_b64 s0, vcc
	s_add_i32 s4, s4, s0
	v_cmp_ge_u32_e32 vcc, v91, v4
	s_and_saveexec_b64 s[0:1], vcc
	s_cbranch_execz .LBB0_714
	s_lshl_b32 s6, s4, 2
	v_mbcnt_lo_u32_b32 v92, vcc_lo, 0
	s_add_i32 s6, s8, s6
	v_mbcnt_hi_u32_b32 v92, vcc_hi, v92
	v_add_u32_e32 v91, 0x9c0, v0
	v_lshl_add_u32 v92, v92, 2, s6
	ds_write_b32 v92, v91 offset:16896
.LBB0_714:
	s_or_b64 exec, exec, s[0:1]
	s_bcnt1_i32_b64 s0, vcc
	s_add_i32 s4, s4, s0
	v_cmp_ge_u32_e32 vcc, v90, v4
	s_and_saveexec_b64 s[0:1], vcc
	s_cbranch_execz .LBB0_716
	s_lshl_b32 s6, s4, 2
	v_mbcnt_lo_u32_b32 v91, vcc_lo, 0
	s_add_i32 s6, s8, s6
	v_mbcnt_hi_u32_b32 v91, vcc_hi, v91
	v_add_u32_e32 v90, 0xa00, v0
	v_lshl_add_u32 v91, v91, 2, s6
	ds_write_b32 v91, v90 offset:16896
.LBB0_716:
	s_or_b64 exec, exec, s[0:1]
	s_bcnt1_i32_b64 s0, vcc
	s_add_i32 s4, s4, s0
	v_cmp_ge_u32_e32 vcc, v89, v4
	s_and_saveexec_b64 s[0:1], vcc
	s_cbranch_execz .LBB0_718
	s_lshl_b32 s6, s4, 2
	v_mbcnt_lo_u32_b32 v90, vcc_lo, 0
	s_add_i32 s6, s8, s6
	v_mbcnt_hi_u32_b32 v90, vcc_hi, v90
	v_add_u32_e32 v89, 0xa40, v0
	v_lshl_add_u32 v90, v90, 2, s6
	ds_write_b32 v90, v89 offset:16896
.LBB0_718:
	s_or_b64 exec, exec, s[0:1]
	s_bcnt1_i32_b64 s0, vcc
	s_add_i32 s4, s4, s0
	v_cmp_ge_u32_e32 vcc, v88, v4
	s_and_saveexec_b64 s[0:1], vcc
	s_cbranch_execz .LBB0_720
	s_lshl_b32 s6, s4, 2
	v_mbcnt_lo_u32_b32 v89, vcc_lo, 0
	s_add_i32 s6, s8, s6
	v_mbcnt_hi_u32_b32 v89, vcc_hi, v89
	v_add_u32_e32 v88, 0xa80, v0
	v_lshl_add_u32 v89, v89, 2, s6
	ds_write_b32 v89, v88 offset:16896
.LBB0_720:
	s_or_b64 exec, exec, s[0:1]
	s_bcnt1_i32_b64 s0, vcc
	s_add_i32 s4, s4, s0
	v_cmp_ge_u32_e32 vcc, v87, v4
	s_and_saveexec_b64 s[0:1], vcc
	s_cbranch_execz .LBB0_722
	s_lshl_b32 s6, s4, 2
	v_mbcnt_lo_u32_b32 v88, vcc_lo, 0
	s_add_i32 s6, s8, s6
	v_mbcnt_hi_u32_b32 v88, vcc_hi, v88
	v_add_u32_e32 v87, 0xac0, v0
	v_lshl_add_u32 v88, v88, 2, s6
	ds_write_b32 v88, v87 offset:16896
.LBB0_722:
	s_or_b64 exec, exec, s[0:1]
	s_bcnt1_i32_b64 s0, vcc
	s_add_i32 s4, s4, s0
	v_cmp_ge_u32_e32 vcc, v86, v4
	s_and_saveexec_b64 s[0:1], vcc
	s_cbranch_execz .LBB0_724
	s_lshl_b32 s6, s4, 2
	v_mbcnt_lo_u32_b32 v87, vcc_lo, 0
	s_add_i32 s6, s8, s6
	v_mbcnt_hi_u32_b32 v87, vcc_hi, v87
	v_add_u32_e32 v86, 0xb00, v0
	v_lshl_add_u32 v87, v87, 2, s6
	ds_write_b32 v87, v86 offset:16896
.LBB0_724:
	s_or_b64 exec, exec, s[0:1]
	s_bcnt1_i32_b64 s0, vcc
	s_add_i32 s4, s4, s0
	v_cmp_ge_u32_e32 vcc, v85, v4
	s_and_saveexec_b64 s[0:1], vcc
	s_cbranch_execz .LBB0_726
	s_lshl_b32 s6, s4, 2
	v_mbcnt_lo_u32_b32 v86, vcc_lo, 0
	s_add_i32 s6, s8, s6
	v_mbcnt_hi_u32_b32 v86, vcc_hi, v86
	v_add_u32_e32 v85, 0xb40, v0
	v_lshl_add_u32 v86, v86, 2, s6
	ds_write_b32 v86, v85 offset:16896
.LBB0_726:
	s_or_b64 exec, exec, s[0:1]
	s_bcnt1_i32_b64 s0, vcc
	s_add_i32 s4, s4, s0
	v_cmp_ge_u32_e32 vcc, v84, v4
	s_and_saveexec_b64 s[0:1], vcc
	s_cbranch_execz .LBB0_728
	s_lshl_b32 s6, s4, 2
	v_mbcnt_lo_u32_b32 v85, vcc_lo, 0
	s_add_i32 s6, s8, s6
	v_mbcnt_hi_u32_b32 v85, vcc_hi, v85
	v_add_u32_e32 v84, 0xb80, v0
	v_lshl_add_u32 v85, v85, 2, s6
	ds_write_b32 v85, v84 offset:16896
.LBB0_728:
	s_or_b64 exec, exec, s[0:1]
	s_bcnt1_i32_b64 s0, vcc
	s_add_i32 s4, s4, s0
	v_cmp_ge_u32_e32 vcc, v83, v4
	s_and_saveexec_b64 s[0:1], vcc
	s_cbranch_execz .LBB0_730
	s_lshl_b32 s6, s4, 2
	v_mbcnt_lo_u32_b32 v84, vcc_lo, 0
	s_add_i32 s6, s8, s6
	v_mbcnt_hi_u32_b32 v84, vcc_hi, v84
	v_add_u32_e32 v83, 0xbc0, v0
	v_lshl_add_u32 v84, v84, 2, s6
	ds_write_b32 v84, v83 offset:16896

; __device__ __forceinline__ void topk_row(const Params& p, int r, int lane, __attribute__((address_space(3))) int* out) {
;     ...
;     if (exact) {
;       int base = 0;
; #pragma unroll
;       for (int blk = 0; blk < 8; ++blk) {
;         if (blk * 16 < nch) {
; #pragma unroll
;           for (int ii = 0; ii < 16; ++ii) {
;             const int i = blk * 16 + ii;
;             const bool g = key[i] >= Tv;
;             const unsigned long long mg = __ballot(g);
;             if (g) out[base + mbcnt64(mg)] = i * 64 + lo;
;             base += __popcll(mg);
;           }
;         }
;       }
;       return;
.LBB0_731:
	v_readlane_b32 s0, v244, 2
	v_readlane_b32 s1, v244, 3
	s_and_b64 vcc, exec, s[0:1]
	s_cbranch_vccnz .LBB0_765
	v_cmp_ge_u32_e32 vcc, v82, v4
	s_and_saveexec_b64 s[0:1], vcc
	s_cbranch_execz .LBB0_734
	s_lshl_b32 s6, s4, 2
	v_mbcnt_lo_u32_b32 v83, vcc_lo, 0
	s_add_i32 s6, s8, s6
	v_mbcnt_hi_u32_b32 v83, vcc_hi, v83
	v_add_u32_e32 v82, 0xc00, v0
	v_lshl_add_u32 v83, v83, 2, s6
	ds_write_b32 v83, v82 offset:16896
.LBB0_734:
	s_or_b64 exec, exec, s[0:1]
	s_bcnt1_i32_b64 s0, vcc
	s_add_i32 s4, s4, s0
	v_cmp_ge_u32_e32 vcc, v81, v4
	s_and_saveexec_b64 s[0:1], vcc
	s_cbranch_execz .LBB0_736
	s_lshl_b32 s6, s4, 2
	v_mbcnt_lo_u32_b32 v82, vcc_lo, 0
	s_add_i32 s6, s8, s6
	v_mbcnt_hi_u32_b32 v82, vcc_hi, v82
	v_add_u32_e32 v81, 0xc40, v0
	v_lshl_add_u32 v82, v82, 2, s6
	ds_write_b32 v82, v81 offset:16896
.LBB0_736:
	s_or_b64 exec, exec, s[0:1]
	s_bcnt1_i32_b64 s0, vcc
	s_add_i32 s4, s4, s0
	v_cmp_ge_u32_e32 vcc, v80, v4
	s_and_saveexec_b64 s[0:1], vcc
	s_cbranch_execz .LBB0_738
	s_lshl_b32 s6, s4, 2
	v_mbcnt_lo_u32_b32 v81, vcc_lo, 0
	s_add_i32 s6, s8, s6
	v_mbcnt_hi_u32_b32 v81, vcc_hi, v81
	v_add_u32_e32 v80, 0xc80, v0
	v_lshl_add_u32 v81, v81, 2, s6
	ds_write_b32 v81, v80 offset:16896
.LBB0_738:
	s_or_b64 exec, exec, s[0:1]
	s_bcnt1_i32_b64 s0, vcc
	s_add_i32 s4, s4, s0
	v_cmp_ge_u32_e32 vcc, v79, v4
	s_and_saveexec_b64 s[0:1], vcc
	s_cbranch_execz .LBB0_740
	s_lshl_b32 s6, s4, 2
	v_mbcnt_lo_u32_b32 v80, vcc_lo, 0
	s_add_i32 s6, s8, s6
	v_mbcnt_hi_u32_b32 v80, vcc_hi, v80
	v_add_u32_e32 v79, 0xcc0, v0
	v_lshl_add_u32 v80, v80, 2, s6
	ds_write_b32 v80, v79 offset:16896
.LBB0_740:
	s_or_b64 exec, exec, s[0:1]
	s_bcnt1_i32_b64 s0, vcc
	s_add_i32 s4, s4, s0
	v_cmp_ge_u32_e32 vcc, v78, v4
	s_and_saveexec_b64 s[0:1], vcc
	s_cbranch_execz .LBB0_742
	s_lshl_b32 s6, s4, 2
	v_mbcnt_lo_u32_b32 v79, vcc_lo, 0
	s_add_i32 s6, s8, s6
	v_mbcnt_hi_u32_b32 v79, vcc_hi, v79
	v_add_u32_e32 v78, 0xd00, v0
	v_lshl_add_u32 v79, v79, 2, s6
	ds_write_b32 v79, v78 offset:16896
.LBB0_742:
	s_or_b64 exec, exec, s[0:1]
	s_bcnt1_i32_b64 s0, vcc
	s_add_i32 s4, s4, s0
	v_cmp_ge_u32_e32 vcc, v77, v4
	s_and_saveexec_b64 s[0:1], vcc
	s_cbranch_execz .LBB0_744
	s_lshl_b32 s6, s4, 2
	v_mbcnt_lo_u32_b32 v78, vcc_lo, 0
	s_add_i32 s6, s8, s6
	v_mbcnt_hi_u32_b32 v78, vcc_hi, v78
	v_add_u32_e32 v77, 0xd40, v0
	v_lshl_add_u32 v78, v78, 2, s6
	ds_write_b32 v78, v77 offset:16896
.LBB0_744:
	s_or_b64 exec, exec, s[0:1]
	s_bcnt1_i32_b64 s0, vcc
	s_add_i32 s4, s4, s0
	v_cmp_ge_u32_e32 vcc, v76, v4
	s_and_saveexec_b64 s[0:1], vcc
	s_cbranch_execz .LBB0_746
	s_lshl_b32 s6, s4, 2
	v_mbcnt_lo_u32_b32 v77, vcc_lo, 0
	s_add_i32 s6, s8, s6
	v_mbcnt_hi_u32_b32 v77, vcc_hi, v77
	v_add_u32_e32 v76, 0xd80, v0
	v_lshl_add_u32 v77, v77, 2, s6
	ds_write_b32 v77, v76 offset:16896
.LBB0_746:
	s_or_b64 exec, exec, s[0:1]
	s_bcnt1_i32_b64 s0, vcc
	s_add_i32 s4, s4, s0
	v_cmp_ge_u32_e32 vcc, v75, v4
	s_and_saveexec_b64 s[0:1], vcc
	s_cbranch_execz .LBB0_748
	s_lshl_b32 s6, s4, 2
	v_mbcnt_lo_u32_b32 v76, vcc_lo, 0
	s_add_i32 s6, s8, s6
	v_mbcnt_hi_u32_b32 v76, vcc_hi, v76
	v_add_u32_e32 v75, 0xdc0, v0
	v_lshl_add_u32 v76, v76, 2, s6
	ds_write_b32 v76, v75 offset:16896
.LBB0_748:
	s_or_b64 exec, exec, s[0:1]
	s_bcnt1_i32_b64 s0, vcc
	s_add_i32 s4, s4, s0
	v_cmp_ge_u32_e32 vcc, v74, v4
	s_and_saveexec_b64 s[0:1], vcc
	s_cbranch_execz .LBB0_750
	s_lshl_b32 s6, s4, 2
	v_mbcnt_lo_u32_b32 v75, vcc_lo, 0
	s_add_i32 s6, s8, s6
	v_mbcnt_hi_u32_b32 v75, vcc_hi, v75
	v_add_u32_e32 v74, 0xe00, v0
	v_lshl_add_u32 v75, v75, 2, s6
	ds_write_b32 v75, v74 offset:16896
.LBB0_750:
	s_or_b64 exec, exec, s[0:1]
	s_bcnt1_i32_b64 s0, vcc
	s_add_i32 s4, s4, s0
	v_cmp_ge_u32_e32 vcc, v73, v4
	s_and_saveexec_b64 s[0:1], vcc
	s_cbranch_execz .LBB0_752
	s_lshl_b32 s6, s4, 2
	v_mbcnt_lo_u32_b32 v74, vcc_lo, 0
	s_add_i32 s6, s8, s6
	v_mbcnt_hi_u32_b32 v74, vcc_hi, v74
	v_add_u32_e32 v73, 0xe40, v0
	v_lshl_add_u32 v74, v74, 2, s6
	ds_write_b32 v74, v73 offset:16896
.LBB0_752:
	s_or_b64 exec, exec, s[0:1]
	s_bcnt1_i32_b64 s0, vcc
	s_add_i32 s4, s4, s0
	v_cmp_ge_u32_e32 vcc, v72, v4
	s_and_saveexec_b64 s[0:1], vcc
	s_cbranch_execz .LBB0_754
	s_lshl_b32 s6, s4, 2
	v_mbcnt_lo_u32_b32 v73, vcc_lo, 0
	s_add_i32 s6, s8, s6
	v_mbcnt_hi_u32_b32 v73, vcc_hi, v73
	v_add_u32_e32 v72, 0xe80, v0
	v_lshl_add_u32 v73, v73, 2, s6
	ds_write_b32 v73, v72 offset:16896
.LBB0_754:
	s_or_b64 exec, exec, s[0:1]
	s_bcnt1_i32_b64 s0, vcc
	s_add_i32 s4, s4, s0
	v_cmp_ge_u32_e32 vcc, v71, v4
	s_and_saveexec_b64 s[0:1], vcc
	s_cbranch_execz .LBB0_756
	s_lshl_b32 s6, s4, 2
	v_mbcnt_lo_u32_b32 v72, vcc_lo, 0
	s_add_i32 s6, s8, s6
	v_mbcnt_hi_u32_b32 v72, vcc_hi, v72
	v_add_u32_e32 v71, 0xec0, v0
	v_lshl_add_u32 v72, v72, 2, s6
	ds_write_b32 v72, v71 offset:16896
.LBB0_756:
	s_or_b64 exec, exec, s[0:1]
	s_bcnt1_i32_b64 s0, vcc
	s_add_i32 s4, s4, s0
	v_cmp_ge_u32_e32 vcc, v70, v4
	s_and_saveexec_b64 s[0:1], vcc
	s_cbranch_execz .LBB0_758
	s_lshl_b32 s6, s4, 2
	v_mbcnt_lo_u32_b32 v71, vcc_lo, 0
	s_add_i32 s6, s8, s6
	v_mbcnt_hi_u32_b32 v71, vcc_hi, v71
	v_add_u32_e32 v70, 0xf00, v0
	v_lshl_add_u32 v71, v71, 2, s6
	ds_write_b32 v71, v70 offset:16896
.LBB0_758:
	s_or_b64 exec, exec, s[0:1]
	s_bcnt1_i32_b64 s0, vcc
	s_add_i32 s4, s4, s0
	v_cmp_ge_u32_e32 vcc, v69, v4
	s_and_saveexec_b64 s[0:1], vcc
	s_cbranch_execz .LBB0_760
	s_lshl_b32 s6, s4, 2
	v_mbcnt_lo_u32_b32 v70, vcc_lo, 0
	s_add_i32 s6, s8, s6
	v_mbcnt_hi_u32_b32 v70, vcc_hi, v70
	v_add_u32_e32 v69, 0xf40, v0
	v_lshl_add_u32 v70, v70, 2, s6
	ds_write_b32 v70, v69 offset:16896
.LBB0_760:
	s_or_b64 exec, exec, s[0:1]
	s_bcnt1_i32_b64 s0, vcc
	s_add_i32 s4, s4, s0
	v_cmp_ge_u32_e32 vcc, v68, v4
	s_and_saveexec_b64 s[0:1], vcc
	s_cbranch_execz .LBB0_762
	s_lshl_b32 s6, s4, 2
	v_mbcnt_lo_u32_b32 v69, vcc_lo, 0
	s_add_i32 s6, s8, s6
	v_mbcnt_hi_u32_b32 v69, vcc_hi, v69
	v_add_u32_e32 v68, 0xf80, v0
	v_lshl_add_u32 v69, v69, 2, s6
	ds_write_b32 v69, v68 offset:16896
.LBB0_762:
	s_or_b64 exec, exec, s[0:1]
	s_bcnt1_i32_b64 s0, vcc
	s_add_i32 s4, s4, s0
	v_cmp_ge_u32_e32 vcc, v67, v4
	s_and_saveexec_b64 s[0:1], vcc
	s_cbranch_execz .LBB0_764
	s_lshl_b32 s6, s4, 2
	v_mbcnt_lo_u32_b32 v68, vcc_lo, 0
	s_add_i32 s6, s8, s6
	v_mbcnt_hi_u32_b32 v68, vcc_hi, v68
	v_add_u32_e32 v67, 0xfc0, v0
	v_lshl_add_u32 v68, v68, 2, s6
	ds_write_b32 v68, v67 offset:16896

; __device__ __forceinline__ void topk_row(const Params& p, int r, int lane, __attribute__((address_space(3))) int* out) {
;     ...
;     if (exact) {
;       int base = 0;
; #pragma unroll
;       for (int blk = 0; blk < 8; ++blk) {
;         if (blk * 16 < nch) {
; #pragma unroll
;           for (int ii = 0; ii < 16; ++ii) {
;             const int i = blk * 16 + ii;
;             const bool g = key[i] >= Tv;
;             const unsigned long long mg = __ballot(g);
;             if (g) out[base + mbcnt64(mg)] = i * 64 + lo;
;             base += __popcll(mg);
;           }
;         }
;       }
;       return;
.LBB0_765:
	v_readlane_b32 s0, v244, 4
	v_readlane_b32 s1, v244, 5
	s_and_b64 vcc, exec, s[0:1]
	s_cbranch_vccnz .LBB0_799
	v_cmp_ge_u32_e32 vcc, v66, v4
	s_and_saveexec_b64 s[0:1], vcc
	s_cbranch_execz .LBB0_768
	s_lshl_b32 s6, s4, 2
	v_mbcnt_lo_u32_b32 v67, vcc_lo, 0
	s_add_i32 s6, s8, s6
	v_mbcnt_hi_u32_b32 v67, vcc_hi, v67
	v_add_u32_e32 v66, 0x1000, v0
	v_lshl_add_u32 v67, v67, 2, s6
	ds_write_b32 v67, v66 offset:16896
.LBB0_768:
	s_or_b64 exec, exec, s[0:1]
	s_bcnt1_i32_b64 s0, vcc
	s_add_i32 s4, s4, s0
	v_cmp_ge_u32_e32 vcc, v65, v4
	s_and_saveexec_b64 s[0:1], vcc
	s_cbranch_execz .LBB0_770
	s_lshl_b32 s6, s4, 2
	v_mbcnt_lo_u32_b32 v66, vcc_lo, 0
	s_add_i32 s6, s8, s6
	v_mbcnt_hi_u32_b32 v66, vcc_hi, v66
	v_add_u32_e32 v65, 0x1040, v0
	v_lshl_add_u32 v66, v66, 2, s6
	ds_write_b32 v66, v65 offset:16896
.LBB0_770:
	s_or_b64 exec, exec, s[0:1]
	s_bcnt1_i32_b64 s0, vcc
	s_add_i32 s4, s4, s0
	v_cmp_ge_u32_e32 vcc, v64, v4
	s_and_saveexec_b64 s[0:1], vcc
	s_cbranch_execz .LBB0_772
	s_lshl_b32 s6, s4, 2
	v_mbcnt_lo_u32_b32 v65, vcc_lo, 0
	s_add_i32 s6, s8, s6
	v_mbcnt_hi_u32_b32 v65, vcc_hi, v65
	v_add_u32_e32 v64, 0x1080, v0
	v_lshl_add_u32 v65, v65, 2, s6
	ds_write_b32 v65, v64 offset:16896
.LBB0_772:
	s_or_b64 exec, exec, s[0:1]
	s_bcnt1_i32_b64 s0, vcc
	s_add_i32 s4, s4, s0
	v_cmp_ge_u32_e32 vcc, v63, v4
	s_and_saveexec_b64 s[0:1], vcc
	s_cbranch_execz .LBB0_774
	s_lshl_b32 s6, s4, 2
	v_mbcnt_lo_u32_b32 v64, vcc_lo, 0
	s_add_i32 s6, s8, s6
	v_mbcnt_hi_u32_b32 v64, vcc_hi, v64
	v_add_u32_e32 v63, 0x10c0, v0
	v_lshl_add_u32 v64, v64, 2, s6
	ds_write_b32 v64, v63 offset:16896
.LBB0_774:
	s_or_b64 exec, exec, s[0:1]
	s_bcnt1_i32_b64 s0, vcc
	s_add_i32 s4, s4, s0
	v_cmp_ge_u32_e32 vcc, v62, v4
	s_and_saveexec_b64 s[0:1], vcc
	s_cbranch_execz .LBB0_776
	s_lshl_b32 s6, s4, 2
	v_mbcnt_lo_u32_b32 v63, vcc_lo, 0
	s_add_i32 s6, s8, s6
	v_mbcnt_hi_u32_b32 v63, vcc_hi, v63
	v_add_u32_e32 v62, 0x1100, v0
	v_lshl_add_u32 v63, v63, 2, s6
	ds_write_b32 v63, v62 offset:16896
.LBB0_776:
	s_or_b64 exec, exec, s[0:1]
	s_bcnt1_i32_b64 s0, vcc
	s_add_i32 s4, s4, s0
	v_cmp_ge_u32_e32 vcc, v61, v4
	s_and_saveexec_b64 s[0:1], vcc
	s_cbranch_execz .LBB0_778
	s_lshl_b32 s6, s4, 2
	v_mbcnt_lo_u32_b32 v62, vcc_lo, 0
	s_add_i32 s6, s8, s6
	v_mbcnt_hi_u32_b32 v62, vcc_hi, v62
	v_add_u32_e32 v61, 0x1140, v0
	v_lshl_add_u32 v62, v62, 2, s6
	ds_write_b32 v62, v61 offset:16896
.LBB0_778:
	s_or_b64 exec, exec, s[0:1]
	s_bcnt1_i32_b64 s0, vcc
	s_add_i32 s4, s4, s0
	v_cmp_ge_u32_e32 vcc, v60, v4
	s_and_saveexec_b64 s[0:1], vcc
	s_cbranch_execz .LBB0_780
	s_lshl_b32 s6, s4, 2
	v_mbcnt_lo_u32_b32 v61, vcc_lo, 0
	s_add_i32 s6, s8, s6
	v_mbcnt_hi_u32_b32 v61, vcc_hi, v61
	v_add_u32_e32 v60, 0x1180, v0
	v_lshl_add_u32 v61, v61, 2, s6
	ds_write_b32 v61, v60 offset:16896
.LBB0_780:
	s_or_b64 exec, exec, s[0:1]
	s_bcnt1_i32_b64 s0, vcc
	s_add_i32 s4, s4, s0
	v_cmp_ge_u32_e32 vcc, v59, v4
	s_and_saveexec_b64 s[0:1], vcc
	s_cbranch_execz .LBB0_782
	s_lshl_b32 s6, s4, 2
	v_mbcnt_lo_u32_b32 v60, vcc_lo, 0
	s_add_i32 s6, s8, s6
	v_mbcnt_hi_u32_b32 v60, vcc_hi, v60
	v_add_u32_e32 v59, 0x11c0, v0
	v_lshl_add_u32 v60, v60, 2, s6
	ds_write_b32 v60, v59 offset:16896
.LBB0_782:
	s_or_b64 exec, exec, s[0:1]
	s_bcnt1_i32_b64 s0, vcc
	s_add_i32 s4, s4, s0
	v_cmp_ge_u32_e32 vcc, v58, v4
	s_and_saveexec_b64 s[0:1], vcc
	s_cbranch_execz .LBB0_784
	s_lshl_b32 s6, s4, 2
	v_mbcnt_lo_u32_b32 v59, vcc_lo, 0
	s_add_i32 s6, s8, s6
	v_mbcnt_hi_u32_b32 v59, vcc_hi, v59
	v_add_u32_e32 v58, 0x1200, v0
	v_lshl_add_u32 v59, v59, 2, s6
	ds_write_b32 v59, v58 offset:16896
.LBB0_784:
	s_or_b64 exec, exec, s[0:1]
	s_bcnt1_i32_b64 s0, vcc
	s_add_i32 s4, s4, s0
	v_cmp_ge_u32_e32 vcc, v57, v4
	s_and_saveexec_b64 s[0:1], vcc
	s_cbranch_execz .LBB0_786
	s_lshl_b32 s6, s4, 2
	v_mbcnt_lo_u32_b32 v58, vcc_lo, 0
	s_add_i32 s6, s8, s6
	v_mbcnt_hi_u32_b32 v58, vcc_hi, v58
	v_add_u32_e32 v57, 0x1240, v0
	v_lshl_add_u32 v58, v58, 2, s6
	ds_write_b32 v58, v57 offset:16896
.LBB0_786:
	s_or_b64 exec, exec, s[0:1]
	s_bcnt1_i32_b64 s0, vcc
	s_add_i32 s4, s4, s0
	v_cmp_ge_u32_e32 vcc, v56, v4
	s_and_saveexec_b64 s[0:1], vcc
	s_cbranch_execz .LBB0_788
	s_lshl_b32 s6, s4, 2
	v_mbcnt_lo_u32_b32 v57, vcc_lo, 0
	s_add_i32 s6, s8, s6
	v_mbcnt_hi_u32_b32 v57, vcc_hi, v57
	v_add_u32_e32 v56, 0x1280, v0
	v_lshl_add_u32 v57, v57, 2, s6
	ds_write_b32 v57, v56 offset:16896
.LBB0_788:
	s_or_b64 exec, exec, s[0:1]
	s_bcnt1_i32_b64 s0, vcc
	s_add_i32 s4, s4, s0
	v_cmp_ge_u32_e32 vcc, v55, v4
	s_and_saveexec_b64 s[0:1], vcc
	s_cbranch_execz .LBB0_790
	s_lshl_b32 s6, s4, 2
	v_mbcnt_lo_u32_b32 v56, vcc_lo, 0
	s_add_i32 s6, s8, s6
	v_mbcnt_hi_u32_b32 v56, vcc_hi, v56
	v_add_u32_e32 v55, 0x12c0, v0
	v_lshl_add_u32 v56, v56, 2, s6
	ds_write_b32 v56, v55 offset:16896
.LBB0_790:
	s_or_b64 exec, exec, s[0:1]
	s_bcnt1_i32_b64 s0, vcc
	s_add_i32 s4, s4, s0
	v_cmp_ge_u32_e32 vcc, v54, v4
	s_and_saveexec_b64 s[0:1], vcc
	s_cbranch_execz .LBB0_792
	s_lshl_b32 s6, s4, 2
	v_mbcnt_lo_u32_b32 v55, vcc_lo, 0
	s_add_i32 s6, s8, s6
	v_mbcnt_hi_u32_b32 v55, vcc_hi, v55
	v_add_u32_e32 v54, 0x1300, v0
	v_lshl_add_u32 v55, v55, 2, s6
	ds_write_b32 v55, v54 offset:16896
.LBB0_792:
	s_or_b64 exec, exec, s[0:1]
	s_bcnt1_i32_b64 s0, vcc
	s_add_i32 s4, s4, s0
	v_cmp_ge_u32_e32 vcc, v53, v4
	s_and_saveexec_b64 s[0:1], vcc
	s_cbranch_execz .LBB0_794
	s_lshl_b32 s6, s4, 2
	v_mbcnt_lo_u32_b32 v54, vcc_lo, 0
	s_add_i32 s6, s8, s6
	v_mbcnt_hi_u32_b32 v54, vcc_hi, v54
	v_add_u32_e32 v53, 0x1340, v0
	v_lshl_add_u32 v54, v54, 2, s6
	ds_write_b32 v54, v53 offset:16896
.LBB0_794:
	s_or_b64 exec, exec, s[0:1]
	s_bcnt1_i32_b64 s0, vcc
	s_add_i32 s4, s4, s0
	v_cmp_ge_u32_e32 vcc, v52, v4
	s_and_saveexec_b64 s[0:1], vcc
	s_cbranch_execz .LBB0_796
	s_lshl_b32 s6, s4, 2
	v_mbcnt_lo_u32_b32 v53, vcc_lo, 0
	s_add_i32 s6, s8, s6
	v_mbcnt_hi_u32_b32 v53, vcc_hi, v53
	v_add_u32_e32 v52, 0x1380, v0
	v_lshl_add_u32 v53, v53, 2, s6
	ds_write_b32 v53, v52 offset:16896
.LBB0_796:
	s_or_b64 exec, exec, s[0:1]
	s_bcnt1_i32_b64 s0, vcc
	s_add_i32 s4, s4, s0
	v_cmp_ge_u32_e32 vcc, v51, v4
	s_and_saveexec_b64 s[0:1], vcc
	s_cbranch_execz .LBB0_798
	s_lshl_b32 s6, s4, 2
	v_mbcnt_lo_u32_b32 v52, vcc_lo, 0
	s_add_i32 s6, s8, s6
	v_mbcnt_hi_u32_b32 v52, vcc_hi, v52
	v_add_u32_e32 v51, 0x13c0, v0
	v_lshl_add_u32 v52, v52, 2, s6
	ds_write_b32 v52, v51 offset:16896

; __device__ __forceinline__ void topk_row(const Params& p, int r, int lane, __attribute__((address_space(3))) int* out) {
;     ...
;     if (exact) {
;       int base = 0;
; #pragma unroll
;       for (int blk = 0; blk < 8; ++blk) {
;         if (blk * 16 < nch) {
; #pragma unroll
;           for (int ii = 0; ii < 16; ++ii) {
;             const int i = blk * 16 + ii;
;             const bool g = key[i] >= Tv;
;             const unsigned long long mg = __ballot(g);
;             if (g) out[base + mbcnt64(mg)] = i * 64 + lo;
;             base += __popcll(mg);
;           }
;         }
;       }
;       return;
.LBB0_799:
	v_readlane_b32 s0, v244, 6
	v_readlane_b32 s1, v244, 7
	s_and_b64 vcc, exec, s[0:1]
	s_cbranch_vccnz .LBB0_833
	v_cmp_ge_u32_e32 vcc, v50, v4
	s_and_saveexec_b64 s[0:1], vcc
	s_cbranch_execz .LBB0_802
	s_lshl_b32 s6, s4, 2
	v_mbcnt_lo_u32_b32 v51, vcc_lo, 0
	s_add_i32 s6, s8, s6
	v_mbcnt_hi_u32_b32 v51, vcc_hi, v51
	v_add_u32_e32 v50, 0x1400, v0
	v_lshl_add_u32 v51, v51, 2, s6
	ds_write_b32 v51, v50 offset:16896
.LBB0_802:
	s_or_b64 exec, exec, s[0:1]
	s_bcnt1_i32_b64 s0, vcc
	s_add_i32 s4, s4, s0
	v_cmp_ge_u32_e32 vcc, v49, v4
	s_and_saveexec_b64 s[0:1], vcc
	s_cbranch_execz .LBB0_804
	s_lshl_b32 s6, s4, 2
	v_mbcnt_lo_u32_b32 v50, vcc_lo, 0
	s_add_i32 s6, s8, s6
	v_mbcnt_hi_u32_b32 v50, vcc_hi, v50
	v_add_u32_e32 v49, 0x1440, v0
	v_lshl_add_u32 v50, v50, 2, s6
	ds_write_b32 v50, v49 offset:16896
.LBB0_804:
	s_or_b64 exec, exec, s[0:1]
	s_bcnt1_i32_b64 s0, vcc
	s_add_i32 s4, s4, s0
	v_cmp_ge_u32_e32 vcc, v48, v4
	s_and_saveexec_b64 s[0:1], vcc
	s_cbranch_execz .LBB0_806
	s_lshl_b32 s6, s4, 2
	v_mbcnt_lo_u32_b32 v49, vcc_lo, 0
	s_add_i32 s6, s8, s6
	v_mbcnt_hi_u32_b32 v49, vcc_hi, v49
	v_add_u32_e32 v48, 0x1480, v0
	v_lshl_add_u32 v49, v49, 2, s6
	ds_write_b32 v49, v48 offset:16896
.LBB0_806:
	s_or_b64 exec, exec, s[0:1]
	s_bcnt1_i32_b64 s0, vcc
	s_add_i32 s4, s4, s0
	v_cmp_ge_u32_e32 vcc, v47, v4
	s_and_saveexec_b64 s[0:1], vcc
	s_cbranch_execz .LBB0_808
	s_lshl_b32 s6, s4, 2
	v_mbcnt_lo_u32_b32 v48, vcc_lo, 0
	s_add_i32 s6, s8, s6
	v_mbcnt_hi_u32_b32 v48, vcc_hi, v48
	v_add_u32_e32 v47, 0x14c0, v0
	v_lshl_add_u32 v48, v48, 2, s6
	ds_write_b32 v48, v47 offset:16896
.LBB0_808:
	s_or_b64 exec, exec, s[0:1]
	s_bcnt1_i32_b64 s0, vcc
	s_add_i32 s4, s4, s0
	v_cmp_ge_u32_e32 vcc, v46, v4
	s_and_saveexec_b64 s[0:1], vcc
	s_cbranch_execz .LBB0_810
	s_lshl_b32 s6, s4, 2
	v_mbcnt_lo_u32_b32 v47, vcc_lo, 0
	s_add_i32 s6, s8, s6
	v_mbcnt_hi_u32_b32 v47, vcc_hi, v47
	v_add_u32_e32 v46, 0x1500, v0
	v_lshl_add_u32 v47, v47, 2, s6
	ds_write_b32 v47, v46 offset:16896
.LBB0_810:
	s_or_b64 exec, exec, s[0:1]
	s_bcnt1_i32_b64 s0, vcc
	s_add_i32 s4, s4, s0
	v_cmp_ge_u32_e32 vcc, v45, v4
	s_and_saveexec_b64 s[0:1], vcc
	s_cbranch_execz .LBB0_812
	s_lshl_b32 s6, s4, 2
	v_mbcnt_lo_u32_b32 v46, vcc_lo, 0
	s_add_i32 s6, s8, s6
	v_mbcnt_hi_u32_b32 v46, vcc_hi, v46
	v_add_u32_e32 v45, 0x1540, v0
	v_lshl_add_u32 v46, v46, 2, s6
	ds_write_b32 v46, v45 offset:16896
.LBB0_812:
	s_or_b64 exec, exec, s[0:1]
	s_bcnt1_i32_b64 s0, vcc
	s_add_i32 s4, s4, s0
	v_cmp_ge_u32_e32 vcc, v44, v4
	s_and_saveexec_b64 s[0:1], vcc
	s_cbranch_execz .LBB0_814
	s_lshl_b32 s6, s4, 2
	v_mbcnt_lo_u32_b32 v45, vcc_lo, 0
	s_add_i32 s6, s8, s6
	v_mbcnt_hi_u32_b32 v45, vcc_hi, v45
	v_add_u32_e32 v44, 0x1580, v0
	v_lshl_add_u32 v45, v45, 2, s6
	ds_write_b32 v45, v44 offset:16896
.LBB0_814:
	s_or_b64 exec, exec, s[0:1]
	s_bcnt1_i32_b64 s0, vcc
	s_add_i32 s4, s4, s0
	v_cmp_ge_u32_e32 vcc, v43, v4
	s_and_saveexec_b64 s[0:1], vcc
	s_cbranch_execz .LBB0_816
	s_lshl_b32 s6, s4, 2
	v_mbcnt_lo_u32_b32 v44, vcc_lo, 0
	s_add_i32 s6, s8, s6
	v_mbcnt_hi_u32_b32 v44, vcc_hi, v44
	v_add_u32_e32 v43, 0x15c0, v0
	v_lshl_add_u32 v44, v44, 2, s6
	ds_write_b32 v44, v43 offset:16896
.LBB0_816:
	s_or_b64 exec, exec, s[0:1]
	s_bcnt1_i32_b64 s0, vcc
	s_add_i32 s4, s4, s0
	v_cmp_ge_u32_e32 vcc, v42, v4
	s_and_saveexec_b64 s[0:1], vcc
	s_cbranch_execz .LBB0_818
	s_lshl_b32 s6, s4, 2
	v_mbcnt_lo_u32_b32 v43, vcc_lo, 0
	s_add_i32 s6, s8, s6
	v_mbcnt_hi_u32_b32 v43, vcc_hi, v43
	v_add_u32_e32 v42, 0x1600, v0
	v_lshl_add_u32 v43, v43, 2, s6
	ds_write_b32 v43, v42 offset:16896
.LBB0_818:
	s_or_b64 exec, exec, s[0:1]
	s_bcnt1_i32_b64 s0, vcc
	s_add_i32 s4, s4, s0
	v_cmp_ge_u32_e32 vcc, v41, v4
	s_and_saveexec_b64 s[0:1], vcc
	s_cbranch_execz .LBB0_820
	s_lshl_b32 s6, s4, 2
	v_mbcnt_lo_u32_b32 v42, vcc_lo, 0
	s_add_i32 s6, s8, s6
	v_mbcnt_hi_u32_b32 v42, vcc_hi, v42
	v_add_u32_e32 v41, 0x1640, v0
	v_lshl_add_u32 v42, v42, 2, s6
	ds_write_b32 v42, v41 offset:16896
.LBB0_820:
	s_or_b64 exec, exec, s[0:1]
	s_bcnt1_i32_b64 s0, vcc
	s_add_i32 s4, s4, s0
	v_cmp_ge_u32_e32 vcc, v40, v4
	s_and_saveexec_b64 s[0:1], vcc
	s_cbranch_execz .LBB0_822
	s_lshl_b32 s6, s4, 2
	v_mbcnt_lo_u32_b32 v41, vcc_lo, 0
	s_add_i32 s6, s8, s6
	v_mbcnt_hi_u32_b32 v41, vcc_hi, v41
	v_add_u32_e32 v40, 0x1680, v0
	v_lshl_add_u32 v41, v41, 2, s6
	ds_write_b32 v41, v40 offset:16896
.LBB0_822:
	s_or_b64 exec, exec, s[0:1]
	s_bcnt1_i32_b64 s0, vcc
	s_add_i32 s4, s4, s0
	v_cmp_ge_u32_e32 vcc, v39, v4
	s_and_saveexec_b64 s[0:1], vcc
	s_cbranch_execz .LBB0_824
	s_lshl_b32 s6, s4, 2
	v_mbcnt_lo_u32_b32 v40, vcc_lo, 0
	s_add_i32 s6, s8, s6
	v_mbcnt_hi_u32_b32 v40, vcc_hi, v40
	v_add_u32_e32 v39, 0x16c0, v0
	v_lshl_add_u32 v40, v40, 2, s6
	ds_write_b32 v40, v39 offset:16896
.LBB0_824:
	s_or_b64 exec, exec, s[0:1]
	s_bcnt1_i32_b64 s0, vcc
	s_add_i32 s4, s4, s0
	v_cmp_ge_u32_e32 vcc, v38, v4
	s_and_saveexec_b64 s[0:1], vcc
	s_cbranch_execz .LBB0_826
	s_lshl_b32 s6, s4, 2
	v_mbcnt_lo_u32_b32 v39, vcc_lo, 0
	s_add_i32 s6, s8, s6
	v_mbcnt_hi_u32_b32 v39, vcc_hi, v39
	v_add_u32_e32 v38, 0x1700, v0
	v_lshl_add_u32 v39, v39, 2, s6
	ds_write_b32 v39, v38 offset:16896
.LBB0_826:
	s_or_b64 exec, exec, s[0:1]
	s_bcnt1_i32_b64 s0, vcc
	s_add_i32 s4, s4, s0
	v_cmp_ge_u32_e32 vcc, v37, v4
	s_and_saveexec_b64 s[0:1], vcc
	s_cbranch_execz .LBB0_828
	s_lshl_b32 s6, s4, 2
	v_mbcnt_lo_u32_b32 v38, vcc_lo, 0
	s_add_i32 s6, s8, s6
	v_mbcnt_hi_u32_b32 v38, vcc_hi, v38
	v_add_u32_e32 v37, 0x1740, v0
	v_lshl_add_u32 v38, v38, 2, s6
	ds_write_b32 v38, v37 offset:16896
.LBB0_828:
	s_or_b64 exec, exec, s[0:1]
	s_bcnt1_i32_b64 s0, vcc
	s_add_i32 s4, s4, s0
	v_cmp_ge_u32_e32 vcc, v36, v4
	s_and_saveexec_b64 s[0:1], vcc
	s_cbranch_execz .LBB0_830
	s_lshl_b32 s6, s4, 2
	v_mbcnt_lo_u32_b32 v37, vcc_lo, 0
	s_add_i32 s6, s8, s6
	v_mbcnt_hi_u32_b32 v37, vcc_hi, v37
	v_add_u32_e32 v36, 0x1780, v0
	v_lshl_add_u32 v37, v37, 2, s6
	ds_write_b32 v37, v36 offset:16896
.LBB0_830:
	s_or_b64 exec, exec, s[0:1]
	s_bcnt1_i32_b64 s0, vcc
	s_add_i32 s4, s4, s0
	v_cmp_ge_u32_e32 vcc, v35, v4
	s_and_saveexec_b64 s[0:1], vcc
	s_cbranch_execz .LBB0_832
	s_lshl_b32 s6, s4, 2
	v_mbcnt_lo_u32_b32 v36, vcc_lo, 0
	s_add_i32 s6, s8, s6
	v_mbcnt_hi_u32_b32 v36, vcc_hi, v36
	v_add_u32_e32 v35, 0x17c0, v0
	v_lshl_add_u32 v36, v36, 2, s6
	ds_write_b32 v36, v35 offset:16896

; __device__ __forceinline__ void topk_row(const Params& p, int r, int lane, __attribute__((address_space(3))) int* out) {
;     ...
;     if (exact) {
;       int base = 0;
; #pragma unroll
;       for (int blk = 0; blk < 8; ++blk) {
;         if (blk * 16 < nch) {
; #pragma unroll
;           for (int ii = 0; ii < 16; ++ii) {
;             const int i = blk * 16 + ii;
;             const bool g = key[i] >= Tv;
;             const unsigned long long mg = __ballot(g);
;             if (g) out[base + mbcnt64(mg)] = i * 64 + lo;
;             base += __popcll(mg);
;           }
;         }
;       }
;       return;
.LBB0_833:
	v_readlane_b32 s0, v244, 8
	v_readlane_b32 s1, v244, 9
	s_and_b64 vcc, exec, s[0:1]
	s_cbranch_vccnz .LBB0_867
	v_cmp_ge_u32_e32 vcc, v34, v4
	s_and_saveexec_b64 s[0:1], vcc
	s_cbranch_execz .LBB0_836
	s_lshl_b32 s6, s4, 2
	v_mbcnt_lo_u32_b32 v35, vcc_lo, 0
	s_add_i32 s6, s8, s6
	v_mbcnt_hi_u32_b32 v35, vcc_hi, v35
	v_add_u32_e32 v34, 0x1800, v0
	v_lshl_add_u32 v35, v35, 2, s6
	ds_write_b32 v35, v34 offset:16896
.LBB0_836:
	s_or_b64 exec, exec, s[0:1]
	s_bcnt1_i32_b64 s0, vcc
	s_add_i32 s4, s4, s0
	v_cmp_ge_u32_e32 vcc, v32, v4
	s_and_saveexec_b64 s[0:1], vcc
	s_cbranch_execz .LBB0_838
	s_lshl_b32 s6, s4, 2
	v_mbcnt_lo_u32_b32 v34, vcc_lo, 0
	s_add_i32 s6, s8, s6
	v_mbcnt_hi_u32_b32 v34, vcc_hi, v34
	v_add_u32_e32 v32, 0x1840, v0
	v_lshl_add_u32 v34, v34, 2, s6
	ds_write_b32 v34, v32 offset:16896
.LBB0_838:
	s_or_b64 exec, exec, s[0:1]
	s_bcnt1_i32_b64 s0, vcc
	s_add_i32 s4, s4, s0
	v_cmp_ge_u32_e32 vcc, v31, v4
	s_and_saveexec_b64 s[0:1], vcc
	s_cbranch_execz .LBB0_840
	s_lshl_b32 s6, s4, 2
	v_mbcnt_lo_u32_b32 v32, vcc_lo, 0
	s_add_i32 s6, s8, s6
	v_mbcnt_hi_u32_b32 v32, vcc_hi, v32
	v_add_u32_e32 v31, 0x1880, v0
	v_lshl_add_u32 v32, v32, 2, s6
	ds_write_b32 v32, v31 offset:16896
.LBB0_840:
	s_or_b64 exec, exec, s[0:1]
	s_bcnt1_i32_b64 s0, vcc
	s_add_i32 s4, s4, s0
	v_cmp_ge_u32_e32 vcc, v30, v4
	s_and_saveexec_b64 s[0:1], vcc
	s_cbranch_execz .LBB0_842
	s_lshl_b32 s6, s4, 2
	v_mbcnt_lo_u32_b32 v31, vcc_lo, 0
	s_add_i32 s6, s8, s6
	v_mbcnt_hi_u32_b32 v31, vcc_hi, v31
	v_add_u32_e32 v30, 0x18c0, v0
	v_lshl_add_u32 v31, v31, 2, s6
	ds_write_b32 v31, v30 offset:16896
.LBB0_842:
	s_or_b64 exec, exec, s[0:1]
	s_bcnt1_i32_b64 s0, vcc
	s_add_i32 s4, s4, s0
	v_cmp_ge_u32_e32 vcc, v29, v4
	s_and_saveexec_b64 s[0:1], vcc
	s_cbranch_execz .LBB0_844
	s_lshl_b32 s6, s4, 2
	v_mbcnt_lo_u32_b32 v30, vcc_lo, 0
	s_add_i32 s6, s8, s6
	v_mbcnt_hi_u32_b32 v30, vcc_hi, v30
	v_add_u32_e32 v29, 0x1900, v0
	v_lshl_add_u32 v30, v30, 2, s6
	ds_write_b32 v30, v29 offset:16896
.LBB0_844:
	s_or_b64 exec, exec, s[0:1]
	s_bcnt1_i32_b64 s0, vcc
	s_add_i32 s4, s4, s0
	v_cmp_ge_u32_e32 vcc, v28, v4
	s_and_saveexec_b64 s[0:1], vcc
	s_cbranch_execz .LBB0_846
	s_lshl_b32 s6, s4, 2
	v_mbcnt_lo_u32_b32 v29, vcc_lo, 0
	s_add_i32 s6, s8, s6
	v_mbcnt_hi_u32_b32 v29, vcc_hi, v29
	v_add_u32_e32 v28, 0x1940, v0
	v_lshl_add_u32 v29, v29, 2, s6
	ds_write_b32 v29, v28 offset:16896
.LBB0_846:
	s_or_b64 exec, exec, s[0:1]
	s_bcnt1_i32_b64 s0, vcc
	s_add_i32 s4, s4, s0
	v_cmp_ge_u32_e32 vcc, v27, v4
	s_and_saveexec_b64 s[0:1], vcc
	s_cbranch_execz .LBB0_848
	s_lshl_b32 s6, s4, 2
	v_mbcnt_lo_u32_b32 v28, vcc_lo, 0
	s_add_i32 s6, s8, s6
	v_mbcnt_hi_u32_b32 v28, vcc_hi, v28
	v_add_u32_e32 v27, 0x1980, v0
	v_lshl_add_u32 v28, v28, 2, s6
	ds_write_b32 v28, v27 offset:16896
.LBB0_848:
	s_or_b64 exec, exec, s[0:1]
	s_bcnt1_i32_b64 s0, vcc
	s_add_i32 s4, s4, s0
	v_cmp_ge_u32_e32 vcc, v26, v4
	s_and_saveexec_b64 s[0:1], vcc
	s_cbranch_execz .LBB0_850
	s_lshl_b32 s6, s4, 2
	v_mbcnt_lo_u32_b32 v27, vcc_lo, 0
	s_add_i32 s6, s8, s6
	v_mbcnt_hi_u32_b32 v27, vcc_hi, v27
	v_add_u32_e32 v26, 0x19c0, v0
	v_lshl_add_u32 v27, v27, 2, s6
	ds_write_b32 v27, v26 offset:16896
.LBB0_850:
	s_or_b64 exec, exec, s[0:1]
	s_bcnt1_i32_b64 s0, vcc
	s_add_i32 s4, s4, s0
	v_cmp_ge_u32_e32 vcc, v25, v4
	s_and_saveexec_b64 s[0:1], vcc
	s_cbranch_execz .LBB0_852
	s_lshl_b32 s6, s4, 2
	v_mbcnt_lo_u32_b32 v26, vcc_lo, 0
	s_add_i32 s6, s8, s6
	v_mbcnt_hi_u32_b32 v26, vcc_hi, v26
	v_add_u32_e32 v25, 0x1a00, v0
	v_lshl_add_u32 v26, v26, 2, s6
	ds_write_b32 v26, v25 offset:16896
.LBB0_852:
	s_or_b64 exec, exec, s[0:1]
	s_bcnt1_i32_b64 s0, vcc
	s_add_i32 s4, s4, s0
	v_cmp_ge_u32_e32 vcc, v24, v4
	s_and_saveexec_b64 s[0:1], vcc
	s_cbranch_execz .LBB0_854
	s_lshl_b32 s6, s4, 2
	v_mbcnt_lo_u32_b32 v25, vcc_lo, 0
	s_add_i32 s6, s8, s6
	v_mbcnt_hi_u32_b32 v25, vcc_hi, v25
	v_add_u32_e32 v24, 0x1a40, v0
	v_lshl_add_u32 v25, v25, 2, s6
	ds_write_b32 v25, v24 offset:16896
.LBB0_854:
	s_or_b64 exec, exec, s[0:1]
	s_bcnt1_i32_b64 s0, vcc
	s_add_i32 s4, s4, s0
	v_cmp_ge_u32_e32 vcc, v23, v4
	s_and_saveexec_b64 s[0:1], vcc
	s_cbranch_execz .LBB0_856
	s_lshl_b32 s6, s4, 2
	v_mbcnt_lo_u32_b32 v24, vcc_lo, 0
	s_add_i32 s6, s8, s6
	v_mbcnt_hi_u32_b32 v24, vcc_hi, v24
	v_add_u32_e32 v23, 0x1a80, v0
	v_lshl_add_u32 v24, v24, 2, s6
	ds_write_b32 v24, v23 offset:16896
.LBB0_856:
	s_or_b64 exec, exec, s[0:1]
	s_bcnt1_i32_b64 s0, vcc
	s_add_i32 s4, s4, s0
	v_cmp_ge_u32_e32 vcc, v22, v4
	s_and_saveexec_b64 s[0:1], vcc
	s_cbranch_execz .LBB0_858
	s_lshl_b32 s6, s4, 2
	v_mbcnt_lo_u32_b32 v23, vcc_lo, 0
	s_add_i32 s6, s8, s6
	v_mbcnt_hi_u32_b32 v23, vcc_hi, v23
	v_add_u32_e32 v22, 0x1ac0, v0
	v_lshl_add_u32 v23, v23, 2, s6
	ds_write_b32 v23, v22 offset:16896
.LBB0_858:
	s_or_b64 exec, exec, s[0:1]
	s_bcnt1_i32_b64 s0, vcc
	s_add_i32 s4, s4, s0
	v_cmp_ge_u32_e32 vcc, v21, v4
	s_and_saveexec_b64 s[0:1], vcc
	s_cbranch_execz .LBB0_860
	s_lshl_b32 s6, s4, 2
	v_mbcnt_lo_u32_b32 v22, vcc_lo, 0
	s_add_i32 s6, s8, s6
	v_mbcnt_hi_u32_b32 v22, vcc_hi, v22
	v_add_u32_e32 v21, 0x1b00, v0
	v_lshl_add_u32 v22, v22, 2, s6
	ds_write_b32 v22, v21 offset:16896
.LBB0_860:
	s_or_b64 exec, exec, s[0:1]
	s_bcnt1_i32_b64 s0, vcc
	s_add_i32 s4, s4, s0
	v_cmp_ge_u32_e32 vcc, v20, v4
	s_and_saveexec_b64 s[0:1], vcc
	s_cbranch_execz .LBB0_862
	s_lshl_b32 s6, s4, 2
	v_mbcnt_lo_u32_b32 v21, vcc_lo, 0
	s_add_i32 s6, s8, s6
	v_mbcnt_hi_u32_b32 v21, vcc_hi, v21
	v_add_u32_e32 v20, 0x1b40, v0
	v_lshl_add_u32 v21, v21, 2, s6
	ds_write_b32 v21, v20 offset:16896
.LBB0_862:
	s_or_b64 exec, exec, s[0:1]
	s_bcnt1_i32_b64 s0, vcc
	s_add_i32 s4, s4, s0
	v_cmp_ge_u32_e32 vcc, v19, v4
	s_and_saveexec_b64 s[0:1], vcc
	s_cbranch_execz .LBB0_864
	s_lshl_b32 s6, s4, 2
	v_mbcnt_lo_u32_b32 v20, vcc_lo, 0
	s_add_i32 s6, s8, s6
	v_mbcnt_hi_u32_b32 v20, vcc_hi, v20
	v_add_u32_e32 v19, 0x1b80, v0
	v_lshl_add_u32 v20, v20, 2, s6
	ds_write_b32 v20, v19 offset:16896
.LBB0_864:
	s_or_b64 exec, exec, s[0:1]
	s_bcnt1_i32_b64 s0, vcc
	s_add_i32 s4, s4, s0
	v_cmp_ge_u32_e32 vcc, v18, v4
	s_and_saveexec_b64 s[0:1], vcc
	s_cbranch_execz .LBB0_866
	s_lshl_b32 s6, s4, 2
	v_mbcnt_lo_u32_b32 v19, vcc_lo, 0
	s_add_i32 s6, s8, s6
	v_mbcnt_hi_u32_b32 v19, vcc_hi, v19
	v_add_u32_e32 v18, 0x1bc0, v0
	v_lshl_add_u32 v19, v19, 2, s6
	ds_write_b32 v19, v18 offset:16896

; __device__ __forceinline__ void topk_row(const Params& p, int r, int lane, __attribute__((address_space(3))) int* out) {
;     ...
;     if (exact) {
;       int base = 0;
; #pragma unroll
;       for (int blk = 0; blk < 8; ++blk) {
;         if (blk * 16 < nch) {
; #pragma unroll
;           for (int ii = 0; ii < 16; ++ii) {
;             const int i = blk * 16 + ii;
;             const bool g = key[i] >= Tv;
;             const unsigned long long mg = __ballot(g);
;             if (g) out[base + mbcnt64(mg)] = i * 64 + lo;
;             base += __popcll(mg);
;           }
;         }
;       }
;       return;
.LBB0_867:
	v_readlane_b32 s0, v244, 10
	v_readlane_b32 s1, v244, 11
	s_and_b64 vcc, exec, s[0:1]
	s_cbranch_vccnz .LBB0_902
	v_cmp_ge_u32_e32 vcc, v17, v4
	s_and_saveexec_b64 s[0:1], vcc
	s_cbranch_execz .LBB0_870
	s_lshl_b32 s6, s4, 2
	v_mbcnt_lo_u32_b32 v18, vcc_lo, 0
	s_add_i32 s6, s8, s6
	v_mbcnt_hi_u32_b32 v18, vcc_hi, v18
	v_add_u32_e32 v17, 0x1c00, v0
	v_lshl_add_u32 v18, v18, 2, s6
	ds_write_b32 v18, v17 offset:16896
.LBB0_870:
	s_or_b64 exec, exec, s[0:1]
	s_bcnt1_i32_b64 s0, vcc
	s_add_i32 s4, s4, s0
	v_cmp_ge_u32_e32 vcc, v16, v4
	s_and_saveexec_b64 s[0:1], vcc
	s_cbranch_execz .LBB0_872
	s_lshl_b32 s6, s4, 2
	v_mbcnt_lo_u32_b32 v17, vcc_lo, 0
	s_add_i32 s6, s8, s6
	v_mbcnt_hi_u32_b32 v17, vcc_hi, v17
	v_add_u32_e32 v16, 0x1c40, v0
	v_lshl_add_u32 v17, v17, 2, s6
	ds_write_b32 v17, v16 offset:16896
.LBB0_872:
	s_or_b64 exec, exec, s[0:1]
	s_bcnt1_i32_b64 s0, vcc
	s_add_i32 s4, s4, s0
	v_cmp_ge_u32_e32 vcc, v15, v4
	s_and_saveexec_b64 s[0:1], vcc
	s_cbranch_execz .LBB0_874
	s_lshl_b32 s6, s4, 2
	v_mbcnt_lo_u32_b32 v16, vcc_lo, 0
	s_add_i32 s6, s8, s6
	v_mbcnt_hi_u32_b32 v16, vcc_hi, v16
	v_add_u32_e32 v15, 0x1c80, v0
	v_lshl_add_u32 v16, v16, 2, s6
	ds_write_b32 v16, v15 offset:16896
.LBB0_874:
	s_or_b64 exec, exec, s[0:1]
	s_bcnt1_i32_b64 s0, vcc
	s_add_i32 s4, s4, s0
	v_cmp_ge_u32_e32 vcc, v14, v4
	s_and_saveexec_b64 s[0:1], vcc
	s_cbranch_execz .LBB0_876
	s_lshl_b32 s6, s4, 2
	v_mbcnt_lo_u32_b32 v15, vcc_lo, 0
	s_add_i32 s6, s8, s6
	v_mbcnt_hi_u32_b32 v15, vcc_hi, v15
	v_add_u32_e32 v14, 0x1cc0, v0
	v_lshl_add_u32 v15, v15, 2, s6
	ds_write_b32 v15, v14 offset:16896
.LBB0_876:
	s_or_b64 exec, exec, s[0:1]
	s_bcnt1_i32_b64 s0, vcc
	s_add_i32 s4, s4, s0
	v_cmp_ge_u32_e32 vcc, v13, v4
	s_and_saveexec_b64 s[0:1], vcc
	s_cbranch_execz .LBB0_878
	s_lshl_b32 s6, s4, 2
	v_mbcnt_lo_u32_b32 v14, vcc_lo, 0
	s_add_i32 s6, s8, s6
	v_mbcnt_hi_u32_b32 v14, vcc_hi, v14
	v_add_u32_e32 v13, 0x1d00, v0
	v_lshl_add_u32 v14, v14, 2, s6
	ds_write_b32 v14, v13 offset:16896
.LBB0_878:
	s_or_b64 exec, exec, s[0:1]
	s_bcnt1_i32_b64 s0, vcc
	s_add_i32 s4, s4, s0
	v_cmp_ge_u32_e32 vcc, v12, v4
	s_and_saveexec_b64 s[0:1], vcc
	s_cbranch_execz .LBB0_880
	s_lshl_b32 s6, s4, 2
	v_mbcnt_lo_u32_b32 v13, vcc_lo, 0
	s_add_i32 s6, s8, s6
	v_mbcnt_hi_u32_b32 v13, vcc_hi, v13
	v_add_u32_e32 v12, 0x1d40, v0
	v_lshl_add_u32 v13, v13, 2, s6
	ds_write_b32 v13, v12 offset:16896
.LBB0_880:
	s_or_b64 exec, exec, s[0:1]
	s_bcnt1_i32_b64 s0, vcc
	s_add_i32 s4, s4, s0
	v_cmp_ge_u32_e32 vcc, v11, v4
	s_and_saveexec_b64 s[0:1], vcc
	s_cbranch_execz .LBB0_882
	s_lshl_b32 s6, s4, 2
	v_mbcnt_lo_u32_b32 v12, vcc_lo, 0
	s_add_i32 s6, s8, s6
	v_mbcnt_hi_u32_b32 v12, vcc_hi, v12
	v_add_u32_e32 v11, 0x1d80, v0
	v_lshl_add_u32 v12, v12, 2, s6
	ds_write_b32 v12, v11 offset:16896
.LBB0_882:
	s_or_b64 exec, exec, s[0:1]
	s_bcnt1_i32_b64 s0, vcc
	s_add_i32 s4, s4, s0
	v_cmp_ge_u32_e32 vcc, v10, v4
	s_and_saveexec_b64 s[0:1], vcc
	s_cbranch_execz .LBB0_884
	s_lshl_b32 s6, s4, 2
	v_mbcnt_lo_u32_b32 v11, vcc_lo, 0
	s_add_i32 s6, s8, s6
	v_mbcnt_hi_u32_b32 v11, vcc_hi, v11
	v_add_u32_e32 v10, 0x1dc0, v0
	v_lshl_add_u32 v11, v11, 2, s6
	ds_write_b32 v11, v10 offset:16896
.LBB0_884:
	s_or_b64 exec, exec, s[0:1]
	s_bcnt1_i32_b64 s0, vcc
	s_add_i32 s4, s4, s0
	v_cmp_ge_u32_e32 vcc, v9, v4
	s_and_saveexec_b64 s[0:1], vcc
	s_cbranch_execz .LBB0_886
	s_lshl_b32 s6, s4, 2
	v_mbcnt_lo_u32_b32 v10, vcc_lo, 0
	s_add_i32 s6, s8, s6
	v_mbcnt_hi_u32_b32 v10, vcc_hi, v10
	v_add_u32_e32 v9, 0x1e00, v0
	v_lshl_add_u32 v10, v10, 2, s6
	ds_write_b32 v10, v9 offset:16896
.LBB0_886:
	s_or_b64 exec, exec, s[0:1]
	s_bcnt1_i32_b64 s0, vcc
	s_add_i32 s4, s4, s0
	v_cmp_ge_u32_e32 vcc, v8, v4
	s_and_saveexec_b64 s[0:1], vcc
	s_cbranch_execz .LBB0_888
	s_lshl_b32 s6, s4, 2
	v_mbcnt_lo_u32_b32 v9, vcc_lo, 0
	s_add_i32 s6, s8, s6
	v_mbcnt_hi_u32_b32 v9, vcc_hi, v9
	v_add_u32_e32 v8, 0x1e40, v0
	v_lshl_add_u32 v9, v9, 2, s6
	ds_write_b32 v9, v8 offset:16896
.LBB0_888:
	s_or_b64 exec, exec, s[0:1]
	s_bcnt1_i32_b64 s0, vcc
	s_add_i32 s4, s4, s0
	v_cmp_ge_u32_e32 vcc, v7, v4
	s_and_saveexec_b64 s[0:1], vcc
	s_cbranch_execz .LBB0_890
	s_lshl_b32 s6, s4, 2
	v_mbcnt_lo_u32_b32 v8, vcc_lo, 0
	s_add_i32 s6, s8, s6
	v_mbcnt_hi_u32_b32 v8, vcc_hi, v8
	v_add_u32_e32 v7, 0x1e80, v0
	v_lshl_add_u32 v8, v8, 2, s6
	ds_write_b32 v8, v7 offset:16896
.LBB0_890:
	s_or_b64 exec, exec, s[0:1]
	s_bcnt1_i32_b64 s0, vcc
	s_add_i32 s4, s4, s0
	v_cmp_ge_u32_e32 vcc, v6, v4
	s_and_saveexec_b64 s[0:1], vcc
	s_cbranch_execz .LBB0_892
	s_lshl_b32 s6, s4, 2
	v_mbcnt_lo_u32_b32 v7, vcc_lo, 0
	s_add_i32 s6, s8, s6
	v_mbcnt_hi_u32_b32 v7, vcc_hi, v7
	v_add_u32_e32 v6, 0x1ec0, v0
	v_lshl_add_u32 v7, v7, 2, s6
	ds_write_b32 v7, v6 offset:16896
.LBB0_892:
	s_or_b64 exec, exec, s[0:1]
	s_bcnt1_i32_b64 s0, vcc
	s_add_i32 s4, s4, s0
	v_cmp_ge_u32_e32 vcc, v5, v4
	s_and_saveexec_b64 s[0:1], vcc
	s_cbranch_execz .LBB0_894
	s_lshl_b32 s6, s4, 2
	v_mbcnt_lo_u32_b32 v6, vcc_lo, 0
	s_add_i32 s6, s8, s6
	v_mbcnt_hi_u32_b32 v6, vcc_hi, v6
	v_add_u32_e32 v5, 0x1f00, v0
	v_lshl_add_u32 v6, v6, 2, s6
	ds_write_b32 v6, v5 offset:16896
.LBB0_894:
	s_or_b64 exec, exec, s[0:1]
	s_bcnt1_i32_b64 s0, vcc
	s_add_i32 s4, s4, s0
	v_cmp_ge_u32_e32 vcc, v3, v4
	s_and_saveexec_b64 s[0:1], vcc
	s_cbranch_execz .LBB0_896
	s_lshl_b32 s6, s4, 2
	v_mbcnt_lo_u32_b32 v5, vcc_lo, 0
	s_add_i32 s6, s8, s6
	v_mbcnt_hi_u32_b32 v5, vcc_hi, v5
	v_add_u32_e32 v3, 0x1f40, v0
	v_lshl_add_u32 v5, v5, 2, s6
	ds_write_b32 v5, v3 offset:16896
.LBB0_896:
	s_or_b64 exec, exec, s[0:1]
	s_bcnt1_i32_b64 s0, vcc
	s_add_i32 s4, s4, s0
	v_cmp_ge_u32_e32 vcc, v2, v4
	s_and_saveexec_b64 s[0:1], vcc
	s_cbranch_execz .LBB0_898
	s_lshl_b32 s6, s4, 2
	v_mbcnt_lo_u32_b32 v3, vcc_lo, 0
	s_add_i32 s6, s8, s6
	v_mbcnt_hi_u32_b32 v3, vcc_hi, v3
	v_add_u32_e32 v2, 0x1f80, v0
	v_lshl_add_u32 v3, v3, 2, s6
	ds_write_b32 v3, v2 offset:16896
.LBB0_898:
	s_or_b64 exec, exec, s[0:1]
	v_cmp_ge_u32_e64 s[0:1], v1, v4
	s_and_saveexec_b64 s[6:7], s[0:1]
	s_cbranch_execz .LBB0_900
	s_lshl_b32 s4, s4, 2
	s_bcnt1_i32_b64 s16, vcc
	s_add_i32 s4, s8, s4
	s_lshl_b32 s16, s16, 2
	v_mbcnt_lo_u32_b32 v1, s0, 0
	s_add_i32 s4, s4, s16
	v_mbcnt_hi_u32_b32 v1, s1, v1
	v_add_u32_e32 v0, 0x1fc0, v0
	v_lshl_add_u32 v1, v1, 2, s4
	ds_write_b32 v1, v0 offset:16896

; #define LDSP(TY, p) ((__attribute__((address_space(3))) TY*)(p))
; #define WAIT_V0() asm volatile("s_waitcnt vmcnt(0)" ::: "memory")
; #define WAIT_L0() asm volatile("s_waitcnt lgkmcnt(0)" ::: "memory")
; __device__ __forceinline__ void ph_attn(const Params& p, char* shm) {
;     ...
;     for (int c = 0; c < nchunk; ++c) {
;       const int slot = c * 16 + hd;
;       int iv = (slot < cnt) ? slot : 0;
;       if (t >= 256) iv = idxl[slot];
;       WAIT_L0();
; #pragma unroll
;       for (int j = 0; j < 16; ++j) {
;         const int kidx = __builtin_amdgcn_readlane(iv, j);
;         __builtin_amdgcn_global_load_lds((const unsigned*)(ckvb + (size_t)kidx * 512 + lane * 8), LDSP(unsigned, wb + j * 1040), 16, 0, 0);
;       }
;       WAIT_V0();
;       f32x4 s = {0.f, 0.f, 0.f, 0.f};
; #pragma unroll
;       for (int ks = 0; ks < 16; ++ks) {
;         const s16x8 a = *(const s16x8*)(wb + hd * 1040 + ks * 64 + g4 * 16);
;         s = __builtin_amdgcn_mfma_f32_16x16x32_bf16(a, qb[ks], s, 0, 0, 0);
;       }
;       float sv[4], cmax = -INFINITY;
; #pragma unroll
;       for (int j = 0; j < 4; ++j) {
;         const int sl = c * 16 + g4 * 4 + j;
;         sv[j] = (sl < cnt) ? s[j] * scale : -INFINITY;
;         cmax = fmaxf(cmax, sv[j]);
;       }
;       {
;         auto r16 = __builtin_amdgcn_permlane16_swap(__float_as_uint(cmax), __float_as_uint(cmax), false, false);
;         cmax = fmaxf(__uint_as_float(r16[0]), __uint_as_float(r16[1]));
;         auto r32 = __builtin_amdgcn_permlane32_swap(__float_as_uint(cmax), __float_as_uint(cmax), false, false);
;         cmax = fmaxf(__uint_as_float(r32[0]), __uint_as_float(r32[1]));
;       }
;       if (__ballot(cmax > mref + 8.f)) {
.LBB0_904:
	s_mov_b32 m0, s8
	v_lshl_add_u64 v[34:35], v[202:203], 0, s[68:69]
	global_load_lds_dwordx4 v[34:35], off
	s_add_i32 m0, s8, 0x420
	v_lshl_add_u64 v[34:35], v[202:203], 0, s[70:71]
	global_load_lds_dwordx4 v[34:35], off
	s_add_i32 m0, s8, 0x840
	v_lshl_add_u64 v[34:35], v[202:203], 0, s[72:73]
	global_load_lds_dwordx4 v[34:35], off
	s_add_i32 m0, s8, 0xc60
	v_lshl_add_u64 v[34:35], v[202:203], 0, s[74:75]
	global_load_lds_dwordx4 v[34:35], off
	s_add_i32 m0, s8, 0x1080
	v_lshl_add_u64 v[34:35], v[202:203], 0, s[76:77]
	global_load_lds_dwordx4 v[34:35], off
	s_add_i32 m0, s8, 0x14a0
	v_lshl_add_u64 v[34:35], v[202:203], 0, s[78:79]
	global_load_lds_dwordx4 v[34:35], off
	s_add_i32 m0, s8, 0x18c0
	v_lshl_add_u64 v[34:35], v[202:203], 0, s[80:81]
	global_load_lds_dwordx4 v[34:35], off
	s_add_i32 m0, s8, 0x1ce0
	v_lshl_add_u64 v[34:35], v[202:203], 0, s[82:83]
	global_load_lds_dwordx4 v[34:35], off
	s_add_i32 m0, s8, 0x2100
	v_lshl_add_u64 v[34:35], v[202:203], 0, s[84:85]
	global_load_lds_dwordx4 v[34:35], off
	s_add_i32 m0, s8, 0x2520
	v_lshl_add_u64 v[34:35], v[202:203], 0, s[88:89]
	global_load_lds_dwordx4 v[34:35], off
	s_add_i32 m0, s8, 0x2940
	v_lshl_add_u64 v[34:35], v[202:203], 0, s[90:91]
	global_load_lds_dwordx4 v[34:35], off
	s_add_i32 m0, s8, 0x2d60
	v_lshl_add_u64 v[34:35], v[202:203], 0, s[92:93]
	global_load_lds_dwordx4 v[34:35], off
	s_add_i32 m0, s8, 0x3180
	v_lshl_add_u64 v[34:35], v[202:203], 0, s[94:95]
	global_load_lds_dwordx4 v[34:35], off
	s_add_i32 m0, s8, 0x35a0
	v_lshl_add_u64 v[34:35], v[202:203], 0, s[96:97]
	global_load_lds_dwordx4 v[34:35], off
	s_add_i32 m0, s8, 0x39c0
	v_lshl_add_u64 v[34:35], v[202:203], 0, s[98:99]
	global_load_lds_dwordx4 v[34:35], off
	s_add_i32 m0, s8, 0x3de0
	v_lshl_add_u64 v[34:35], v[202:203], 0, s[34:35]
	global_load_lds_dwordx4 v[34:35], off
	v_cmp_ge_u32_e32 vcc, s4, v227
	s_waitcnt vmcnt(0)
	ds_read_b128 v[234:237], v222
	ds_read_b128 v[238:241], v222 offset:64
	v_add_u32_e32 v229, 2, v227
	s_mov_b32 s0, 0xff800000
	s_waitcnt lgkmcnt(1)
	v_mfma_f32_16x16x32_bf16 v[230:233], v[234:237], v[132:135], 0
	ds_read_b128 v[234:237], v222 offset:128
	s_waitcnt lgkmcnt(1)
	v_mfma_f32_16x16x32_bf16 v[230:233], v[238:241], v[136:139], v[230:233]
	ds_read_b128 v[238:241], v222 offset:192
	s_waitcnt lgkmcnt(1)
	v_mfma_f32_16x16x32_bf16 v[230:233], v[234:237], v[140:143], v[230:233]
	ds_read_b128 v[234:237], v222 offset:256
	s_waitcnt lgkmcnt(1)
	v_mfma_f32_16x16x32_bf16 v[230:233], v[238:241], v[144:147], v[230:233]
	ds_read_b128 v[238:241], v222 offset:320
	s_waitcnt lgkmcnt(1)
	v_mfma_f32_16x16x32_bf16 v[230:233], v[234:237], v[148:151], v[230:233]
	ds_read_b128 v[234:237], v222 offset:384
	s_waitcnt lgkmcnt(1)
	v_mfma_f32_16x16x32_bf16 v[230:233], v[238:241], v[152:155], v[230:233]
	ds_read_b128 v[238:241], v222 offset:448
	s_waitcnt lgkmcnt(1)
	v_mfma_f32_16x16x32_bf16 v[230:233], v[234:237], v[156:159], v[230:233]
	ds_read_b128 v[234:237], v222 offset:512
	s_waitcnt lgkmcnt(1)
	v_mfma_f32_16x16x32_bf16 v[230:233], v[238:241], v[160:163], v[230:233]
	ds_read_b128 v[238:241], v222 offset:576
	s_waitcnt lgkmcnt(1)
	v_mfma_f32_16x16x32_bf16 v[230:233], v[234:237], v[164:167], v[230:233]
	ds_read_b128 v[234:237], v222 offset:640
	s_waitcnt lgkmcnt(1)
	v_mfma_f32_16x16x32_bf16 v[230:233], v[238:241], v[168:171], v[230:233]
	ds_read_b128 v[238:241], v222 offset:704
	s_waitcnt lgkmcnt(1)
	v_mfma_f32_16x16x32_bf16 v[230:233], v[234:237], v[172:175], v[230:233]
	ds_read_b128 v[234:237], v222 offset:768
	s_waitcnt lgkmcnt(1)
	v_mfma_f32_16x16x32_bf16 v[230:233], v[238:241], v[176:179], v[230:233]
	ds_read_b128 v[238:241], v222 offset:832
	s_waitcnt lgkmcnt(1)
	v_mfma_f32_16x16x32_bf16 v[230:233], v[234:237], v[180:183], v[230:233]
	ds_read_b128 v[234:237], v222 offset:896
	s_waitcnt lgkmcnt(1)
	v_mfma_f32_16x16x32_bf16 v[230:233], v[238:241], v[184:187], v[230:233]
	ds_read_b128 v[238:241], v222 offset:960
	s_waitcnt lgkmcnt(1)
	v_mfma_f32_16x16x32_bf16 v[230:233], v[234:237], v[188:191], v[230:233]
	s_waitcnt lgkmcnt(0)
	v_mfma_f32_16x16x32_bf16 v[230:233], v[238:241], v[192:195], v[230:233]
	s_nop 7
	v_mul_f32_e32 v32, 0x3db504f3, v230
	v_cndmask_b32_e32 v34, v216, v32, vcc
	v_cmp_gt_u32_e32 vcc, s4, v227
	v_mul_f32_e32 v32, 0x3db504f3, v231
	v_mul_f32_e32 v230, 0x3db504f3, v232
	v_cndmask_b32_e32 v35, v216, v32, vcc
	v_cmp_ge_u32_e32 vcc, s4, v229
	v_mul_f32_e32 v231, 0x3db504f3, v233
	v_max3_f32 v32, v34, s0, v35
	v_cndmask_b32_e32 v229, v216, v230, vcc
	v_add_u32_e32 v230, 3, v227
	v_cmp_ge_u32_e32 vcc, s4, v230
	s_nop 1
	v_cndmask_b32_e32 v230, v216, v231, vcc
	v_max3_f32 v32, v32, v229, v230
	v_mov_b32_e32 v231, v32
	s_nop 1
	v_permlane16_swap_b32_e32 v32, v231
	v_max_f32_e32 v231, v231, v231
	v_max_f32_e32 v32, v32, v32
	v_max_f32_e32 v32, v32, v231
	v_mov_b32_e32 v231, v32
	s_nop 1
	v_permlane32_swap_b32_e32 v32, v231
	v_max_f32_e32 v231, v231, v231
	v_max_f32_e32 v32, v32, v32
	v_max_f32_e32 v32, v32, v231
	v_add_f32_e32 v231, 0x41000000, v228
	v_cmp_gt_f32_e32 vcc, v32, v231
	s_cbranch_vccz .LBB0_903
; __device__ __forceinline__ void ph_attn(const Params& p, char* shm) {
;     ...
;       if (__ballot(cmax > mref + 8.f)) {
;         const float mn = fmaxf(mref, cmax);
;         const float al = __expf(mref - mn);
; #pragma unroll
;         for (int dt = 0; dt < 32; ++dt) O[dt] *= al;
;         lsum *= al;
;         mref = mn;
;       }
	v_max_f32_e32 v32, v32, v32
	v_max_f32_e32 v231, v228, v228
	v_max_f32_e32 v231, v231, v32
	v_sub_f32_e32 v32, v228, v231
	v_mul_f32_e32 v32, 0x3fb8aa3b, v32
	v_exp_f32_e32 v32, v32
	v_mov_b32_e32 v228, v231
	v_pk_mul_f32 v[130:131], v[130:131], v[32:33] op_sel_hi:[1,0]
	v_pk_mul_f32 v[128:129], v[128:129], v[32:33] op_sel_hi:[1,0]
	v_pk_mul_f32 v[126:127], v[126:127], v[32:33] op_sel_hi:[1,0]
	v_pk_mul_f32 v[124:125], v[124:125], v[32:33] op_sel_hi:[1,0]
	v_pk_mul_f32 v[122:123], v[122:123], v[32:33] op_sel_hi:[1,0]
	v_pk_mul_f32 v[120:121], v[120:121], v[32:33] op_sel_hi:[1,0]
	v_pk_mul_f32 v[118:119], v[118:119], v[32:33] op_sel_hi:[1,0]
	v_pk_mul_f32 v[116:117], v[116:117], v[32:33] op_sel_hi:[1,0]
	v_pk_mul_f32 v[114:115], v[114:115], v[32:33] op_sel_hi:[1,0]
	v_pk_mul_f32 v[112:113], v[112:113], v[32:33] op_sel_hi:[1,0]
	v_pk_mul_f32 v[110:111], v[110:111], v[32:33] op_sel_hi:[1,0]
	v_pk_mul_f32 v[108:109], v[108:109], v[32:33] op_sel_hi:[1,0]
	v_pk_mul_f32 v[106:107], v[106:107], v[32:33] op_sel_hi:[1,0]
	v_pk_mul_f32 v[104:105], v[104:105], v[32:33] op_sel_hi:[1,0]
	v_pk_mul_f32 v[102:103], v[102:103], v[32:33] op_sel_hi:[1,0]
	v_pk_mul_f32 v[100:101], v[100:101], v[32:33] op_sel_hi:[1,0]
	v_pk_mul_f32 v[98:99], v[98:99], v[32:33] op_sel_hi:[1,0]
	v_pk_mul_f32 v[96:97], v[96:97], v[32:33] op_sel_hi:[1,0]
	v_pk_mul_f32 v[94:95], v[94:95], v[32:33] op_sel_hi:[1,0]
	v_pk_mul_f32 v[92:93], v[92:93], v[32:33] op_sel_hi:[1,0]
	v_pk_mul_f32 v[90:91], v[90:91], v[32:33] op_sel_hi:[1,0]
	v_pk_mul_f32 v[88:89], v[88:89], v[32:33] op_sel_hi:[1,0]
	v_pk_mul_f32 v[86:87], v[86:87], v[32:33] op_sel_hi:[1,0]
	v_pk_mul_f32 v[84:85], v[84:85], v[32:33] op_sel_hi:[1,0]
	v_pk_mul_f32 v[82:83], v[82:83], v[32:33] op_sel_hi:[1,0]
	v_pk_mul_f32 v[80:81], v[80:81], v[32:33] op_sel_hi:[1,0]
	v_pk_mul_f32 v[78:79], v[78:79], v[32:33] op_sel_hi:[1,0]
	v_pk_mul_f32 v[76:77], v[76:77], v[32:33] op_sel_hi:[1,0]
	v_pk_mul_f32 v[74:75], v[74:75], v[32:33] op_sel_hi:[1,0]
	v_pk_mul_f32 v[72:73], v[72:73], v[32:33] op_sel_hi:[1,0]
	v_pk_mul_f32 v[70:71], v[70:71], v[32:33] op_sel_hi:[1,0]
	v_pk_mul_f32 v[68:69], v[68:69], v[32:33] op_sel_hi:[1,0]
	v_pk_mul_f32 v[66:67], v[66:67], v[32:33] op_sel_hi:[1,0]
	v_pk_mul_f32 v[64:65], v[64:65], v[32:33] op_sel_hi:[1,0]
	v_pk_mul_f32 v[62:63], v[62:63], v[32:33] op_sel_hi:[1,0]
	v_pk_mul_f32 v[60:61], v[60:61], v[32:33] op_sel_hi:[1,0]
	v_pk_mul_f32 v[58:59], v[58:59], v[32:33] op_sel_hi:[1,0]
	v_pk_mul_f32 v[56:57], v[56:57], v[32:33] op_sel_hi:[1,0]
	v_pk_mul_f32 v[54:55], v[54:55], v[32:33] op_sel_hi:[1,0]
	v_pk_mul_f32 v[52:53], v[52:53], v[32:33] op_sel_hi:[1,0]
	v_pk_mul_f32 v[50:51], v[50:51], v[32:33] op_sel_hi:[1,0]
	v_pk_mul_f32 v[48:49], v[48:49], v[32:33] op_sel_hi:[1,0]
	v_pk_mul_f32 v[46:47], v[46:47], v[32:33] op_sel_hi:[1,0]
	v_pk_mul_f32 v[44:45], v[44:45], v[32:33] op_sel_hi:[1,0]
	v_pk_mul_f32 v[38:39], v[38:39], v[32:33] op_sel_hi:[1,0]
	v_pk_mul_f32 v[36:37], v[36:37], v[32:33] op_sel_hi:[1,0]
	v_pk_mul_f32 v[26:27], v[26:27], v[32:33] op_sel_hi:[1,0]
	v_pk_mul_f32 v[24:25], v[24:25], v[32:33] op_sel_hi:[1,0]
	v_pk_mul_f32 v[42:43], v[42:43], v[32:33] op_sel_hi:[1,0]
	v_pk_mul_f32 v[40:41], v[40:41], v[32:33] op_sel_hi:[1,0]
	v_pk_mul_f32 v[30:31], v[30:31], v[32:33] op_sel_hi:[1,0]
	v_pk_mul_f32 v[28:29], v[28:29], v[32:33] op_sel_hi:[1,0]
	v_pk_mul_f32 v[22:23], v[22:23], v[32:33] op_sel_hi:[1,0]
	v_pk_mul_f32 v[20:21], v[20:21], v[32:33] op_sel_hi:[1,0]
	v_pk_mul_f32 v[18:19], v[18:19], v[32:33] op_sel_hi:[1,0]
	v_pk_mul_f32 v[16:17], v[16:17], v[32:33] op_sel_hi:[1,0]
	v_pk_mul_f32 v[14:15], v[14:15], v[32:33] op_sel_hi:[1,0]
	v_pk_mul_f32 v[12:13], v[12:13], v[32:33] op_sel_hi:[1,0]
	v_pk_mul_f32 v[10:11], v[10:11], v[32:33] op_sel_hi:[1,0]
	v_pk_mul_f32 v[8:9], v[8:9], v[32:33] op_sel_hi:[1,0]
	v_pk_mul_f32 v[6:7], v[6:7], v[32:33] op_sel_hi:[1,0]
	v_pk_mul_f32 v[4:5], v[4:5], v[32:33] op_sel_hi:[1,0]
	v_pk_mul_f32 v[2:3], v[2:3], v[32:33] op_sel_hi:[1,0]
	v_pk_mul_f32 v[0:1], v[0:1], v[32:33] op_sel_hi:[1,0]
	v_mul_f32_e32 v224, v224, v32
	s_branch .LBB0_903
